# plus: leading half runs its own K-loop copy with LDS-DMA waits one interval later
# speedup vs baseline: 1.0075x; 1.0075x over previous
.LBB0_119:
	s_ashr_i32 s81, s80, 31
	s_lshl_b64 s[52:53], s[80:81], 19
	s_add_u32 s82, s12, s52
	s_addc_u32 s83, s13, s53
	s_and_b64 s[52:53], s[6:7], exec
	s_cselect_b32 s52, s83, s89
	s_cselect_b32 s53, s82, s88
	s_ashr_i32 s79, s78, 31
	s_lshl_b64 s[56:57], s[78:79], 19
	s_add_u32 s84, s14, s56
	s_addc_u32 s85, s15, s57
	s_and_b64 s[56:57], s[6:7], exec
	s_cselect_b32 s56, s85, s91
	s_cselect_b32 s57, s84, s90
	s_add_u32 s88, s88, 0x40080
	s_addc_u32 s89, s89, 0
	s_add_u32 s58, s90, 0x100
	v_mov_b32_e32 v0, 0
	s_addc_u32 s59, s91, 0
	s_mov_b32 s66, -2
	s_waitcnt lgkmcnt(0)
	s_and_b64 s[100:101], exec, s[76:77]
	s_cbranch_scc1 .Lka0_head

.Lzskip_0:
	s_branch .Lka0_skip
.Lka0_head:
	ds_read_b128 v[128:131], v178
	ds_read_b128 v[132:135], v178 offset:1024
	ds_read_b128 v[154:157], v178 offset:2048
	ds_read_b128 v[158:161], v178 offset:3072
	ds_read_b128 v[162:165], v179
	ds_read_b128 v[166:169], v179 offset:1024
	ds_read_b128 v[182:185], v179 offset:2048
	ds_read_b128 v[186:189], v179 offset:3072
	s_add_u32 s67, s88, 0xfffc0080
	s_addc_u32 s68, s89, -1
	s_cmp_eq_u32 s66, 12
	s_cselect_b32 s93, s52, s68
	s_cselect_b32 s92, s53, s67
	s_cselect_b32 s91, s56, s59
	s_cselect_b32 s90, s57, s58
	v_lshl_add_u64 v[170:171], s[88:89], 0, v[144:145]
	s_add_i32 m0, s17, 0xc000
	ds_read_b128 v[190:193], v180
	ds_read_b128 v[194:197], v180 offset:1024
	ds_read_b128 v[198:201], v180 offset:2048
	ds_read_b128 v[202:205], v180 offset:3072
	ds_read_b128 v[206:209], v180 offset:4096
	ds_read_b128 v[210:213], v180 offset:5120
	ds_read_b128 v[214:217], v180 offset:6144
	ds_read_b128 v[218:221], v180 offset:7168
	global_load_lds_dwordx4 v[170:171], off
	s_add_i32 m0, s17, 0xe000
	v_lshl_add_u64 v[170:171], s[88:89], 0, v[148:149]
	global_load_lds_dwordx4 v[170:171], off
	s_cmp_eq_u32 s66, -2
	s_waitcnt lgkmcnt(0)
	s_barrier
	s_setprio 1
	s_cbranch_scc1 .Lkazv_0_0
	v_mfma_f32_16x16x32_bf16 v[124:127], v[128:131], v[190:193], v[124:127]
	v_mfma_f32_16x16x32_bf16 v[124:127], v[132:135], v[194:197], v[124:127]
	v_mfma_f32_16x16x32_bf16 v[116:119], v[154:157], v[190:193], v[116:119]
	v_mfma_f32_16x16x32_bf16 v[116:119], v[158:161], v[194:197], v[116:119]
	v_mfma_f32_16x16x32_bf16 v[108:111], v[128:131], v[198:201], v[108:111]
	v_mfma_f32_16x16x32_bf16 v[108:111], v[132:135], v[202:205], v[108:111]
	v_mfma_f32_16x16x32_bf16 v[100:103], v[154:157], v[198:201], v[100:103]
	v_mfma_f32_16x16x32_bf16 v[100:103], v[158:161], v[202:205], v[100:103]
	v_mfma_f32_16x16x32_bf16 v[92:95], v[128:131], v[206:209], v[92:95]
	v_mfma_f32_16x16x32_bf16 v[92:95], v[132:135], v[210:213], v[92:95]
	v_mfma_f32_16x16x32_bf16 v[84:87], v[154:157], v[206:209], v[84:87]
	v_mfma_f32_16x16x32_bf16 v[84:87], v[158:161], v[210:213], v[84:87]
	v_mfma_f32_16x16x32_bf16 v[76:79], v[128:131], v[214:217], v[76:79]
	v_mfma_f32_16x16x32_bf16 v[76:79], v[132:135], v[218:221], v[76:79]
	v_mfma_f32_16x16x32_bf16 v[68:71], v[154:157], v[214:217], v[68:71]
	v_mfma_f32_16x16x32_bf16 v[68:71], v[158:161], v[218:221], v[68:71]
	v_mfma_f32_16x16x32_bf16 v[120:123], v[162:165], v[190:193], v[120:123]
	v_mfma_f32_16x16x32_bf16 v[120:123], v[166:169], v[194:197], v[120:123]
	v_mfma_f32_16x16x32_bf16 v[112:115], v[182:185], v[190:193], v[112:115]
	v_mfma_f32_16x16x32_bf16 v[112:115], v[186:189], v[194:197], v[112:115]
	v_mfma_f32_16x16x32_bf16 v[104:107], v[162:165], v[198:201], v[104:107]
	v_mfma_f32_16x16x32_bf16 v[104:107], v[166:169], v[202:205], v[104:107]
	v_mfma_f32_16x16x32_bf16 v[96:99], v[182:185], v[198:201], v[96:99]
	v_mfma_f32_16x16x32_bf16 v[96:99], v[186:189], v[202:205], v[96:99]
	v_mfma_f32_16x16x32_bf16 v[88:91], v[162:165], v[206:209], v[88:91]
	v_mfma_f32_16x16x32_bf16 v[88:91], v[166:169], v[210:213], v[88:91]
	v_mfma_f32_16x16x32_bf16 v[80:83], v[182:185], v[206:209], v[80:83]
	v_mfma_f32_16x16x32_bf16 v[80:83], v[186:189], v[210:213], v[80:83]
	v_mfma_f32_16x16x32_bf16 v[72:75], v[162:165], v[214:217], v[72:75]
	v_mfma_f32_16x16x32_bf16 v[72:75], v[166:169], v[218:221], v[72:75]
	s_waitcnt vmcnt(8)
	s_setprio 3
	s_barrier
	v_mfma_f32_16x16x32_bf16 v[64:67], v[182:185], v[214:217], v[64:67]
	v_mfma_f32_16x16x32_bf16 v[64:67], v[186:189], v[218:221], v[64:67]
	s_setprio 0
.Lkazj_0_0:
	s_add_i32 s67, s25, s16
	v_lshl_add_u64 v[170:171], s[90:91], 0, v[140:141]
	s_mov_b32 m0, s67
	ds_read_b128 v[190:193], v180 offset:16384
	ds_read_b128 v[194:197], v180 offset:17408
	ds_read_b128 v[198:201], v180 offset:18432
	ds_read_b128 v[202:205], v180 offset:19456
	ds_read_b128 v[206:209], v180 offset:20480
	ds_read_b128 v[210:213], v180 offset:21504
	ds_read_b128 v[214:217], v180 offset:22528
	ds_read_b128 v[218:221], v180 offset:23552
	global_load_lds_dwordx4 v[170:171], off
	s_add_i32 m0, s67, 0x2000
	s_add_u32 s68, s90, 0x40000
	v_lshl_add_u64 v[222:223], s[90:91], 0, v[136:137]
	s_addc_u32 s69, s91, 0
	s_add_i32 s67, s26, s16
	global_load_lds_dwordx4 v[222:223], off
	v_lshl_add_u64 v[224:225], s[68:69], 0, v[140:141]
	s_mov_b32 m0, s67
	global_load_lds_dwordx4 v[224:225], off
	s_add_i32 m0, s67, 0x2000
	v_lshl_add_u64 v[224:225], s[68:69], 0, v[136:137]
	global_load_lds_dwordx4 v[224:225], off
	s_mov_b32 m0, s17
	v_lshl_add_u64 v[224:225], s[92:93], 0, v[142:143]
	global_load_lds_dwordx4 v[224:225], off
	s_mov_b32 m0, s18
	v_lshl_add_u64 v[226:227], s[92:93], 0, v[138:139]
	global_load_lds_dwordx4 v[226:227], off
	s_cmp_eq_u32 s66, -2
	s_waitcnt lgkmcnt(0)
	s_barrier
	s_setprio 1
	s_cbranch_scc1 .Lkazv_0_1
	v_mfma_f32_16x16x32_bf16 v[60:63], v[128:131], v[190:193], v[60:63]
	v_mfma_f32_16x16x32_bf16 v[60:63], v[132:135], v[194:197], v[60:63]
	v_mfma_f32_16x16x32_bf16 v[52:55], v[154:157], v[190:193], v[52:55]
	v_mfma_f32_16x16x32_bf16 v[52:55], v[158:161], v[194:197], v[52:55]
	v_mfma_f32_16x16x32_bf16 v[44:47], v[128:131], v[198:201], v[44:47]
	v_mfma_f32_16x16x32_bf16 v[44:47], v[132:135], v[202:205], v[44:47]
	v_mfma_f32_16x16x32_bf16 v[36:39], v[154:157], v[198:201], v[36:39]
	v_mfma_f32_16x16x32_bf16 v[36:39], v[158:161], v[202:205], v[36:39]
	v_mfma_f32_16x16x32_bf16 v[28:31], v[128:131], v[206:209], v[28:31]
	v_mfma_f32_16x16x32_bf16 v[28:31], v[132:135], v[210:213], v[28:31]
	v_mfma_f32_16x16x32_bf16 v[20:23], v[154:157], v[206:209], v[20:23]
	v_mfma_f32_16x16x32_bf16 v[20:23], v[158:161], v[210:213], v[20:23]
	v_mfma_f32_16x16x32_bf16 v[12:15], v[128:131], v[214:217], v[12:15]
	v_mfma_f32_16x16x32_bf16 v[12:15], v[132:135], v[218:221], v[12:15]
	v_mfma_f32_16x16x32_bf16 v[4:7], v[154:157], v[214:217], v[4:7]
	v_mfma_f32_16x16x32_bf16 v[4:7], v[158:161], v[218:221], v[4:7]
	v_mfma_f32_16x16x32_bf16 v[56:59], v[162:165], v[190:193], v[56:59]
	v_mfma_f32_16x16x32_bf16 v[56:59], v[166:169], v[194:197], v[56:59]
	v_mfma_f32_16x16x32_bf16 v[48:51], v[182:185], v[190:193], v[48:51]
	v_mfma_f32_16x16x32_bf16 v[48:51], v[186:189], v[194:197], v[48:51]
	v_mfma_f32_16x16x32_bf16 v[40:43], v[162:165], v[198:201], v[40:43]
	v_mfma_f32_16x16x32_bf16 v[40:43], v[166:169], v[202:205], v[40:43]
	v_mfma_f32_16x16x32_bf16 v[32:35], v[182:185], v[198:201], v[32:35]
	v_mfma_f32_16x16x32_bf16 v[32:35], v[186:189], v[202:205], v[32:35]
	v_mfma_f32_16x16x32_bf16 v[24:27], v[162:165], v[206:209], v[24:27]
	v_mfma_f32_16x16x32_bf16 v[24:27], v[166:169], v[210:213], v[24:27]
	v_mfma_f32_16x16x32_bf16 v[16:19], v[182:185], v[206:209], v[16:19]
	v_mfma_f32_16x16x32_bf16 v[16:19], v[186:189], v[210:213], v[16:19]
	v_mfma_f32_16x16x32_bf16 v[8:11], v[162:165], v[214:217], v[8:11]
	v_mfma_f32_16x16x32_bf16 v[8:11], v[166:169], v[218:221], v[8:11]
	s_waitcnt vmcnt(8)
	s_setprio 3
	s_barrier
	v_mfma_f32_16x16x32_bf16 v[0:3], v[182:185], v[214:217], v[0:3]
	v_mfma_f32_16x16x32_bf16 v[0:3], v[186:189], v[218:221], v[0:3]
	s_setprio 0
.Lkazj_0_1:
	s_add_i32 s67, 0, 0x18000
	s_add_i32 s73, 0, 0x1c000
	v_add_u32_e32 v158, s67, v175
	v_add_u32_e32 v186, s73, v175
	ds_read_b128 v[128:131], v158
	ds_read_b128 v[132:135], v158 offset:1024
	ds_read_b128 v[154:157], v158 offset:2048
	ds_read_b128 v[158:161], v158 offset:3072
	ds_read_b128 v[162:165], v186
	ds_read_b128 v[166:169], v186 offset:1024
	ds_read_b128 v[182:185], v186 offset:2048
	ds_read_b128 v[186:189], v186 offset:3072
	s_add_u32 s68, s92, 0x40000
	s_addc_u32 s69, s93, 0
	s_mov_b32 m0, s19
	v_lshl_add_u64 v[228:229], s[68:69], 0, v[142:143]
	ds_read_b128 v[190:193], v180 offset:32768
	ds_read_b128 v[194:197], v180 offset:33792
	ds_read_b128 v[198:201], v180 offset:34816
	ds_read_b128 v[202:205], v180 offset:35840
	ds_read_b128 v[206:209], v180 offset:36864
	ds_read_b128 v[210:213], v180 offset:37888
	ds_read_b128 v[214:217], v180 offset:38912
	ds_read_b128 v[218:221], v180 offset:39936
	global_load_lds_dwordx4 v[228:229], off
	s_mov_b32 m0, s20
	v_lshl_add_u64 v[228:229], s[68:69], 0, v[138:139]
	global_load_lds_dwordx4 v[228:229], off
	s_waitcnt lgkmcnt(0)
	s_barrier
	s_setprio 1
	v_mfma_f32_16x16x32_bf16 v[124:127], v[128:131], v[190:193], v[124:127]
	v_mfma_f32_16x16x32_bf16 v[124:127], v[132:135], v[194:197], v[124:127]
	v_mfma_f32_16x16x32_bf16 v[116:119], v[154:157], v[190:193], v[116:119]
	v_mfma_f32_16x16x32_bf16 v[116:119], v[158:161], v[194:197], v[116:119]
	v_mfma_f32_16x16x32_bf16 v[108:111], v[128:131], v[198:201], v[108:111]
	v_mfma_f32_16x16x32_bf16 v[108:111], v[132:135], v[202:205], v[108:111]
	v_mfma_f32_16x16x32_bf16 v[100:103], v[154:157], v[198:201], v[100:103]
	v_mfma_f32_16x16x32_bf16 v[100:103], v[158:161], v[202:205], v[100:103]
	v_mfma_f32_16x16x32_bf16 v[92:95], v[128:131], v[206:209], v[92:95]
	v_mfma_f32_16x16x32_bf16 v[92:95], v[132:135], v[210:213], v[92:95]
	v_mfma_f32_16x16x32_bf16 v[84:87], v[154:157], v[206:209], v[84:87]
	v_mfma_f32_16x16x32_bf16 v[84:87], v[158:161], v[210:213], v[84:87]
	v_mfma_f32_16x16x32_bf16 v[76:79], v[128:131], v[214:217], v[76:79]
	v_mfma_f32_16x16x32_bf16 v[76:79], v[132:135], v[218:221], v[76:79]
	v_mfma_f32_16x16x32_bf16 v[68:71], v[154:157], v[214:217], v[68:71]
	v_mfma_f32_16x16x32_bf16 v[68:71], v[158:161], v[218:221], v[68:71]
	v_mfma_f32_16x16x32_bf16 v[120:123], v[162:165], v[190:193], v[120:123]
	v_mfma_f32_16x16x32_bf16 v[120:123], v[166:169], v[194:197], v[120:123]
	v_mfma_f32_16x16x32_bf16 v[112:115], v[182:185], v[190:193], v[112:115]
	v_mfma_f32_16x16x32_bf16 v[112:115], v[186:189], v[194:197], v[112:115]
	v_mfma_f32_16x16x32_bf16 v[104:107], v[162:165], v[198:201], v[104:107]
	v_mfma_f32_16x16x32_bf16 v[104:107], v[166:169], v[202:205], v[104:107]
	v_mfma_f32_16x16x32_bf16 v[96:99], v[182:185], v[198:201], v[96:99]
	v_mfma_f32_16x16x32_bf16 v[96:99], v[186:189], v[202:205], v[96:99]
	v_mfma_f32_16x16x32_bf16 v[88:91], v[162:165], v[206:209], v[88:91]
	v_mfma_f32_16x16x32_bf16 v[88:91], v[166:169], v[210:213], v[88:91]
	v_mfma_f32_16x16x32_bf16 v[80:83], v[182:185], v[206:209], v[80:83]
	v_mfma_f32_16x16x32_bf16 v[80:83], v[186:189], v[210:213], v[80:83]
	v_mfma_f32_16x16x32_bf16 v[72:75], v[162:165], v[214:217], v[72:75]
	v_mfma_f32_16x16x32_bf16 v[72:75], v[166:169], v[218:221], v[72:75]
	s_waitcnt vmcnt(8)
	s_setprio 3
	s_barrier
	v_mfma_f32_16x16x32_bf16 v[64:67], v[182:185], v[214:217], v[64:67]
	v_mfma_f32_16x16x32_bf16 v[64:67], v[186:189], v[218:221], v[64:67]
	s_setprio 0
	s_add_i32 s67, s67, s16
	v_lshl_add_u64 v[170:171], v[170:171], 0, s[74:75]
	s_mov_b32 m0, s67
	ds_read_b128 v[190:193], v180 offset:49152
	ds_read_b128 v[194:197], v180 offset:50176
	ds_read_b128 v[198:201], v180 offset:51200
	ds_read_b128 v[202:205], v180 offset:52224
	ds_read_b128 v[206:209], v180 offset:53248
	ds_read_b128 v[210:213], v180 offset:54272
	ds_read_b128 v[214:217], v180 offset:55296
	ds_read_b128 v[218:221], v180 offset:56320
	global_load_lds_dwordx4 v[170:171], off
	s_add_i32 m0, s67, 0x2000
	s_add_u32 s68, s90, 0x40080
	v_lshl_add_u64 v[170:171], v[222:223], 0, s[74:75]
	s_addc_u32 s69, s91, 0
	s_add_i32 s67, s73, s16
	global_load_lds_dwordx4 v[170:171], off
	s_mov_b32 m0, s67
	v_lshl_add_u64 v[170:171], s[68:69], 0, v[140:141]
	global_load_lds_dwordx4 v[170:171], off
	s_add_i32 m0, s67, 0x2000
	v_lshl_add_u64 v[170:171], s[68:69], 0, v[136:137]
	global_load_lds_dwordx4 v[170:171], off
	s_mov_b32 m0, s23
	v_lshl_add_u64 v[170:171], v[224:225], 0, s[74:75]
	global_load_lds_dwordx4 v[170:171], off
	s_mov_b32 m0, s24
	v_lshl_add_u64 v[170:171], v[226:227], 0, s[74:75]
	global_load_lds_dwordx4 v[170:171], off
	s_waitcnt lgkmcnt(0)
	s_barrier
	s_setprio 1
	v_mfma_f32_16x16x32_bf16 v[60:63], v[128:131], v[190:193], v[60:63]
	v_mfma_f32_16x16x32_bf16 v[60:63], v[132:135], v[194:197], v[60:63]
	v_mfma_f32_16x16x32_bf16 v[52:55], v[154:157], v[190:193], v[52:55]
	v_mfma_f32_16x16x32_bf16 v[52:55], v[158:161], v[194:197], v[52:55]
	v_mfma_f32_16x16x32_bf16 v[44:47], v[128:131], v[198:201], v[44:47]
	v_mfma_f32_16x16x32_bf16 v[44:47], v[132:135], v[202:205], v[44:47]
	v_mfma_f32_16x16x32_bf16 v[36:39], v[154:157], v[198:201], v[36:39]
	v_mfma_f32_16x16x32_bf16 v[36:39], v[158:161], v[202:205], v[36:39]
	v_mfma_f32_16x16x32_bf16 v[28:31], v[128:131], v[206:209], v[28:31]
	v_mfma_f32_16x16x32_bf16 v[28:31], v[132:135], v[210:213], v[28:31]
	v_mfma_f32_16x16x32_bf16 v[20:23], v[154:157], v[206:209], v[20:23]
	v_mfma_f32_16x16x32_bf16 v[20:23], v[158:161], v[210:213], v[20:23]
	v_mfma_f32_16x16x32_bf16 v[12:15], v[128:131], v[214:217], v[12:15]
	v_mfma_f32_16x16x32_bf16 v[12:15], v[132:135], v[218:221], v[12:15]
	v_mfma_f32_16x16x32_bf16 v[4:7], v[154:157], v[214:217], v[4:7]
	v_mfma_f32_16x16x32_bf16 v[4:7], v[158:161], v[218:221], v[4:7]
	v_mfma_f32_16x16x32_bf16 v[56:59], v[162:165], v[190:193], v[56:59]
	v_mfma_f32_16x16x32_bf16 v[56:59], v[166:169], v[194:197], v[56:59]
	v_mfma_f32_16x16x32_bf16 v[48:51], v[182:185], v[190:193], v[48:51]
	v_mfma_f32_16x16x32_bf16 v[48:51], v[186:189], v[194:197], v[48:51]
	v_mfma_f32_16x16x32_bf16 v[40:43], v[162:165], v[198:201], v[40:43]
	v_mfma_f32_16x16x32_bf16 v[40:43], v[166:169], v[202:205], v[40:43]
	v_mfma_f32_16x16x32_bf16 v[32:35], v[182:185], v[198:201], v[32:35]
	v_mfma_f32_16x16x32_bf16 v[32:35], v[186:189], v[202:205], v[32:35]
	v_mfma_f32_16x16x32_bf16 v[24:27], v[162:165], v[206:209], v[24:27]
	v_mfma_f32_16x16x32_bf16 v[24:27], v[166:169], v[210:213], v[24:27]
	v_mfma_f32_16x16x32_bf16 v[16:19], v[182:185], v[206:209], v[16:19]
	v_mfma_f32_16x16x32_bf16 v[16:19], v[186:189], v[210:213], v[16:19]
	v_mfma_f32_16x16x32_bf16 v[8:11], v[162:165], v[214:217], v[8:11]
	v_mfma_f32_16x16x32_bf16 v[8:11], v[166:169], v[218:221], v[8:11]
	s_waitcnt vmcnt(8)
	s_setprio 3
	s_barrier
	v_mfma_f32_16x16x32_bf16 v[0:3], v[182:185], v[214:217], v[0:3]
	v_mfma_f32_16x16x32_bf16 v[0:3], v[186:189], v[218:221], v[0:3]
	s_setprio 0
	s_add_i32 s66, s66, 2
	s_add_u32 s88, s88, 0x100
	s_addc_u32 s89, s89, 0
	s_add_u32 s58, s58, 0x100
	s_addc_u32 s59, s59, 0
	s_cmp_gt_u32 s66, 13
	s_cbranch_scc0 .Lka0_head
	s_branch .Lzskip_0
.Lkazv_0_0:
	v_mfma_f32_16x16x32_bf16 v[124:127], v[128:131], v[190:193], 0
	v_mfma_f32_16x16x32_bf16 v[124:127], v[132:135], v[194:197], v[124:127]
	v_mfma_f32_16x16x32_bf16 v[116:119], v[154:157], v[190:193], 0
	v_mfma_f32_16x16x32_bf16 v[116:119], v[158:161], v[194:197], v[116:119]
	v_mfma_f32_16x16x32_bf16 v[108:111], v[128:131], v[198:201], 0
	v_mfma_f32_16x16x32_bf16 v[108:111], v[132:135], v[202:205], v[108:111]
	v_mfma_f32_16x16x32_bf16 v[100:103], v[154:157], v[198:201], 0
	v_mfma_f32_16x16x32_bf16 v[100:103], v[158:161], v[202:205], v[100:103]
	v_mfma_f32_16x16x32_bf16 v[92:95], v[128:131], v[206:209], 0
	v_mfma_f32_16x16x32_bf16 v[92:95], v[132:135], v[210:213], v[92:95]
	v_mfma_f32_16x16x32_bf16 v[84:87], v[154:157], v[206:209], 0
	v_mfma_f32_16x16x32_bf16 v[84:87], v[158:161], v[210:213], v[84:87]
	v_mfma_f32_16x16x32_bf16 v[76:79], v[128:131], v[214:217], 0
	v_mfma_f32_16x16x32_bf16 v[76:79], v[132:135], v[218:221], v[76:79]
	v_mfma_f32_16x16x32_bf16 v[68:71], v[154:157], v[214:217], 0
	v_mfma_f32_16x16x32_bf16 v[68:71], v[158:161], v[218:221], v[68:71]
	v_mfma_f32_16x16x32_bf16 v[120:123], v[162:165], v[190:193], 0
	v_mfma_f32_16x16x32_bf16 v[120:123], v[166:169], v[194:197], v[120:123]
	v_mfma_f32_16x16x32_bf16 v[112:115], v[182:185], v[190:193], 0
	v_mfma_f32_16x16x32_bf16 v[112:115], v[186:189], v[194:197], v[112:115]
	v_mfma_f32_16x16x32_bf16 v[104:107], v[162:165], v[198:201], 0
	v_mfma_f32_16x16x32_bf16 v[104:107], v[166:169], v[202:205], v[104:107]
	v_mfma_f32_16x16x32_bf16 v[96:99], v[182:185], v[198:201], 0
	v_mfma_f32_16x16x32_bf16 v[96:99], v[186:189], v[202:205], v[96:99]
	v_mfma_f32_16x16x32_bf16 v[88:91], v[162:165], v[206:209], 0
	v_mfma_f32_16x16x32_bf16 v[88:91], v[166:169], v[210:213], v[88:91]
	v_mfma_f32_16x16x32_bf16 v[80:83], v[182:185], v[206:209], 0
	v_mfma_f32_16x16x32_bf16 v[80:83], v[186:189], v[210:213], v[80:83]
	v_mfma_f32_16x16x32_bf16 v[72:75], v[162:165], v[214:217], 0
	v_mfma_f32_16x16x32_bf16 v[72:75], v[166:169], v[218:221], v[72:75]
	s_waitcnt vmcnt(8)
	s_setprio 3
	s_barrier
	v_mfma_f32_16x16x32_bf16 v[64:67], v[182:185], v[214:217], 0
	v_mfma_f32_16x16x32_bf16 v[64:67], v[186:189], v[218:221], v[64:67]
	s_setprio 0
	s_branch .Lkazj_0_0
.Lkazv_0_1:
	v_mfma_f32_16x16x32_bf16 v[60:63], v[128:131], v[190:193], 0
	v_mfma_f32_16x16x32_bf16 v[60:63], v[132:135], v[194:197], v[60:63]
	v_mfma_f32_16x16x32_bf16 v[52:55], v[154:157], v[190:193], 0
	v_mfma_f32_16x16x32_bf16 v[52:55], v[158:161], v[194:197], v[52:55]
	v_mfma_f32_16x16x32_bf16 v[44:47], v[128:131], v[198:201], 0
	v_mfma_f32_16x16x32_bf16 v[44:47], v[132:135], v[202:205], v[44:47]
	v_mfma_f32_16x16x32_bf16 v[36:39], v[154:157], v[198:201], 0
	v_mfma_f32_16x16x32_bf16 v[36:39], v[158:161], v[202:205], v[36:39]
	v_mfma_f32_16x16x32_bf16 v[28:31], v[128:131], v[206:209], 0
	v_mfma_f32_16x16x32_bf16 v[28:31], v[132:135], v[210:213], v[28:31]
	v_mfma_f32_16x16x32_bf16 v[20:23], v[154:157], v[206:209], 0
	v_mfma_f32_16x16x32_bf16 v[20:23], v[158:161], v[210:213], v[20:23]
	v_mfma_f32_16x16x32_bf16 v[12:15], v[128:131], v[214:217], 0
	v_mfma_f32_16x16x32_bf16 v[12:15], v[132:135], v[218:221], v[12:15]
	v_mfma_f32_16x16x32_bf16 v[4:7], v[154:157], v[214:217], 0
	v_mfma_f32_16x16x32_bf16 v[4:7], v[158:161], v[218:221], v[4:7]
	v_mfma_f32_16x16x32_bf16 v[56:59], v[162:165], v[190:193], 0
	v_mfma_f32_16x16x32_bf16 v[56:59], v[166:169], v[194:197], v[56:59]
	v_mfma_f32_16x16x32_bf16 v[48:51], v[182:185], v[190:193], 0
	v_mfma_f32_16x16x32_bf16 v[48:51], v[186:189], v[194:197], v[48:51]
	v_mfma_f32_16x16x32_bf16 v[40:43], v[162:165], v[198:201], 0
	v_mfma_f32_16x16x32_bf16 v[40:43], v[166:169], v[202:205], v[40:43]
	v_mfma_f32_16x16x32_bf16 v[32:35], v[182:185], v[198:201], 0
	v_mfma_f32_16x16x32_bf16 v[32:35], v[186:189], v[202:205], v[32:35]
	v_mfma_f32_16x16x32_bf16 v[24:27], v[162:165], v[206:209], 0
	v_mfma_f32_16x16x32_bf16 v[24:27], v[166:169], v[210:213], v[24:27]
	v_mfma_f32_16x16x32_bf16 v[16:19], v[182:185], v[206:209], 0
	v_mfma_f32_16x16x32_bf16 v[16:19], v[186:189], v[210:213], v[16:19]
	v_mfma_f32_16x16x32_bf16 v[8:11], v[162:165], v[214:217], 0
	v_mfma_f32_16x16x32_bf16 v[8:11], v[166:169], v[218:221], v[8:11]
	s_waitcnt vmcnt(8)
	s_setprio 3
	s_barrier
	v_mfma_f32_16x16x32_bf16 v[0:3], v[182:185], v[214:217], 0
	v_mfma_f32_16x16x32_bf16 v[0:3], v[186:189], v[218:221], v[0:3]
	s_setprio 0
	s_branch .Lkazj_0_1
	s_branch .Lzskip_0

.LBB0_271:
	s_add_u32 s86, s86, 0xb0080
	s_addc_u32 s87, s87, 0
	s_add_u32 s56, s88, 0x100
	v_mov_b32_e32 v0, 0
	s_addc_u32 s57, s89, 0
	s_mov_b32 s58, -2
	s_and_b64 s[100:101], exec, s[82:83]
	s_cbranch_scc1 .Lka1_head

.Lka1_head:
	ds_read_b128 v[120:123], v245
	ds_read_b128 v[124:127], v245 offset:1024
	ds_read_b128 v[128:131], v245 offset:2048
	ds_read_b128 v[132:135], v245 offset:3072
	ds_read_b128 v[144:147], v246
	ds_read_b128 v[148:151], v246 offset:1024
	ds_read_b128 v[152:155], v246 offset:2048
	ds_read_b128 v[156:159], v246 offset:3072
	s_add_u32 s59, s86, 0xfff50080
	s_addc_u32 s66, s87, -1
	s_cmp_eq_u32 s58, 40
	s_cselect_b32 s91, s11, s66
	s_cselect_b32 s90, s10, s59
	s_cselect_b32 s89, s85, s57
	s_cselect_b32 s88, s84, s56
	v_lshl_add_u64 v[204:205], s[86:87], 0, v[200:201]
	s_add_i32 m0, s16, 0xc000
	ds_read_b128 v[160:163], v247
	ds_read_b128 v[164:167], v247 offset:1024
	ds_read_b128 v[168:171], v247 offset:2048
	ds_read_b128 v[172:175], v247 offset:3072
	ds_read_b128 v[176:179], v247 offset:4096
	ds_read_b128 v[180:183], v247 offset:5120
	ds_read_b128 v[184:187], v247 offset:6144
	ds_read_b128 v[188:191], v247 offset:7168
	global_load_lds_dwordx4 v[204:205], off
	s_add_i32 m0, s16, 0xe000
	v_lshl_add_u64 v[204:205], s[86:87], 0, v[202:203]
	global_load_lds_dwordx4 v[204:205], off
	s_cmp_eq_u32 s58, -2
	s_waitcnt lgkmcnt(0)
	s_barrier
	s_setprio 1
	s_cbranch_scc1 .Lkazv_1_0
	v_mfma_f32_16x16x32_bf16 v[140:143], v[120:123], v[160:163], v[140:143]
	v_mfma_f32_16x16x32_bf16 v[140:143], v[124:127], v[164:167], v[140:143]
	v_mfma_f32_16x16x32_bf16 v[136:139], v[128:131], v[160:163], v[136:139]
	v_mfma_f32_16x16x32_bf16 v[136:139], v[132:135], v[164:167], v[136:139]
	v_mfma_f32_16x16x32_bf16 v[108:111], v[120:123], v[168:171], v[108:111]
	v_mfma_f32_16x16x32_bf16 v[108:111], v[124:127], v[172:175], v[108:111]
	v_mfma_f32_16x16x32_bf16 v[104:107], v[128:131], v[168:171], v[104:107]
	v_mfma_f32_16x16x32_bf16 v[104:107], v[132:135], v[172:175], v[104:107]
	v_mfma_f32_16x16x32_bf16 v[92:95], v[120:123], v[176:179], v[92:95]
	v_mfma_f32_16x16x32_bf16 v[92:95], v[124:127], v[180:183], v[92:95]
	v_mfma_f32_16x16x32_bf16 v[88:91], v[128:131], v[176:179], v[88:91]
	v_mfma_f32_16x16x32_bf16 v[88:91], v[132:135], v[180:183], v[88:91]
	v_mfma_f32_16x16x32_bf16 v[76:79], v[120:123], v[184:187], v[76:79]
	v_mfma_f32_16x16x32_bf16 v[76:79], v[124:127], v[188:191], v[76:79]
	v_mfma_f32_16x16x32_bf16 v[72:75], v[128:131], v[184:187], v[72:75]
	v_mfma_f32_16x16x32_bf16 v[72:75], v[132:135], v[188:191], v[72:75]
	v_mfma_f32_16x16x32_bf16 v[116:119], v[144:147], v[160:163], v[116:119]
	v_mfma_f32_16x16x32_bf16 v[116:119], v[148:151], v[164:167], v[116:119]
	v_mfma_f32_16x16x32_bf16 v[112:115], v[152:155], v[160:163], v[112:115]
	v_mfma_f32_16x16x32_bf16 v[112:115], v[156:159], v[164:167], v[112:115]
	v_mfma_f32_16x16x32_bf16 v[100:103], v[144:147], v[168:171], v[100:103]
	v_mfma_f32_16x16x32_bf16 v[100:103], v[148:151], v[172:175], v[100:103]
	v_mfma_f32_16x16x32_bf16 v[96:99], v[152:155], v[168:171], v[96:99]
	v_mfma_f32_16x16x32_bf16 v[96:99], v[156:159], v[172:175], v[96:99]
	v_mfma_f32_16x16x32_bf16 v[84:87], v[144:147], v[176:179], v[84:87]
	v_mfma_f32_16x16x32_bf16 v[84:87], v[148:151], v[180:183], v[84:87]
	v_mfma_f32_16x16x32_bf16 v[80:83], v[152:155], v[176:179], v[80:83]
	v_mfma_f32_16x16x32_bf16 v[80:83], v[156:159], v[180:183], v[80:83]
	v_mfma_f32_16x16x32_bf16 v[68:71], v[144:147], v[184:187], v[68:71]
	v_mfma_f32_16x16x32_bf16 v[68:71], v[148:151], v[188:191], v[68:71]
	s_waitcnt vmcnt(8)
	s_setprio 3
	s_barrier
	v_mfma_f32_16x16x32_bf16 v[64:67], v[152:155], v[184:187], v[64:67]
	v_mfma_f32_16x16x32_bf16 v[64:67], v[156:159], v[188:191], v[64:67]
	s_setprio 0
.Lkazj_1_0:
	s_add_i32 s59, s26, s15
	v_lshl_add_u64 v[204:205], s[88:89], 0, v[194:195]
	s_mov_b32 m0, s59
	ds_read_b128 v[160:163], v247 offset:16384
	ds_read_b128 v[164:167], v247 offset:17408
	ds_read_b128 v[168:171], v247 offset:18432
	ds_read_b128 v[172:175], v247 offset:19456
	ds_read_b128 v[176:179], v247 offset:20480
	ds_read_b128 v[180:183], v247 offset:21504
	ds_read_b128 v[184:187], v247 offset:22528
	ds_read_b128 v[188:191], v247 offset:23552
	global_load_lds_dwordx4 v[204:205], off
	s_add_i32 m0, s59, 0x2000
	s_add_u32 s66, s88, 0xb0000
	v_lshl_add_u64 v[206:207], s[88:89], 0, v[198:199]
	s_addc_u32 s67, s89, 0
	s_add_i32 s59, s27, s15
	global_load_lds_dwordx4 v[206:207], off
	v_lshl_add_u64 v[208:209], s[66:67], 0, v[194:195]
	s_mov_b32 m0, s59
	global_load_lds_dwordx4 v[208:209], off
	s_add_i32 m0, s59, 0x2000
	v_lshl_add_u64 v[208:209], s[66:67], 0, v[198:199]
	global_load_lds_dwordx4 v[208:209], off
	s_mov_b32 m0, s16
	v_lshl_add_u64 v[208:209], s[90:91], 0, v[192:193]
	global_load_lds_dwordx4 v[208:209], off
	s_mov_b32 m0, s17
	v_lshl_add_u64 v[210:211], s[90:91], 0, v[196:197]
	global_load_lds_dwordx4 v[210:211], off
	s_cmp_eq_u32 s58, -2
	s_waitcnt lgkmcnt(0)
	s_barrier
	s_setprio 1
	s_cbranch_scc1 .Lkazv_1_1
	v_mfma_f32_16x16x32_bf16 v[60:63], v[120:123], v[160:163], v[60:63]
	v_mfma_f32_16x16x32_bf16 v[60:63], v[124:127], v[164:167], v[60:63]
	v_mfma_f32_16x16x32_bf16 v[56:59], v[128:131], v[160:163], v[56:59]
	v_mfma_f32_16x16x32_bf16 v[56:59], v[132:135], v[164:167], v[56:59]
	v_mfma_f32_16x16x32_bf16 v[44:47], v[120:123], v[168:171], v[44:47]
	v_mfma_f32_16x16x32_bf16 v[44:47], v[124:127], v[172:175], v[44:47]
	v_mfma_f32_16x16x32_bf16 v[40:43], v[128:131], v[168:171], v[40:43]
	v_mfma_f32_16x16x32_bf16 v[40:43], v[132:135], v[172:175], v[40:43]
	v_mfma_f32_16x16x32_bf16 v[28:31], v[120:123], v[176:179], v[28:31]
	v_mfma_f32_16x16x32_bf16 v[28:31], v[124:127], v[180:183], v[28:31]
	v_mfma_f32_16x16x32_bf16 v[24:27], v[128:131], v[176:179], v[24:27]
	v_mfma_f32_16x16x32_bf16 v[24:27], v[132:135], v[180:183], v[24:27]
	v_mfma_f32_16x16x32_bf16 v[12:15], v[120:123], v[184:187], v[12:15]
	v_mfma_f32_16x16x32_bf16 v[12:15], v[124:127], v[188:191], v[12:15]
	v_mfma_f32_16x16x32_bf16 v[8:11], v[128:131], v[184:187], v[8:11]
	v_mfma_f32_16x16x32_bf16 v[8:11], v[132:135], v[188:191], v[8:11]
	v_mfma_f32_16x16x32_bf16 v[52:55], v[144:147], v[160:163], v[52:55]
	v_mfma_f32_16x16x32_bf16 v[52:55], v[148:151], v[164:167], v[52:55]
	v_mfma_f32_16x16x32_bf16 v[48:51], v[152:155], v[160:163], v[48:51]
	v_mfma_f32_16x16x32_bf16 v[48:51], v[156:159], v[164:167], v[48:51]
	v_mfma_f32_16x16x32_bf16 v[36:39], v[144:147], v[168:171], v[36:39]
	v_mfma_f32_16x16x32_bf16 v[36:39], v[148:151], v[172:175], v[36:39]
	v_mfma_f32_16x16x32_bf16 v[32:35], v[152:155], v[168:171], v[32:35]
	v_mfma_f32_16x16x32_bf16 v[32:35], v[156:159], v[172:175], v[32:35]
	v_mfma_f32_16x16x32_bf16 v[20:23], v[144:147], v[176:179], v[20:23]
	v_mfma_f32_16x16x32_bf16 v[20:23], v[148:151], v[180:183], v[20:23]
	v_mfma_f32_16x16x32_bf16 v[16:19], v[152:155], v[176:179], v[16:19]
	v_mfma_f32_16x16x32_bf16 v[16:19], v[156:159], v[180:183], v[16:19]
	v_mfma_f32_16x16x32_bf16 v[4:7], v[144:147], v[184:187], v[4:7]
	v_mfma_f32_16x16x32_bf16 v[4:7], v[148:151], v[188:191], v[4:7]
	s_waitcnt vmcnt(8)
	s_setprio 3
	s_barrier
	v_mfma_f32_16x16x32_bf16 v[0:3], v[152:155], v[184:187], v[0:3]
	v_mfma_f32_16x16x32_bf16 v[0:3], v[156:159], v[188:191], v[0:3]
	s_setprio 0
.Lkazj_1_1:
	s_add_i32 s59, 0, 0x18000
	s_add_i32 s68, 0, 0x1c000
	v_add_u32_e32 v132, s59, v243
	v_add_u32_e32 v156, s68, v243
	ds_read_b128 v[120:123], v132
	ds_read_b128 v[124:127], v132 offset:1024
	ds_read_b128 v[128:131], v132 offset:2048
	ds_read_b128 v[132:135], v132 offset:3072
	ds_read_b128 v[144:147], v156
	ds_read_b128 v[148:151], v156 offset:1024
	ds_read_b128 v[152:155], v156 offset:2048
	ds_read_b128 v[156:159], v156 offset:3072
	s_add_u32 s66, s90, 0xb0000
	s_addc_u32 s67, s91, 0
	s_mov_b32 m0, s18
	v_lshl_add_u64 v[212:213], s[66:67], 0, v[192:193]
	ds_read_b128 v[160:163], v247 offset:32768
	ds_read_b128 v[164:167], v247 offset:33792
	ds_read_b128 v[168:171], v247 offset:34816
	ds_read_b128 v[172:175], v247 offset:35840
	ds_read_b128 v[176:179], v247 offset:36864
	ds_read_b128 v[180:183], v247 offset:37888
	ds_read_b128 v[184:187], v247 offset:38912
	ds_read_b128 v[188:191], v247 offset:39936
	global_load_lds_dwordx4 v[212:213], off
	s_mov_b32 m0, s19
	v_lshl_add_u64 v[212:213], s[66:67], 0, v[196:197]
	global_load_lds_dwordx4 v[212:213], off
	s_waitcnt lgkmcnt(0)
	s_barrier
	s_setprio 1
	v_mfma_f32_16x16x32_bf16 v[140:143], v[120:123], v[160:163], v[140:143]
	v_mfma_f32_16x16x32_bf16 v[140:143], v[124:127], v[164:167], v[140:143]
	v_mfma_f32_16x16x32_bf16 v[136:139], v[128:131], v[160:163], v[136:139]
	v_mfma_f32_16x16x32_bf16 v[136:139], v[132:135], v[164:167], v[136:139]
	v_mfma_f32_16x16x32_bf16 v[108:111], v[120:123], v[168:171], v[108:111]
	v_mfma_f32_16x16x32_bf16 v[108:111], v[124:127], v[172:175], v[108:111]
	v_mfma_f32_16x16x32_bf16 v[104:107], v[128:131], v[168:171], v[104:107]
	v_mfma_f32_16x16x32_bf16 v[104:107], v[132:135], v[172:175], v[104:107]
	v_mfma_f32_16x16x32_bf16 v[92:95], v[120:123], v[176:179], v[92:95]
	v_mfma_f32_16x16x32_bf16 v[92:95], v[124:127], v[180:183], v[92:95]
	v_mfma_f32_16x16x32_bf16 v[88:91], v[128:131], v[176:179], v[88:91]
	v_mfma_f32_16x16x32_bf16 v[88:91], v[132:135], v[180:183], v[88:91]
	v_mfma_f32_16x16x32_bf16 v[76:79], v[120:123], v[184:187], v[76:79]
	v_mfma_f32_16x16x32_bf16 v[76:79], v[124:127], v[188:191], v[76:79]
	v_mfma_f32_16x16x32_bf16 v[72:75], v[128:131], v[184:187], v[72:75]
	v_mfma_f32_16x16x32_bf16 v[72:75], v[132:135], v[188:191], v[72:75]
	v_mfma_f32_16x16x32_bf16 v[116:119], v[144:147], v[160:163], v[116:119]
	v_mfma_f32_16x16x32_bf16 v[116:119], v[148:151], v[164:167], v[116:119]
	v_mfma_f32_16x16x32_bf16 v[112:115], v[152:155], v[160:163], v[112:115]
	v_mfma_f32_16x16x32_bf16 v[112:115], v[156:159], v[164:167], v[112:115]
	v_mfma_f32_16x16x32_bf16 v[100:103], v[144:147], v[168:171], v[100:103]
	v_mfma_f32_16x16x32_bf16 v[100:103], v[148:151], v[172:175], v[100:103]
	v_mfma_f32_16x16x32_bf16 v[96:99], v[152:155], v[168:171], v[96:99]
	v_mfma_f32_16x16x32_bf16 v[96:99], v[156:159], v[172:175], v[96:99]
	v_mfma_f32_16x16x32_bf16 v[84:87], v[144:147], v[176:179], v[84:87]
	v_mfma_f32_16x16x32_bf16 v[84:87], v[148:151], v[180:183], v[84:87]
	v_mfma_f32_16x16x32_bf16 v[80:83], v[152:155], v[176:179], v[80:83]
	v_mfma_f32_16x16x32_bf16 v[80:83], v[156:159], v[180:183], v[80:83]
	v_mfma_f32_16x16x32_bf16 v[68:71], v[144:147], v[184:187], v[68:71]
	v_mfma_f32_16x16x32_bf16 v[68:71], v[148:151], v[188:191], v[68:71]
	s_waitcnt vmcnt(8)
	s_setprio 3
	s_barrier
	v_mfma_f32_16x16x32_bf16 v[64:67], v[152:155], v[184:187], v[64:67]
	v_mfma_f32_16x16x32_bf16 v[64:67], v[156:159], v[188:191], v[64:67]
	s_setprio 0
	s_add_i32 s59, s59, s15
	v_lshl_add_u64 v[204:205], v[204:205], 0, s[80:81]
	s_mov_b32 m0, s59
	ds_read_b128 v[160:163], v247 offset:49152
	ds_read_b128 v[164:167], v247 offset:50176
	ds_read_b128 v[168:171], v247 offset:51200
	ds_read_b128 v[172:175], v247 offset:52224
	ds_read_b128 v[176:179], v247 offset:53248
	ds_read_b128 v[180:183], v247 offset:54272
	ds_read_b128 v[184:187], v247 offset:55296
	ds_read_b128 v[188:191], v247 offset:56320
	global_load_lds_dwordx4 v[204:205], off
	s_add_i32 m0, s59, 0x2000
	s_add_u32 s66, s88, 0xb0080
	v_lshl_add_u64 v[204:205], v[206:207], 0, s[80:81]
	s_addc_u32 s67, s89, 0
	s_add_i32 s59, s68, s15
	global_load_lds_dwordx4 v[204:205], off
	s_mov_b32 m0, s59
	v_lshl_add_u64 v[204:205], s[66:67], 0, v[194:195]
	global_load_lds_dwordx4 v[204:205], off
	s_add_i32 m0, s59, 0x2000
	v_lshl_add_u64 v[204:205], s[66:67], 0, v[198:199]
	global_load_lds_dwordx4 v[204:205], off
	s_mov_b32 m0, s21
	v_lshl_add_u64 v[204:205], v[208:209], 0, s[80:81]
	global_load_lds_dwordx4 v[204:205], off
	s_mov_b32 m0, s22
	v_lshl_add_u64 v[204:205], v[210:211], 0, s[80:81]
	global_load_lds_dwordx4 v[204:205], off
	s_waitcnt lgkmcnt(0)
	s_barrier
	s_setprio 1
	v_mfma_f32_16x16x32_bf16 v[60:63], v[120:123], v[160:163], v[60:63]
	v_mfma_f32_16x16x32_bf16 v[60:63], v[124:127], v[164:167], v[60:63]
	v_mfma_f32_16x16x32_bf16 v[56:59], v[128:131], v[160:163], v[56:59]
	v_mfma_f32_16x16x32_bf16 v[56:59], v[132:135], v[164:167], v[56:59]
	v_mfma_f32_16x16x32_bf16 v[44:47], v[120:123], v[168:171], v[44:47]
	v_mfma_f32_16x16x32_bf16 v[44:47], v[124:127], v[172:175], v[44:47]
	v_mfma_f32_16x16x32_bf16 v[40:43], v[128:131], v[168:171], v[40:43]
	v_mfma_f32_16x16x32_bf16 v[40:43], v[132:135], v[172:175], v[40:43]
	v_mfma_f32_16x16x32_bf16 v[28:31], v[120:123], v[176:179], v[28:31]
	v_mfma_f32_16x16x32_bf16 v[28:31], v[124:127], v[180:183], v[28:31]
	v_mfma_f32_16x16x32_bf16 v[24:27], v[128:131], v[176:179], v[24:27]
	v_mfma_f32_16x16x32_bf16 v[24:27], v[132:135], v[180:183], v[24:27]
	v_mfma_f32_16x16x32_bf16 v[12:15], v[120:123], v[184:187], v[12:15]
	v_mfma_f32_16x16x32_bf16 v[12:15], v[124:127], v[188:191], v[12:15]
	v_mfma_f32_16x16x32_bf16 v[8:11], v[128:131], v[184:187], v[8:11]
	v_mfma_f32_16x16x32_bf16 v[8:11], v[132:135], v[188:191], v[8:11]
	v_mfma_f32_16x16x32_bf16 v[52:55], v[144:147], v[160:163], v[52:55]
	v_mfma_f32_16x16x32_bf16 v[52:55], v[148:151], v[164:167], v[52:55]
	v_mfma_f32_16x16x32_bf16 v[48:51], v[152:155], v[160:163], v[48:51]
	v_mfma_f32_16x16x32_bf16 v[48:51], v[156:159], v[164:167], v[48:51]
	v_mfma_f32_16x16x32_bf16 v[36:39], v[144:147], v[168:171], v[36:39]
	v_mfma_f32_16x16x32_bf16 v[36:39], v[148:151], v[172:175], v[36:39]
	v_mfma_f32_16x16x32_bf16 v[32:35], v[152:155], v[168:171], v[32:35]
	v_mfma_f32_16x16x32_bf16 v[32:35], v[156:159], v[172:175], v[32:35]
	v_mfma_f32_16x16x32_bf16 v[20:23], v[144:147], v[176:179], v[20:23]
	v_mfma_f32_16x16x32_bf16 v[20:23], v[148:151], v[180:183], v[20:23]
	v_mfma_f32_16x16x32_bf16 v[16:19], v[152:155], v[176:179], v[16:19]
	v_mfma_f32_16x16x32_bf16 v[16:19], v[156:159], v[180:183], v[16:19]
	v_mfma_f32_16x16x32_bf16 v[4:7], v[144:147], v[184:187], v[4:7]
	v_mfma_f32_16x16x32_bf16 v[4:7], v[148:151], v[188:191], v[4:7]
	s_waitcnt vmcnt(8)
	s_setprio 3
	s_barrier
	v_mfma_f32_16x16x32_bf16 v[0:3], v[152:155], v[184:187], v[0:3]
	v_mfma_f32_16x16x32_bf16 v[0:3], v[156:159], v[188:191], v[0:3]
	s_setprio 0
	s_add_i32 s58, s58, 2
	s_add_u32 s86, s86, 0x100
	s_addc_u32 s87, s87, 0
	s_add_u32 s56, s56, 0x100
	s_addc_u32 s57, s57, 0
	s_cmp_gt_u32 s58, 41
	s_cbranch_scc0 .Lka1_head
	s_branch .Lzskip_1
.Lkazv_1_0:
	v_mfma_f32_16x16x32_bf16 v[140:143], v[120:123], v[160:163], 0
	v_mfma_f32_16x16x32_bf16 v[140:143], v[124:127], v[164:167], v[140:143]
	v_mfma_f32_16x16x32_bf16 v[136:139], v[128:131], v[160:163], 0
	v_mfma_f32_16x16x32_bf16 v[136:139], v[132:135], v[164:167], v[136:139]
	v_mfma_f32_16x16x32_bf16 v[108:111], v[120:123], v[168:171], 0
	v_mfma_f32_16x16x32_bf16 v[108:111], v[124:127], v[172:175], v[108:111]
	v_mfma_f32_16x16x32_bf16 v[104:107], v[128:131], v[168:171], 0
	v_mfma_f32_16x16x32_bf16 v[104:107], v[132:135], v[172:175], v[104:107]
	v_mfma_f32_16x16x32_bf16 v[92:95], v[120:123], v[176:179], 0
	v_mfma_f32_16x16x32_bf16 v[92:95], v[124:127], v[180:183], v[92:95]
	v_mfma_f32_16x16x32_bf16 v[88:91], v[128:131], v[176:179], 0
	v_mfma_f32_16x16x32_bf16 v[88:91], v[132:135], v[180:183], v[88:91]
	v_mfma_f32_16x16x32_bf16 v[76:79], v[120:123], v[184:187], 0
	v_mfma_f32_16x16x32_bf16 v[76:79], v[124:127], v[188:191], v[76:79]
	v_mfma_f32_16x16x32_bf16 v[72:75], v[128:131], v[184:187], 0
	v_mfma_f32_16x16x32_bf16 v[72:75], v[132:135], v[188:191], v[72:75]
	v_mfma_f32_16x16x32_bf16 v[116:119], v[144:147], v[160:163], 0
	v_mfma_f32_16x16x32_bf16 v[116:119], v[148:151], v[164:167], v[116:119]
	v_mfma_f32_16x16x32_bf16 v[112:115], v[152:155], v[160:163], 0
	v_mfma_f32_16x16x32_bf16 v[112:115], v[156:159], v[164:167], v[112:115]
	v_mfma_f32_16x16x32_bf16 v[100:103], v[144:147], v[168:171], 0
	v_mfma_f32_16x16x32_bf16 v[100:103], v[148:151], v[172:175], v[100:103]
	v_mfma_f32_16x16x32_bf16 v[96:99], v[152:155], v[168:171], 0
	v_mfma_f32_16x16x32_bf16 v[96:99], v[156:159], v[172:175], v[96:99]
	v_mfma_f32_16x16x32_bf16 v[84:87], v[144:147], v[176:179], 0
	v_mfma_f32_16x16x32_bf16 v[84:87], v[148:151], v[180:183], v[84:87]
	v_mfma_f32_16x16x32_bf16 v[80:83], v[152:155], v[176:179], 0
	v_mfma_f32_16x16x32_bf16 v[80:83], v[156:159], v[180:183], v[80:83]
	v_mfma_f32_16x16x32_bf16 v[68:71], v[144:147], v[184:187], 0
	v_mfma_f32_16x16x32_bf16 v[68:71], v[148:151], v[188:191], v[68:71]
	s_waitcnt vmcnt(8)
	s_setprio 3
	s_barrier
	v_mfma_f32_16x16x32_bf16 v[64:67], v[152:155], v[184:187], 0
	v_mfma_f32_16x16x32_bf16 v[64:67], v[156:159], v[188:191], v[64:67]
	s_setprio 0
	s_branch .Lkazj_1_0
.Lkazv_1_1:
	v_mfma_f32_16x16x32_bf16 v[60:63], v[120:123], v[160:163], 0
	v_mfma_f32_16x16x32_bf16 v[60:63], v[124:127], v[164:167], v[60:63]
	v_mfma_f32_16x16x32_bf16 v[56:59], v[128:131], v[160:163], 0
	v_mfma_f32_16x16x32_bf16 v[56:59], v[132:135], v[164:167], v[56:59]
	v_mfma_f32_16x16x32_bf16 v[44:47], v[120:123], v[168:171], 0
	v_mfma_f32_16x16x32_bf16 v[44:47], v[124:127], v[172:175], v[44:47]
	v_mfma_f32_16x16x32_bf16 v[40:43], v[128:131], v[168:171], 0
	v_mfma_f32_16x16x32_bf16 v[40:43], v[132:135], v[172:175], v[40:43]
	v_mfma_f32_16x16x32_bf16 v[28:31], v[120:123], v[176:179], 0
	v_mfma_f32_16x16x32_bf16 v[28:31], v[124:127], v[180:183], v[28:31]
	v_mfma_f32_16x16x32_bf16 v[24:27], v[128:131], v[176:179], 0
	v_mfma_f32_16x16x32_bf16 v[24:27], v[132:135], v[180:183], v[24:27]
	v_mfma_f32_16x16x32_bf16 v[12:15], v[120:123], v[184:187], 0
	v_mfma_f32_16x16x32_bf16 v[12:15], v[124:127], v[188:191], v[12:15]
	v_mfma_f32_16x16x32_bf16 v[8:11], v[128:131], v[184:187], 0
	v_mfma_f32_16x16x32_bf16 v[8:11], v[132:135], v[188:191], v[8:11]
	v_mfma_f32_16x16x32_bf16 v[52:55], v[144:147], v[160:163], 0
	v_mfma_f32_16x16x32_bf16 v[52:55], v[148:151], v[164:167], v[52:55]
	v_mfma_f32_16x16x32_bf16 v[48:51], v[152:155], v[160:163], 0
	v_mfma_f32_16x16x32_bf16 v[48:51], v[156:159], v[164:167], v[48:51]
	v_mfma_f32_16x16x32_bf16 v[36:39], v[144:147], v[168:171], 0
	v_mfma_f32_16x16x32_bf16 v[36:39], v[148:151], v[172:175], v[36:39]
	v_mfma_f32_16x16x32_bf16 v[32:35], v[152:155], v[168:171], 0
	v_mfma_f32_16x16x32_bf16 v[32:35], v[156:159], v[172:175], v[32:35]
	v_mfma_f32_16x16x32_bf16 v[20:23], v[144:147], v[176:179], 0
	v_mfma_f32_16x16x32_bf16 v[20:23], v[148:151], v[180:183], v[20:23]
	v_mfma_f32_16x16x32_bf16 v[16:19], v[152:155], v[176:179], 0
	v_mfma_f32_16x16x32_bf16 v[16:19], v[156:159], v[180:183], v[16:19]
	v_mfma_f32_16x16x32_bf16 v[4:7], v[144:147], v[184:187], 0
	v_mfma_f32_16x16x32_bf16 v[4:7], v[148:151], v[188:191], v[4:7]
	s_waitcnt vmcnt(8)
	s_setprio 3
	s_barrier
	v_mfma_f32_16x16x32_bf16 v[0:3], v[152:155], v[184:187], 0
	v_mfma_f32_16x16x32_bf16 v[0:3], v[156:159], v[188:191], v[0:3]
	s_setprio 0
	s_branch .Lkazj_1_1
	s_branch .Lzskip_1

.LBB0_428:
	s_ashr_i32 s95, s94, 31
	s_lshl_b64 s[16:17], s[94:95], 19
	s_add_u32 s96, s12, s16
	s_addc_u32 s97, s13, s17
	s_and_b64 s[16:17], s[8:9], exec
	s_cselect_b32 s15, s97, s89
	s_cselect_b32 s16, s96, s88
	s_ashr_i32 s85, s84, 31
	s_lshl_b64 s[18:19], s[84:85], 19
	s_add_u32 s90, s54, s18
	s_addc_u32 s91, s55, s19
	s_and_b64 s[18:19], s[8:9], exec
	s_cselect_b32 s17, s91, s7
	s_cselect_b32 s18, s90, s6
	s_add_u32 s88, s88, 0x40080
	s_addc_u32 s89, s89, 0
	s_add_u32 s19, s6, 0x100
	v_mov_b32_e32 v0, 0
	s_addc_u32 s20, s7, 0
	s_mov_b32 s21, -2
	s_waitcnt lgkmcnt(0)
	s_and_b64 s[100:101], exec, s[82:83]
	s_cbranch_scc1 .Lka2_head

.Lka2_head:
	ds_read_b128 v[128:131], v203
	ds_read_b128 v[132:135], v203 offset:1024
	ds_read_b128 v[136:139], v203 offset:2048
	ds_read_b128 v[164:167], v203 offset:3072
	ds_read_b128 v[168:171], v204
	ds_read_b128 v[172:175], v204 offset:1024
	ds_read_b128 v[176:179], v204 offset:2048
	ds_read_b128 v[180:183], v204 offset:3072
	s_add_u32 s6, s88, 0xfffc0080
	s_addc_u32 s7, s89, -1
	s_cmp_eq_u32 s21, 12
	s_cselect_b32 vcc_hi, s15, s7
	s_cselect_b32 vcc_lo, s16, s6
	s_cselect_b32 s7, s17, s20
	s_cselect_b32 s6, s18, s19
	v_lshl_add_u64 v[196:197], s[88:89], 0, v[156:157]
	s_add_i32 m0, s58, 0xc000
	ds_read_b128 v[184:187], v205
	ds_read_b128 v[188:191], v205 offset:1024
	ds_read_b128 v[192:195], v205 offset:2048
	ds_read_b128 v[212:215], v205 offset:3072
	ds_read_b128 v[216:219], v205 offset:4096
	ds_read_b128 v[220:223], v205 offset:5120
	ds_read_b128 v[224:227], v205 offset:6144
	ds_read_b128 v[228:231], v205 offset:7168
	global_load_lds_dwordx4 v[196:197], off
	s_add_i32 m0, s58, 0xe000
	v_lshl_add_u64 v[196:197], s[88:89], 0, v[158:159]
	global_load_lds_dwordx4 v[196:197], off
	s_cmp_eq_u32 s21, -2
	s_waitcnt lgkmcnt(0)
	s_barrier
	s_setprio 1
	s_cbranch_scc1 .Lkazv_2_0
	v_mfma_f32_16x16x32_bf16 v[124:127], v[128:131], v[184:187], v[124:127]
	v_mfma_f32_16x16x32_bf16 v[124:127], v[132:135], v[188:191], v[124:127]
	v_mfma_f32_16x16x32_bf16 v[116:119], v[136:139], v[184:187], v[116:119]
	v_mfma_f32_16x16x32_bf16 v[116:119], v[164:167], v[188:191], v[116:119]
	v_mfma_f32_16x16x32_bf16 v[108:111], v[128:131], v[192:195], v[108:111]
	v_mfma_f32_16x16x32_bf16 v[108:111], v[132:135], v[212:215], v[108:111]
	v_mfma_f32_16x16x32_bf16 v[100:103], v[136:139], v[192:195], v[100:103]
	v_mfma_f32_16x16x32_bf16 v[100:103], v[164:167], v[212:215], v[100:103]
	v_mfma_f32_16x16x32_bf16 v[92:95], v[128:131], v[216:219], v[92:95]
	v_mfma_f32_16x16x32_bf16 v[92:95], v[132:135], v[220:223], v[92:95]
	v_mfma_f32_16x16x32_bf16 v[84:87], v[136:139], v[216:219], v[84:87]
	v_mfma_f32_16x16x32_bf16 v[84:87], v[164:167], v[220:223], v[84:87]
	v_mfma_f32_16x16x32_bf16 v[76:79], v[128:131], v[224:227], v[76:79]
	v_mfma_f32_16x16x32_bf16 v[76:79], v[132:135], v[228:231], v[76:79]
	v_mfma_f32_16x16x32_bf16 v[68:71], v[136:139], v[224:227], v[68:71]
	v_mfma_f32_16x16x32_bf16 v[68:71], v[164:167], v[228:231], v[68:71]
	v_mfma_f32_16x16x32_bf16 v[120:123], v[168:171], v[184:187], v[120:123]
	v_mfma_f32_16x16x32_bf16 v[120:123], v[172:175], v[188:191], v[120:123]
	v_mfma_f32_16x16x32_bf16 v[112:115], v[176:179], v[184:187], v[112:115]
	v_mfma_f32_16x16x32_bf16 v[112:115], v[180:183], v[188:191], v[112:115]
	v_mfma_f32_16x16x32_bf16 v[104:107], v[168:171], v[192:195], v[104:107]
	v_mfma_f32_16x16x32_bf16 v[104:107], v[172:175], v[212:215], v[104:107]
	v_mfma_f32_16x16x32_bf16 v[96:99], v[176:179], v[192:195], v[96:99]
	v_mfma_f32_16x16x32_bf16 v[96:99], v[180:183], v[212:215], v[96:99]
	v_mfma_f32_16x16x32_bf16 v[88:91], v[168:171], v[216:219], v[88:91]
	v_mfma_f32_16x16x32_bf16 v[88:91], v[172:175], v[220:223], v[88:91]
	v_mfma_f32_16x16x32_bf16 v[80:83], v[176:179], v[216:219], v[80:83]
	v_mfma_f32_16x16x32_bf16 v[80:83], v[180:183], v[220:223], v[80:83]
	v_mfma_f32_16x16x32_bf16 v[72:75], v[168:171], v[224:227], v[72:75]
	v_mfma_f32_16x16x32_bf16 v[72:75], v[172:175], v[228:231], v[72:75]
	s_waitcnt vmcnt(8)
	s_setprio 3
	s_barrier
	v_mfma_f32_16x16x32_bf16 v[64:67], v[176:179], v[224:227], v[64:67]
	v_mfma_f32_16x16x32_bf16 v[64:67], v[180:183], v[228:231], v[64:67]
	s_setprio 0
.Lkazj_2_0:
	s_add_i32 s22, s76, s57
	v_lshl_add_u64 v[196:197], s[6:7], 0, v[142:143]
	s_mov_b32 m0, s22
	ds_read_b128 v[184:187], v205 offset:16384
	ds_read_b128 v[188:191], v205 offset:17408
	ds_read_b128 v[192:195], v205 offset:18432
	ds_read_b128 v[212:215], v205 offset:19456
	ds_read_b128 v[216:219], v205 offset:20480
	ds_read_b128 v[220:223], v205 offset:21504
	ds_read_b128 v[224:227], v205 offset:22528
	ds_read_b128 v[228:231], v205 offset:23552
	global_load_lds_dwordx4 v[196:197], off
	s_add_i32 m0, s22, 0x2000
	s_add_u32 s22, s6, 0x40000
	v_lshl_add_u64 v[232:233], s[6:7], 0, v[146:147]
	s_addc_u32 s23, s7, 0
	s_add_i32 s24, s77, s57
	global_load_lds_dwordx4 v[232:233], off
	v_lshl_add_u64 v[234:235], s[22:23], 0, v[142:143]
	s_mov_b32 m0, s24
	global_load_lds_dwordx4 v[234:235], off
	s_add_i32 m0, s24, 0x2000
	v_lshl_add_u64 v[234:235], s[22:23], 0, v[146:147]
	global_load_lds_dwordx4 v[234:235], off
	s_mov_b32 m0, s58
	v_lshl_add_u64 v[234:235], vcc, 0, v[140:141]
	global_load_lds_dwordx4 v[234:235], off
	s_mov_b32 m0, s59
	v_lshl_add_u64 v[236:237], vcc, 0, v[144:145]
	global_load_lds_dwordx4 v[236:237], off
	s_cmp_eq_u32 s21, -2
	s_waitcnt lgkmcnt(0)
	s_barrier
	s_setprio 1
	s_cbranch_scc1 .Lkazv_2_1
	v_mfma_f32_16x16x32_bf16 v[60:63], v[128:131], v[184:187], v[60:63]
	v_mfma_f32_16x16x32_bf16 v[60:63], v[132:135], v[188:191], v[60:63]
	v_mfma_f32_16x16x32_bf16 v[52:55], v[136:139], v[184:187], v[52:55]
	v_mfma_f32_16x16x32_bf16 v[52:55], v[164:167], v[188:191], v[52:55]
	v_mfma_f32_16x16x32_bf16 v[44:47], v[128:131], v[192:195], v[44:47]
	v_mfma_f32_16x16x32_bf16 v[44:47], v[132:135], v[212:215], v[44:47]
	v_mfma_f32_16x16x32_bf16 v[36:39], v[136:139], v[192:195], v[36:39]
	v_mfma_f32_16x16x32_bf16 v[36:39], v[164:167], v[212:215], v[36:39]
	v_mfma_f32_16x16x32_bf16 v[28:31], v[128:131], v[216:219], v[28:31]
	v_mfma_f32_16x16x32_bf16 v[28:31], v[132:135], v[220:223], v[28:31]
	v_mfma_f32_16x16x32_bf16 v[20:23], v[136:139], v[216:219], v[20:23]
	v_mfma_f32_16x16x32_bf16 v[20:23], v[164:167], v[220:223], v[20:23]
	v_mfma_f32_16x16x32_bf16 v[12:15], v[128:131], v[224:227], v[12:15]
	v_mfma_f32_16x16x32_bf16 v[12:15], v[132:135], v[228:231], v[12:15]
	v_mfma_f32_16x16x32_bf16 v[4:7], v[136:139], v[224:227], v[4:7]
	v_mfma_f32_16x16x32_bf16 v[4:7], v[164:167], v[228:231], v[4:7]
	v_mfma_f32_16x16x32_bf16 v[56:59], v[168:171], v[184:187], v[56:59]
	v_mfma_f32_16x16x32_bf16 v[56:59], v[172:175], v[188:191], v[56:59]
	v_mfma_f32_16x16x32_bf16 v[48:51], v[176:179], v[184:187], v[48:51]
	v_mfma_f32_16x16x32_bf16 v[48:51], v[180:183], v[188:191], v[48:51]
	v_mfma_f32_16x16x32_bf16 v[40:43], v[168:171], v[192:195], v[40:43]
	v_mfma_f32_16x16x32_bf16 v[40:43], v[172:175], v[212:215], v[40:43]
	v_mfma_f32_16x16x32_bf16 v[32:35], v[176:179], v[192:195], v[32:35]
	v_mfma_f32_16x16x32_bf16 v[32:35], v[180:183], v[212:215], v[32:35]
	v_mfma_f32_16x16x32_bf16 v[24:27], v[168:171], v[216:219], v[24:27]
	v_mfma_f32_16x16x32_bf16 v[24:27], v[172:175], v[220:223], v[24:27]
	v_mfma_f32_16x16x32_bf16 v[16:19], v[176:179], v[216:219], v[16:19]
	v_mfma_f32_16x16x32_bf16 v[16:19], v[180:183], v[220:223], v[16:19]
	v_mfma_f32_16x16x32_bf16 v[8:11], v[168:171], v[224:227], v[8:11]
	v_mfma_f32_16x16x32_bf16 v[8:11], v[172:175], v[228:231], v[8:11]
	s_waitcnt vmcnt(8)
	s_setprio 3
	s_barrier
	v_mfma_f32_16x16x32_bf16 v[0:3], v[176:179], v[224:227], v[0:3]
	v_mfma_f32_16x16x32_bf16 v[0:3], v[180:183], v[228:231], v[0:3]
	s_setprio 0
.Lkazj_2_1:
	s_add_i32 s24, 0, 0x18000
	v_add_u32_e32 v150, s24, v200
	s_add_i32 s25, 0, 0x1c000
	ds_read_b128 v[128:131], v150
	ds_read_b128 v[132:135], v150 offset:1024
	ds_read_b128 v[136:139], v150 offset:2048
	ds_read_b128 v[164:167], v150 offset:3072
	v_add_u32_e32 v150, s25, v200
	ds_read_b128 v[168:171], v150
	ds_read_b128 v[172:175], v150 offset:1024
	ds_read_b128 v[176:179], v150 offset:2048
	ds_read_b128 v[180:183], v150 offset:3072
	s_add_u32 s22, vcc_lo, 0x40000
	s_addc_u32 s23, vcc_hi, 0
	s_mov_b32 m0, s66
	v_lshl_add_u64 v[238:239], s[22:23], 0, v[140:141]
	ds_read_b128 v[184:187], v205 offset:32768
	ds_read_b128 v[188:191], v205 offset:33792
	ds_read_b128 v[192:195], v205 offset:34816
	ds_read_b128 v[212:215], v205 offset:35840
	ds_read_b128 v[216:219], v205 offset:36864
	ds_read_b128 v[220:223], v205 offset:37888
	ds_read_b128 v[224:227], v205 offset:38912
	ds_read_b128 v[228:231], v205 offset:39936
	global_load_lds_dwordx4 v[238:239], off
	s_mov_b32 m0, s67
	v_lshl_add_u64 v[238:239], s[22:23], 0, v[144:145]
	global_load_lds_dwordx4 v[238:239], off
	s_waitcnt lgkmcnt(0)
	s_barrier
	s_setprio 1
	v_mfma_f32_16x16x32_bf16 v[124:127], v[128:131], v[184:187], v[124:127]
	v_mfma_f32_16x16x32_bf16 v[124:127], v[132:135], v[188:191], v[124:127]
	v_mfma_f32_16x16x32_bf16 v[116:119], v[136:139], v[184:187], v[116:119]
	v_mfma_f32_16x16x32_bf16 v[116:119], v[164:167], v[188:191], v[116:119]
	v_mfma_f32_16x16x32_bf16 v[108:111], v[128:131], v[192:195], v[108:111]
	v_mfma_f32_16x16x32_bf16 v[108:111], v[132:135], v[212:215], v[108:111]
	v_mfma_f32_16x16x32_bf16 v[100:103], v[136:139], v[192:195], v[100:103]
	v_mfma_f32_16x16x32_bf16 v[100:103], v[164:167], v[212:215], v[100:103]
	v_mfma_f32_16x16x32_bf16 v[92:95], v[128:131], v[216:219], v[92:95]
	v_mfma_f32_16x16x32_bf16 v[92:95], v[132:135], v[220:223], v[92:95]
	v_mfma_f32_16x16x32_bf16 v[84:87], v[136:139], v[216:219], v[84:87]
	v_mfma_f32_16x16x32_bf16 v[84:87], v[164:167], v[220:223], v[84:87]
	v_mfma_f32_16x16x32_bf16 v[76:79], v[128:131], v[224:227], v[76:79]
	v_mfma_f32_16x16x32_bf16 v[76:79], v[132:135], v[228:231], v[76:79]
	v_mfma_f32_16x16x32_bf16 v[68:71], v[136:139], v[224:227], v[68:71]
	v_mfma_f32_16x16x32_bf16 v[68:71], v[164:167], v[228:231], v[68:71]
	v_mfma_f32_16x16x32_bf16 v[120:123], v[168:171], v[184:187], v[120:123]
	v_mfma_f32_16x16x32_bf16 v[120:123], v[172:175], v[188:191], v[120:123]
	v_mfma_f32_16x16x32_bf16 v[112:115], v[176:179], v[184:187], v[112:115]
	v_mfma_f32_16x16x32_bf16 v[112:115], v[180:183], v[188:191], v[112:115]
	v_mfma_f32_16x16x32_bf16 v[104:107], v[168:171], v[192:195], v[104:107]
	v_mfma_f32_16x16x32_bf16 v[104:107], v[172:175], v[212:215], v[104:107]
	v_mfma_f32_16x16x32_bf16 v[96:99], v[176:179], v[192:195], v[96:99]
	v_mfma_f32_16x16x32_bf16 v[96:99], v[180:183], v[212:215], v[96:99]
	v_mfma_f32_16x16x32_bf16 v[88:91], v[168:171], v[216:219], v[88:91]
	v_mfma_f32_16x16x32_bf16 v[88:91], v[172:175], v[220:223], v[88:91]
	v_mfma_f32_16x16x32_bf16 v[80:83], v[176:179], v[216:219], v[80:83]
	v_mfma_f32_16x16x32_bf16 v[80:83], v[180:183], v[220:223], v[80:83]
	v_mfma_f32_16x16x32_bf16 v[72:75], v[168:171], v[224:227], v[72:75]
	v_mfma_f32_16x16x32_bf16 v[72:75], v[172:175], v[228:231], v[72:75]
	s_waitcnt vmcnt(8)
	s_setprio 3
	s_barrier
	v_mfma_f32_16x16x32_bf16 v[64:67], v[176:179], v[224:227], v[64:67]
	v_mfma_f32_16x16x32_bf16 v[64:67], v[180:183], v[228:231], v[64:67]
	s_setprio 0
	s_add_i32 s22, s24, s57
	v_lshl_add_u64 v[196:197], v[196:197], 0, s[80:81]
	s_mov_b32 m0, s22
	ds_read_b128 v[184:187], v205 offset:49152
	ds_read_b128 v[188:191], v205 offset:50176
	ds_read_b128 v[192:195], v205 offset:51200
	ds_read_b128 v[212:215], v205 offset:52224
	ds_read_b128 v[216:219], v205 offset:53248
	ds_read_b128 v[220:223], v205 offset:54272
	ds_read_b128 v[224:227], v205 offset:55296
	ds_read_b128 v[228:231], v205 offset:56320
	global_load_lds_dwordx4 v[196:197], off
	s_add_i32 m0, s22, 0x2000
	s_add_u32 s6, s6, 0x40080
	v_lshl_add_u64 v[196:197], v[232:233], 0, s[80:81]
	s_addc_u32 s7, s7, 0
	s_add_i32 s22, s25, s57
	global_load_lds_dwordx4 v[196:197], off
	s_mov_b32 m0, s22
	v_lshl_add_u64 v[196:197], s[6:7], 0, v[142:143]
	global_load_lds_dwordx4 v[196:197], off
	s_add_i32 m0, s22, 0x2000
	v_lshl_add_u64 v[196:197], s[6:7], 0, v[146:147]
	global_load_lds_dwordx4 v[196:197], off
	s_mov_b32 m0, s93
	v_lshl_add_u64 v[196:197], v[234:235], 0, s[80:81]
	global_load_lds_dwordx4 v[196:197], off
	s_mov_b32 m0, s69
	v_lshl_add_u64 v[196:197], v[236:237], 0, s[80:81]
	global_load_lds_dwordx4 v[196:197], off
	s_waitcnt lgkmcnt(0)
	s_barrier
	s_setprio 1
	v_mfma_f32_16x16x32_bf16 v[60:63], v[128:131], v[184:187], v[60:63]
	v_mfma_f32_16x16x32_bf16 v[60:63], v[132:135], v[188:191], v[60:63]
	v_mfma_f32_16x16x32_bf16 v[52:55], v[136:139], v[184:187], v[52:55]
	v_mfma_f32_16x16x32_bf16 v[52:55], v[164:167], v[188:191], v[52:55]
	v_mfma_f32_16x16x32_bf16 v[44:47], v[128:131], v[192:195], v[44:47]
	v_mfma_f32_16x16x32_bf16 v[44:47], v[132:135], v[212:215], v[44:47]
	v_mfma_f32_16x16x32_bf16 v[36:39], v[136:139], v[192:195], v[36:39]
	v_mfma_f32_16x16x32_bf16 v[36:39], v[164:167], v[212:215], v[36:39]
	v_mfma_f32_16x16x32_bf16 v[28:31], v[128:131], v[216:219], v[28:31]
	v_mfma_f32_16x16x32_bf16 v[28:31], v[132:135], v[220:223], v[28:31]
	v_mfma_f32_16x16x32_bf16 v[20:23], v[136:139], v[216:219], v[20:23]
	v_mfma_f32_16x16x32_bf16 v[20:23], v[164:167], v[220:223], v[20:23]
	v_mfma_f32_16x16x32_bf16 v[12:15], v[128:131], v[224:227], v[12:15]
	v_mfma_f32_16x16x32_bf16 v[12:15], v[132:135], v[228:231], v[12:15]
	v_mfma_f32_16x16x32_bf16 v[4:7], v[136:139], v[224:227], v[4:7]
	v_mfma_f32_16x16x32_bf16 v[4:7], v[164:167], v[228:231], v[4:7]
	v_mfma_f32_16x16x32_bf16 v[56:59], v[168:171], v[184:187], v[56:59]
	v_mfma_f32_16x16x32_bf16 v[56:59], v[172:175], v[188:191], v[56:59]
	v_mfma_f32_16x16x32_bf16 v[48:51], v[176:179], v[184:187], v[48:51]
	v_mfma_f32_16x16x32_bf16 v[48:51], v[180:183], v[188:191], v[48:51]
	v_mfma_f32_16x16x32_bf16 v[40:43], v[168:171], v[192:195], v[40:43]
	v_mfma_f32_16x16x32_bf16 v[40:43], v[172:175], v[212:215], v[40:43]
	v_mfma_f32_16x16x32_bf16 v[32:35], v[176:179], v[192:195], v[32:35]
	v_mfma_f32_16x16x32_bf16 v[32:35], v[180:183], v[212:215], v[32:35]
	v_mfma_f32_16x16x32_bf16 v[24:27], v[168:171], v[216:219], v[24:27]
	v_mfma_f32_16x16x32_bf16 v[24:27], v[172:175], v[220:223], v[24:27]
	v_mfma_f32_16x16x32_bf16 v[16:19], v[176:179], v[216:219], v[16:19]
	v_mfma_f32_16x16x32_bf16 v[16:19], v[180:183], v[220:223], v[16:19]
	v_mfma_f32_16x16x32_bf16 v[8:11], v[168:171], v[224:227], v[8:11]
	v_mfma_f32_16x16x32_bf16 v[8:11], v[172:175], v[228:231], v[8:11]
	s_waitcnt vmcnt(8)
	s_setprio 3
	s_barrier
	v_mfma_f32_16x16x32_bf16 v[0:3], v[176:179], v[224:227], v[0:3]
	v_mfma_f32_16x16x32_bf16 v[0:3], v[180:183], v[228:231], v[0:3]
	s_setprio 0
	s_add_i32 s21, s21, 2
	s_add_u32 s88, s88, 0x100
	s_addc_u32 s89, s89, 0
	s_add_u32 s19, s19, 0x100
	s_addc_u32 s20, s20, 0
	s_cmp_gt_u32 s21, 13
	s_cbranch_scc0 .Lka2_head
	s_branch .Lzskip_2
.Lkazv_2_0:
	v_mfma_f32_16x16x32_bf16 v[124:127], v[128:131], v[184:187], 0
	v_mfma_f32_16x16x32_bf16 v[124:127], v[132:135], v[188:191], v[124:127]
	v_mfma_f32_16x16x32_bf16 v[116:119], v[136:139], v[184:187], 0
	v_mfma_f32_16x16x32_bf16 v[116:119], v[164:167], v[188:191], v[116:119]
	v_mfma_f32_16x16x32_bf16 v[108:111], v[128:131], v[192:195], 0
	v_mfma_f32_16x16x32_bf16 v[108:111], v[132:135], v[212:215], v[108:111]
	v_mfma_f32_16x16x32_bf16 v[100:103], v[136:139], v[192:195], 0
	v_mfma_f32_16x16x32_bf16 v[100:103], v[164:167], v[212:215], v[100:103]
	v_mfma_f32_16x16x32_bf16 v[92:95], v[128:131], v[216:219], 0
	v_mfma_f32_16x16x32_bf16 v[92:95], v[132:135], v[220:223], v[92:95]
	v_mfma_f32_16x16x32_bf16 v[84:87], v[136:139], v[216:219], 0
	v_mfma_f32_16x16x32_bf16 v[84:87], v[164:167], v[220:223], v[84:87]
	v_mfma_f32_16x16x32_bf16 v[76:79], v[128:131], v[224:227], 0
	v_mfma_f32_16x16x32_bf16 v[76:79], v[132:135], v[228:231], v[76:79]
	v_mfma_f32_16x16x32_bf16 v[68:71], v[136:139], v[224:227], 0
	v_mfma_f32_16x16x32_bf16 v[68:71], v[164:167], v[228:231], v[68:71]
	v_mfma_f32_16x16x32_bf16 v[120:123], v[168:171], v[184:187], 0
	v_mfma_f32_16x16x32_bf16 v[120:123], v[172:175], v[188:191], v[120:123]
	v_mfma_f32_16x16x32_bf16 v[112:115], v[176:179], v[184:187], 0
	v_mfma_f32_16x16x32_bf16 v[112:115], v[180:183], v[188:191], v[112:115]
	v_mfma_f32_16x16x32_bf16 v[104:107], v[168:171], v[192:195], 0
	v_mfma_f32_16x16x32_bf16 v[104:107], v[172:175], v[212:215], v[104:107]
	v_mfma_f32_16x16x32_bf16 v[96:99], v[176:179], v[192:195], 0
	v_mfma_f32_16x16x32_bf16 v[96:99], v[180:183], v[212:215], v[96:99]
	v_mfma_f32_16x16x32_bf16 v[88:91], v[168:171], v[216:219], 0
	v_mfma_f32_16x16x32_bf16 v[88:91], v[172:175], v[220:223], v[88:91]
	v_mfma_f32_16x16x32_bf16 v[80:83], v[176:179], v[216:219], 0
	v_mfma_f32_16x16x32_bf16 v[80:83], v[180:183], v[220:223], v[80:83]
	v_mfma_f32_16x16x32_bf16 v[72:75], v[168:171], v[224:227], 0
	v_mfma_f32_16x16x32_bf16 v[72:75], v[172:175], v[228:231], v[72:75]
	s_waitcnt vmcnt(8)
	s_setprio 3
	s_barrier
	v_mfma_f32_16x16x32_bf16 v[64:67], v[176:179], v[224:227], 0
	v_mfma_f32_16x16x32_bf16 v[64:67], v[180:183], v[228:231], v[64:67]
	s_setprio 0
	s_branch .Lkazj_2_0
.Lkazv_2_1:
	v_mfma_f32_16x16x32_bf16 v[60:63], v[128:131], v[184:187], 0
	v_mfma_f32_16x16x32_bf16 v[60:63], v[132:135], v[188:191], v[60:63]
	v_mfma_f32_16x16x32_bf16 v[52:55], v[136:139], v[184:187], 0
	v_mfma_f32_16x16x32_bf16 v[52:55], v[164:167], v[188:191], v[52:55]
	v_mfma_f32_16x16x32_bf16 v[44:47], v[128:131], v[192:195], 0
	v_mfma_f32_16x16x32_bf16 v[44:47], v[132:135], v[212:215], v[44:47]
	v_mfma_f32_16x16x32_bf16 v[36:39], v[136:139], v[192:195], 0
	v_mfma_f32_16x16x32_bf16 v[36:39], v[164:167], v[212:215], v[36:39]
	v_mfma_f32_16x16x32_bf16 v[28:31], v[128:131], v[216:219], 0
	v_mfma_f32_16x16x32_bf16 v[28:31], v[132:135], v[220:223], v[28:31]
	v_mfma_f32_16x16x32_bf16 v[20:23], v[136:139], v[216:219], 0
	v_mfma_f32_16x16x32_bf16 v[20:23], v[164:167], v[220:223], v[20:23]
	v_mfma_f32_16x16x32_bf16 v[12:15], v[128:131], v[224:227], 0
	v_mfma_f32_16x16x32_bf16 v[12:15], v[132:135], v[228:231], v[12:15]
	v_mfma_f32_16x16x32_bf16 v[4:7], v[136:139], v[224:227], 0
	v_mfma_f32_16x16x32_bf16 v[4:7], v[164:167], v[228:231], v[4:7]
	v_mfma_f32_16x16x32_bf16 v[56:59], v[168:171], v[184:187], 0
	v_mfma_f32_16x16x32_bf16 v[56:59], v[172:175], v[188:191], v[56:59]
	v_mfma_f32_16x16x32_bf16 v[48:51], v[176:179], v[184:187], 0
	v_mfma_f32_16x16x32_bf16 v[48:51], v[180:183], v[188:191], v[48:51]
	v_mfma_f32_16x16x32_bf16 v[40:43], v[168:171], v[192:195], 0
	v_mfma_f32_16x16x32_bf16 v[40:43], v[172:175], v[212:215], v[40:43]
	v_mfma_f32_16x16x32_bf16 v[32:35], v[176:179], v[192:195], 0
	v_mfma_f32_16x16x32_bf16 v[32:35], v[180:183], v[212:215], v[32:35]
	v_mfma_f32_16x16x32_bf16 v[24:27], v[168:171], v[216:219], 0
	v_mfma_f32_16x16x32_bf16 v[24:27], v[172:175], v[220:223], v[24:27]
	v_mfma_f32_16x16x32_bf16 v[16:19], v[176:179], v[216:219], 0
	v_mfma_f32_16x16x32_bf16 v[16:19], v[180:183], v[220:223], v[16:19]
	v_mfma_f32_16x16x32_bf16 v[8:11], v[168:171], v[224:227], 0
	v_mfma_f32_16x16x32_bf16 v[8:11], v[172:175], v[228:231], v[8:11]
	s_waitcnt vmcnt(8)
	s_setprio 3
	s_barrier
	v_mfma_f32_16x16x32_bf16 v[0:3], v[176:179], v[224:227], 0
	v_mfma_f32_16x16x32_bf16 v[0:3], v[180:183], v[228:231], v[0:3]
	s_setprio 0
	s_branch .Lkazj_2_1
	s_branch .Lzskip_2

.LBB0_992:
	s_ashr_i32 s53, s52, 31
	s_lshl_b64 s[54:55], s[52:53], 19
	s_add_u32 s76, s42, s54
	s_addc_u32 s77, s43, s55
	s_and_b64 s[54:55], s[6:7], exec
	s_cselect_b32 s53, s77, s83
	s_cselect_b32 s54, s76, s82
	s_ashr_i32 s51, s50, 31
	s_lshl_b64 s[56:57], s[50:51], 19
	s_add_u32 s78, s3, s56
	s_addc_u32 s79, s14, s57
	s_and_b64 s[56:57], s[6:7], exec
	s_cselect_b32 s51, s79, s85
	s_cselect_b32 s55, s78, s84
	s_add_u32 s82, s82, 0x40080
	s_addc_u32 s83, s83, 0
	s_add_u32 s56, s84, 0x100
	v_mov_b32_e32 v0, 0
	s_addc_u32 s57, s85, 0
	s_mov_b32 s58, -2
	s_and_b64 s[100:101], exec, s[48:49]
	s_cbranch_scc1 .Lka3_head

.Lka3_head:
	ds_read_b128 v[120:123], v245
	ds_read_b128 v[124:127], v245 offset:1024
	ds_read_b128 v[128:131], v245 offset:2048
	ds_read_b128 v[132:135], v245 offset:3072
	ds_read_b128 v[144:147], v246
	ds_read_b128 v[148:151], v246 offset:1024
	ds_read_b128 v[152:155], v246 offset:2048
	ds_read_b128 v[156:159], v246 offset:3072
	s_add_u32 s59, s82, 0xfffc0080
	s_addc_u32 s66, s83, -1
	s_cmp_eq_u32 s58, 12
	s_cselect_b32 s87, s53, s66
	s_cselect_b32 s86, s54, s59
	s_cselect_b32 s85, s51, s57
	s_cselect_b32 s84, s55, s56
	v_lshl_add_u64 v[204:205], s[82:83], 0, v[200:201]
	s_add_i32 m0, s16, 0xc000
	ds_read_b128 v[160:163], v247
	ds_read_b128 v[164:167], v247 offset:1024
	ds_read_b128 v[168:171], v247 offset:2048
	ds_read_b128 v[172:175], v247 offset:3072
	ds_read_b128 v[176:179], v247 offset:4096
	ds_read_b128 v[180:183], v247 offset:5120
	ds_read_b128 v[184:187], v247 offset:6144
	ds_read_b128 v[188:191], v247 offset:7168
	global_load_lds_dwordx4 v[204:205], off
	s_add_i32 m0, s16, 0xe000
	v_lshl_add_u64 v[204:205], s[82:83], 0, v[202:203]
	global_load_lds_dwordx4 v[204:205], off
	s_cmp_eq_u32 s58, -2
	s_waitcnt lgkmcnt(0)
	s_barrier
	s_setprio 1
	s_cbranch_scc1 .Lkazv_3_0
	v_mfma_f32_16x16x32_bf16 v[140:143], v[120:123], v[160:163], v[140:143]
	v_mfma_f32_16x16x32_bf16 v[140:143], v[124:127], v[164:167], v[140:143]
	v_mfma_f32_16x16x32_bf16 v[136:139], v[128:131], v[160:163], v[136:139]
	v_mfma_f32_16x16x32_bf16 v[136:139], v[132:135], v[164:167], v[136:139]
	v_mfma_f32_16x16x32_bf16 v[108:111], v[120:123], v[168:171], v[108:111]
	v_mfma_f32_16x16x32_bf16 v[108:111], v[124:127], v[172:175], v[108:111]
	v_mfma_f32_16x16x32_bf16 v[104:107], v[128:131], v[168:171], v[104:107]
	v_mfma_f32_16x16x32_bf16 v[104:107], v[132:135], v[172:175], v[104:107]
	v_mfma_f32_16x16x32_bf16 v[92:95], v[120:123], v[176:179], v[92:95]
	v_mfma_f32_16x16x32_bf16 v[92:95], v[124:127], v[180:183], v[92:95]
	v_mfma_f32_16x16x32_bf16 v[88:91], v[128:131], v[176:179], v[88:91]
	v_mfma_f32_16x16x32_bf16 v[88:91], v[132:135], v[180:183], v[88:91]
	v_mfma_f32_16x16x32_bf16 v[76:79], v[120:123], v[184:187], v[76:79]
	v_mfma_f32_16x16x32_bf16 v[76:79], v[124:127], v[188:191], v[76:79]
	v_mfma_f32_16x16x32_bf16 v[72:75], v[128:131], v[184:187], v[72:75]
	v_mfma_f32_16x16x32_bf16 v[72:75], v[132:135], v[188:191], v[72:75]
	v_mfma_f32_16x16x32_bf16 v[116:119], v[144:147], v[160:163], v[116:119]
	v_mfma_f32_16x16x32_bf16 v[116:119], v[148:151], v[164:167], v[116:119]
	v_mfma_f32_16x16x32_bf16 v[112:115], v[152:155], v[160:163], v[112:115]
	v_mfma_f32_16x16x32_bf16 v[112:115], v[156:159], v[164:167], v[112:115]
	v_mfma_f32_16x16x32_bf16 v[100:103], v[144:147], v[168:171], v[100:103]
	v_mfma_f32_16x16x32_bf16 v[100:103], v[148:151], v[172:175], v[100:103]
	v_mfma_f32_16x16x32_bf16 v[96:99], v[152:155], v[168:171], v[96:99]
	v_mfma_f32_16x16x32_bf16 v[96:99], v[156:159], v[172:175], v[96:99]
	v_mfma_f32_16x16x32_bf16 v[84:87], v[144:147], v[176:179], v[84:87]
	v_mfma_f32_16x16x32_bf16 v[84:87], v[148:151], v[180:183], v[84:87]
	v_mfma_f32_16x16x32_bf16 v[80:83], v[152:155], v[176:179], v[80:83]
	v_mfma_f32_16x16x32_bf16 v[80:83], v[156:159], v[180:183], v[80:83]
	v_mfma_f32_16x16x32_bf16 v[68:71], v[144:147], v[184:187], v[68:71]
	v_mfma_f32_16x16x32_bf16 v[68:71], v[148:151], v[188:191], v[68:71]
	s_waitcnt vmcnt(8)
	s_setprio 3
	s_barrier
	v_mfma_f32_16x16x32_bf16 v[64:67], v[152:155], v[184:187], v[64:67]
	v_mfma_f32_16x16x32_bf16 v[64:67], v[156:159], v[188:191], v[64:67]
	s_setprio 0
.Lkazj_3_0:
	s_add_i32 s59, s26, s15
	v_lshl_add_u64 v[204:205], s[84:85], 0, v[194:195]
	s_mov_b32 m0, s59
	ds_read_b128 v[160:163], v247 offset:16384
	ds_read_b128 v[164:167], v247 offset:17408
	ds_read_b128 v[168:171], v247 offset:18432
	ds_read_b128 v[172:175], v247 offset:19456
	ds_read_b128 v[176:179], v247 offset:20480
	ds_read_b128 v[180:183], v247 offset:21504
	ds_read_b128 v[184:187], v247 offset:22528
	ds_read_b128 v[188:191], v247 offset:23552
	global_load_lds_dwordx4 v[204:205], off
	s_add_i32 m0, s59, 0x2000
	s_add_u32 s66, s84, 0x40000
	v_lshl_add_u64 v[206:207], s[84:85], 0, v[198:199]
	s_addc_u32 s67, s85, 0
	s_add_i32 s59, s27, s15
	global_load_lds_dwordx4 v[206:207], off
	v_lshl_add_u64 v[208:209], s[66:67], 0, v[194:195]
	s_mov_b32 m0, s59
	global_load_lds_dwordx4 v[208:209], off
	s_add_i32 m0, s59, 0x2000
	v_lshl_add_u64 v[208:209], s[66:67], 0, v[198:199]
	global_load_lds_dwordx4 v[208:209], off
	s_mov_b32 m0, s16
	v_lshl_add_u64 v[208:209], s[86:87], 0, v[192:193]
	global_load_lds_dwordx4 v[208:209], off
	s_mov_b32 m0, s17
	v_lshl_add_u64 v[210:211], s[86:87], 0, v[196:197]
	global_load_lds_dwordx4 v[210:211], off
	s_cmp_eq_u32 s58, -2
	s_waitcnt lgkmcnt(0)
	s_barrier
	s_setprio 1
	s_cbranch_scc1 .Lkazv_3_1
	v_mfma_f32_16x16x32_bf16 v[60:63], v[120:123], v[160:163], v[60:63]
	v_mfma_f32_16x16x32_bf16 v[60:63], v[124:127], v[164:167], v[60:63]
	v_mfma_f32_16x16x32_bf16 v[56:59], v[128:131], v[160:163], v[56:59]
	v_mfma_f32_16x16x32_bf16 v[56:59], v[132:135], v[164:167], v[56:59]
	v_mfma_f32_16x16x32_bf16 v[44:47], v[120:123], v[168:171], v[44:47]
	v_mfma_f32_16x16x32_bf16 v[44:47], v[124:127], v[172:175], v[44:47]
	v_mfma_f32_16x16x32_bf16 v[40:43], v[128:131], v[168:171], v[40:43]
	v_mfma_f32_16x16x32_bf16 v[40:43], v[132:135], v[172:175], v[40:43]
	v_mfma_f32_16x16x32_bf16 v[28:31], v[120:123], v[176:179], v[28:31]
	v_mfma_f32_16x16x32_bf16 v[28:31], v[124:127], v[180:183], v[28:31]
	v_mfma_f32_16x16x32_bf16 v[24:27], v[128:131], v[176:179], v[24:27]
	v_mfma_f32_16x16x32_bf16 v[24:27], v[132:135], v[180:183], v[24:27]
	v_mfma_f32_16x16x32_bf16 v[12:15], v[120:123], v[184:187], v[12:15]
	v_mfma_f32_16x16x32_bf16 v[12:15], v[124:127], v[188:191], v[12:15]
	v_mfma_f32_16x16x32_bf16 v[8:11], v[128:131], v[184:187], v[8:11]
	v_mfma_f32_16x16x32_bf16 v[8:11], v[132:135], v[188:191], v[8:11]
	v_mfma_f32_16x16x32_bf16 v[52:55], v[144:147], v[160:163], v[52:55]
	v_mfma_f32_16x16x32_bf16 v[52:55], v[148:151], v[164:167], v[52:55]
	v_mfma_f32_16x16x32_bf16 v[48:51], v[152:155], v[160:163], v[48:51]
	v_mfma_f32_16x16x32_bf16 v[48:51], v[156:159], v[164:167], v[48:51]
	v_mfma_f32_16x16x32_bf16 v[36:39], v[144:147], v[168:171], v[36:39]
	v_mfma_f32_16x16x32_bf16 v[36:39], v[148:151], v[172:175], v[36:39]
	v_mfma_f32_16x16x32_bf16 v[32:35], v[152:155], v[168:171], v[32:35]
	v_mfma_f32_16x16x32_bf16 v[32:35], v[156:159], v[172:175], v[32:35]
	v_mfma_f32_16x16x32_bf16 v[20:23], v[144:147], v[176:179], v[20:23]
	v_mfma_f32_16x16x32_bf16 v[20:23], v[148:151], v[180:183], v[20:23]
	v_mfma_f32_16x16x32_bf16 v[16:19], v[152:155], v[176:179], v[16:19]
	v_mfma_f32_16x16x32_bf16 v[16:19], v[156:159], v[180:183], v[16:19]
	v_mfma_f32_16x16x32_bf16 v[4:7], v[144:147], v[184:187], v[4:7]
	v_mfma_f32_16x16x32_bf16 v[4:7], v[148:151], v[188:191], v[4:7]
	s_waitcnt vmcnt(8)
	s_setprio 3
	s_barrier
	v_mfma_f32_16x16x32_bf16 v[0:3], v[152:155], v[184:187], v[0:3]
	v_mfma_f32_16x16x32_bf16 v[0:3], v[156:159], v[188:191], v[0:3]
	s_setprio 0
.Lkazj_3_1:
	s_add_i32 s59, 0, 0x18000
	s_add_i32 s68, 0, 0x1c000
	v_add_u32_e32 v132, s59, v243
	v_add_u32_e32 v156, s68, v243
	ds_read_b128 v[120:123], v132
	ds_read_b128 v[124:127], v132 offset:1024
	ds_read_b128 v[128:131], v132 offset:2048
	ds_read_b128 v[132:135], v132 offset:3072
	ds_read_b128 v[144:147], v156
	ds_read_b128 v[148:151], v156 offset:1024
	ds_read_b128 v[152:155], v156 offset:2048
	ds_read_b128 v[156:159], v156 offset:3072
	s_add_u32 s66, s86, 0x40000
	s_addc_u32 s67, s87, 0
	s_mov_b32 m0, s18
	v_lshl_add_u64 v[212:213], s[66:67], 0, v[192:193]
	ds_read_b128 v[160:163], v247 offset:32768
	ds_read_b128 v[164:167], v247 offset:33792
	ds_read_b128 v[168:171], v247 offset:34816
	ds_read_b128 v[172:175], v247 offset:35840
	ds_read_b128 v[176:179], v247 offset:36864
	ds_read_b128 v[180:183], v247 offset:37888
	ds_read_b128 v[184:187], v247 offset:38912
	ds_read_b128 v[188:191], v247 offset:39936
	global_load_lds_dwordx4 v[212:213], off
	s_mov_b32 m0, s19
	v_lshl_add_u64 v[212:213], s[66:67], 0, v[196:197]
	global_load_lds_dwordx4 v[212:213], off
	s_waitcnt lgkmcnt(0)
	s_barrier
	s_setprio 1
	v_mfma_f32_16x16x32_bf16 v[140:143], v[120:123], v[160:163], v[140:143]
	v_mfma_f32_16x16x32_bf16 v[140:143], v[124:127], v[164:167], v[140:143]
	v_mfma_f32_16x16x32_bf16 v[136:139], v[128:131], v[160:163], v[136:139]
	v_mfma_f32_16x16x32_bf16 v[136:139], v[132:135], v[164:167], v[136:139]
	v_mfma_f32_16x16x32_bf16 v[108:111], v[120:123], v[168:171], v[108:111]
	v_mfma_f32_16x16x32_bf16 v[108:111], v[124:127], v[172:175], v[108:111]
	v_mfma_f32_16x16x32_bf16 v[104:107], v[128:131], v[168:171], v[104:107]
	v_mfma_f32_16x16x32_bf16 v[104:107], v[132:135], v[172:175], v[104:107]
	v_mfma_f32_16x16x32_bf16 v[92:95], v[120:123], v[176:179], v[92:95]
	v_mfma_f32_16x16x32_bf16 v[92:95], v[124:127], v[180:183], v[92:95]
	v_mfma_f32_16x16x32_bf16 v[88:91], v[128:131], v[176:179], v[88:91]
	v_mfma_f32_16x16x32_bf16 v[88:91], v[132:135], v[180:183], v[88:91]
	v_mfma_f32_16x16x32_bf16 v[76:79], v[120:123], v[184:187], v[76:79]
	v_mfma_f32_16x16x32_bf16 v[76:79], v[124:127], v[188:191], v[76:79]
	v_mfma_f32_16x16x32_bf16 v[72:75], v[128:131], v[184:187], v[72:75]
	v_mfma_f32_16x16x32_bf16 v[72:75], v[132:135], v[188:191], v[72:75]
	v_mfma_f32_16x16x32_bf16 v[116:119], v[144:147], v[160:163], v[116:119]
	v_mfma_f32_16x16x32_bf16 v[116:119], v[148:151], v[164:167], v[116:119]
	v_mfma_f32_16x16x32_bf16 v[112:115], v[152:155], v[160:163], v[112:115]
	v_mfma_f32_16x16x32_bf16 v[112:115], v[156:159], v[164:167], v[112:115]
	v_mfma_f32_16x16x32_bf16 v[100:103], v[144:147], v[168:171], v[100:103]
	v_mfma_f32_16x16x32_bf16 v[100:103], v[148:151], v[172:175], v[100:103]
	v_mfma_f32_16x16x32_bf16 v[96:99], v[152:155], v[168:171], v[96:99]
	v_mfma_f32_16x16x32_bf16 v[96:99], v[156:159], v[172:175], v[96:99]
	v_mfma_f32_16x16x32_bf16 v[84:87], v[144:147], v[176:179], v[84:87]
	v_mfma_f32_16x16x32_bf16 v[84:87], v[148:151], v[180:183], v[84:87]
	v_mfma_f32_16x16x32_bf16 v[80:83], v[152:155], v[176:179], v[80:83]
	v_mfma_f32_16x16x32_bf16 v[80:83], v[156:159], v[180:183], v[80:83]
	v_mfma_f32_16x16x32_bf16 v[68:71], v[144:147], v[184:187], v[68:71]
	v_mfma_f32_16x16x32_bf16 v[68:71], v[148:151], v[188:191], v[68:71]
	s_waitcnt vmcnt(8)
	s_setprio 3
	s_barrier
	v_mfma_f32_16x16x32_bf16 v[64:67], v[152:155], v[184:187], v[64:67]
	v_mfma_f32_16x16x32_bf16 v[64:67], v[156:159], v[188:191], v[64:67]
	s_setprio 0
	s_add_i32 s59, s59, s15
	v_lshl_add_u64 v[204:205], v[204:205], 0, s[46:47]
	s_mov_b32 m0, s59
	ds_read_b128 v[160:163], v247 offset:49152
	ds_read_b128 v[164:167], v247 offset:50176
	ds_read_b128 v[168:171], v247 offset:51200
	ds_read_b128 v[172:175], v247 offset:52224
	ds_read_b128 v[176:179], v247 offset:53248
	ds_read_b128 v[180:183], v247 offset:54272
	ds_read_b128 v[184:187], v247 offset:55296
	ds_read_b128 v[188:191], v247 offset:56320
	global_load_lds_dwordx4 v[204:205], off
	s_add_i32 m0, s59, 0x2000
	s_add_u32 s66, s84, 0x40080
	v_lshl_add_u64 v[204:205], v[206:207], 0, s[46:47]
	s_addc_u32 s67, s85, 0
	s_add_i32 s59, s68, s15
	global_load_lds_dwordx4 v[204:205], off
	s_mov_b32 m0, s59
	v_lshl_add_u64 v[204:205], s[66:67], 0, v[194:195]
	global_load_lds_dwordx4 v[204:205], off
	s_add_i32 m0, s59, 0x2000
	v_lshl_add_u64 v[204:205], s[66:67], 0, v[198:199]
	global_load_lds_dwordx4 v[204:205], off
	s_mov_b32 m0, s21
	v_lshl_add_u64 v[204:205], v[208:209], 0, s[46:47]
	global_load_lds_dwordx4 v[204:205], off
	s_mov_b32 m0, s22
	v_lshl_add_u64 v[204:205], v[210:211], 0, s[46:47]
	global_load_lds_dwordx4 v[204:205], off
	s_waitcnt lgkmcnt(0)
	s_barrier
	s_setprio 1
	v_mfma_f32_16x16x32_bf16 v[60:63], v[120:123], v[160:163], v[60:63]
	v_mfma_f32_16x16x32_bf16 v[60:63], v[124:127], v[164:167], v[60:63]
	v_mfma_f32_16x16x32_bf16 v[56:59], v[128:131], v[160:163], v[56:59]
	v_mfma_f32_16x16x32_bf16 v[56:59], v[132:135], v[164:167], v[56:59]
	v_mfma_f32_16x16x32_bf16 v[44:47], v[120:123], v[168:171], v[44:47]
	v_mfma_f32_16x16x32_bf16 v[44:47], v[124:127], v[172:175], v[44:47]
	v_mfma_f32_16x16x32_bf16 v[40:43], v[128:131], v[168:171], v[40:43]
	v_mfma_f32_16x16x32_bf16 v[40:43], v[132:135], v[172:175], v[40:43]
	v_mfma_f32_16x16x32_bf16 v[28:31], v[120:123], v[176:179], v[28:31]
	v_mfma_f32_16x16x32_bf16 v[28:31], v[124:127], v[180:183], v[28:31]
	v_mfma_f32_16x16x32_bf16 v[24:27], v[128:131], v[176:179], v[24:27]
	v_mfma_f32_16x16x32_bf16 v[24:27], v[132:135], v[180:183], v[24:27]
	v_mfma_f32_16x16x32_bf16 v[12:15], v[120:123], v[184:187], v[12:15]
	v_mfma_f32_16x16x32_bf16 v[12:15], v[124:127], v[188:191], v[12:15]
	v_mfma_f32_16x16x32_bf16 v[8:11], v[128:131], v[184:187], v[8:11]
	v_mfma_f32_16x16x32_bf16 v[8:11], v[132:135], v[188:191], v[8:11]
	v_mfma_f32_16x16x32_bf16 v[52:55], v[144:147], v[160:163], v[52:55]
	v_mfma_f32_16x16x32_bf16 v[52:55], v[148:151], v[164:167], v[52:55]
	v_mfma_f32_16x16x32_bf16 v[48:51], v[152:155], v[160:163], v[48:51]
	v_mfma_f32_16x16x32_bf16 v[48:51], v[156:159], v[164:167], v[48:51]
	v_mfma_f32_16x16x32_bf16 v[36:39], v[144:147], v[168:171], v[36:39]
	v_mfma_f32_16x16x32_bf16 v[36:39], v[148:151], v[172:175], v[36:39]
	v_mfma_f32_16x16x32_bf16 v[32:35], v[152:155], v[168:171], v[32:35]
	v_mfma_f32_16x16x32_bf16 v[32:35], v[156:159], v[172:175], v[32:35]
	v_mfma_f32_16x16x32_bf16 v[20:23], v[144:147], v[176:179], v[20:23]
	v_mfma_f32_16x16x32_bf16 v[20:23], v[148:151], v[180:183], v[20:23]
	v_mfma_f32_16x16x32_bf16 v[16:19], v[152:155], v[176:179], v[16:19]
	v_mfma_f32_16x16x32_bf16 v[16:19], v[156:159], v[180:183], v[16:19]
	v_mfma_f32_16x16x32_bf16 v[4:7], v[144:147], v[184:187], v[4:7]
	v_mfma_f32_16x16x32_bf16 v[4:7], v[148:151], v[188:191], v[4:7]
	s_waitcnt vmcnt(8)
	s_setprio 3
	s_barrier
	v_mfma_f32_16x16x32_bf16 v[0:3], v[152:155], v[184:187], v[0:3]
	v_mfma_f32_16x16x32_bf16 v[0:3], v[156:159], v[188:191], v[0:3]
	s_setprio 0
	s_add_i32 s58, s58, 2
	s_add_u32 s82, s82, 0x100
	s_addc_u32 s83, s83, 0
	s_add_u32 s56, s56, 0x100
	s_addc_u32 s57, s57, 0
	s_cmp_gt_u32 s58, 13
	s_cbranch_scc0 .Lka3_head
	s_branch .Lzskip_3

.LBB0_1147:
	s_ashr_i32 s49, s48, 31
	s_lshl_b64 s[50:51], s[48:49], 19
	s_add_u32 s50, s12, s50
	s_addc_u32 s51, s13, s51
	s_and_b64 s[52:53], s[4:5], exec
	s_cselect_b32 s49, s51, s79
	s_cselect_b32 s54, s50, s78
	s_ashr_i32 s47, s46, 31
	s_lshl_b64 s[52:53], s[46:47], 19
	s_add_u32 s52, s14, s52
	s_addc_u32 s53, s15, s53
	s_and_b64 s[58:59], s[4:5], exec
	s_cselect_b32 s47, s53, s81
	s_cselect_b32 s55, s52, s80
	s_add_u32 s78, s78, 0x40080
	s_addc_u32 s79, s79, 0
	s_add_u32 s58, s80, 0x100
	v_mov_b32_e32 v0, 0
	s_addc_u32 s59, s81, 0
	s_mov_b32 s66, -2
	s_waitcnt lgkmcnt(0)
	s_and_b64 s[100:101], exec, s[44:45]
	s_cbranch_scc1 .Lka4_head

.Lka4_head:
	ds_read_b128 v[146:149], v174
	ds_read_b128 v[150:153], v174 offset:1024
	ds_read_b128 v[154:157], v174 offset:2048
	ds_read_b128 v[158:161], v174 offset:3072
	ds_read_b128 v[162:165], v175
	ds_read_b128 v[178:181], v175 offset:1024
	ds_read_b128 v[182:185], v175 offset:2048
	ds_read_b128 v[186:189], v175 offset:3072
	s_add_u32 s67, s78, 0xfffc0080
	s_addc_u32 s68, s79, -1
	s_cmp_eq_u32 s66, 12
	s_cselect_b32 s83, s49, s68
	s_cselect_b32 s82, s54, s67
	s_cselect_b32 s81, s47, s59
	s_cselect_b32 s80, s55, s58
	v_lshl_add_u64 v[166:167], s[78:79], 0, v[136:137]
	s_add_i32 m0, s17, 0xc000
	ds_read_b128 v[190:193], v176
	ds_read_b128 v[194:197], v176 offset:1024
	ds_read_b128 v[198:201], v176 offset:2048
	ds_read_b128 v[202:205], v176 offset:3072
	ds_read_b128 v[206:209], v176 offset:4096
	ds_read_b128 v[210:213], v176 offset:5120
	ds_read_b128 v[214:217], v176 offset:6144
	ds_read_b128 v[218:221], v176 offset:7168
	global_load_lds_dwordx4 v[166:167], off
	s_add_i32 m0, s17, 0xe000
	v_lshl_add_u64 v[166:167], s[78:79], 0, v[140:141]
	global_load_lds_dwordx4 v[166:167], off
	s_cmp_eq_u32 s66, -2
	s_waitcnt lgkmcnt(0)
	s_barrier
	s_setprio 1
	s_cbranch_scc1 .Lkazv_4_0
	v_mfma_f32_16x16x32_bf16 v[124:127], v[146:149], v[190:193], v[124:127]
	v_mfma_f32_16x16x32_bf16 v[124:127], v[150:153], v[194:197], v[124:127]
	v_mfma_f32_16x16x32_bf16 v[116:119], v[154:157], v[190:193], v[116:119]
	v_mfma_f32_16x16x32_bf16 v[116:119], v[158:161], v[194:197], v[116:119]
	v_mfma_f32_16x16x32_bf16 v[108:111], v[146:149], v[198:201], v[108:111]
	v_mfma_f32_16x16x32_bf16 v[108:111], v[150:153], v[202:205], v[108:111]
	v_mfma_f32_16x16x32_bf16 v[100:103], v[154:157], v[198:201], v[100:103]
	v_mfma_f32_16x16x32_bf16 v[100:103], v[158:161], v[202:205], v[100:103]
	v_mfma_f32_16x16x32_bf16 v[92:95], v[146:149], v[206:209], v[92:95]
	v_mfma_f32_16x16x32_bf16 v[92:95], v[150:153], v[210:213], v[92:95]
	v_mfma_f32_16x16x32_bf16 v[84:87], v[154:157], v[206:209], v[84:87]
	v_mfma_f32_16x16x32_bf16 v[84:87], v[158:161], v[210:213], v[84:87]
	v_mfma_f32_16x16x32_bf16 v[76:79], v[146:149], v[214:217], v[76:79]
	v_mfma_f32_16x16x32_bf16 v[76:79], v[150:153], v[218:221], v[76:79]
	v_mfma_f32_16x16x32_bf16 v[68:71], v[154:157], v[214:217], v[68:71]
	v_mfma_f32_16x16x32_bf16 v[68:71], v[158:161], v[218:221], v[68:71]
	v_mfma_f32_16x16x32_bf16 v[120:123], v[162:165], v[190:193], v[120:123]
	v_mfma_f32_16x16x32_bf16 v[120:123], v[178:181], v[194:197], v[120:123]
	v_mfma_f32_16x16x32_bf16 v[112:115], v[182:185], v[190:193], v[112:115]
	v_mfma_f32_16x16x32_bf16 v[112:115], v[186:189], v[194:197], v[112:115]
	v_mfma_f32_16x16x32_bf16 v[104:107], v[162:165], v[198:201], v[104:107]
	v_mfma_f32_16x16x32_bf16 v[104:107], v[178:181], v[202:205], v[104:107]
	v_mfma_f32_16x16x32_bf16 v[96:99], v[182:185], v[198:201], v[96:99]
	v_mfma_f32_16x16x32_bf16 v[96:99], v[186:189], v[202:205], v[96:99]
	v_mfma_f32_16x16x32_bf16 v[88:91], v[162:165], v[206:209], v[88:91]
	v_mfma_f32_16x16x32_bf16 v[88:91], v[178:181], v[210:213], v[88:91]
	v_mfma_f32_16x16x32_bf16 v[80:83], v[182:185], v[206:209], v[80:83]
	v_mfma_f32_16x16x32_bf16 v[80:83], v[186:189], v[210:213], v[80:83]
	v_mfma_f32_16x16x32_bf16 v[72:75], v[162:165], v[214:217], v[72:75]
	v_mfma_f32_16x16x32_bf16 v[72:75], v[178:181], v[218:221], v[72:75]
	s_waitcnt vmcnt(8)
	s_setprio 3
	s_barrier
	v_mfma_f32_16x16x32_bf16 v[64:67], v[182:185], v[214:217], v[64:67]
	v_mfma_f32_16x16x32_bf16 v[64:67], v[186:189], v[218:221], v[64:67]
	s_setprio 0
.Lkazj_4_0:
	s_add_i32 s67, s25, s16
	v_lshl_add_u64 v[166:167], s[80:81], 0, v[132:133]
	s_mov_b32 m0, s67
	ds_read_b128 v[190:193], v176 offset:16384
	ds_read_b128 v[194:197], v176 offset:17408
	ds_read_b128 v[198:201], v176 offset:18432
	ds_read_b128 v[202:205], v176 offset:19456
	ds_read_b128 v[206:209], v176 offset:20480
	ds_read_b128 v[210:213], v176 offset:21504
	ds_read_b128 v[214:217], v176 offset:22528
	ds_read_b128 v[218:221], v176 offset:23552
	global_load_lds_dwordx4 v[166:167], off
	s_add_i32 m0, s67, 0x2000
	s_add_u32 s68, s80, 0x40000
	v_lshl_add_u64 v[222:223], s[80:81], 0, v[128:129]
	s_addc_u32 s69, s81, 0
	s_add_i32 s67, s26, s16
	global_load_lds_dwordx4 v[222:223], off
	v_lshl_add_u64 v[224:225], s[68:69], 0, v[132:133]
	s_mov_b32 m0, s67
	global_load_lds_dwordx4 v[224:225], off
	s_add_i32 m0, s67, 0x2000
	v_lshl_add_u64 v[224:225], s[68:69], 0, v[128:129]
	global_load_lds_dwordx4 v[224:225], off
	s_mov_b32 m0, s17
	v_lshl_add_u64 v[224:225], s[82:83], 0, v[134:135]
	global_load_lds_dwordx4 v[224:225], off
	s_mov_b32 m0, s18
	v_lshl_add_u64 v[226:227], s[82:83], 0, v[130:131]
	global_load_lds_dwordx4 v[226:227], off
	s_cmp_eq_u32 s66, -2
	s_waitcnt lgkmcnt(0)
	s_barrier
	s_setprio 1
	s_cbranch_scc1 .Lkazv_4_1
	v_mfma_f32_16x16x32_bf16 v[60:63], v[146:149], v[190:193], v[60:63]
	v_mfma_f32_16x16x32_bf16 v[60:63], v[150:153], v[194:197], v[60:63]
	v_mfma_f32_16x16x32_bf16 v[52:55], v[154:157], v[190:193], v[52:55]
	v_mfma_f32_16x16x32_bf16 v[52:55], v[158:161], v[194:197], v[52:55]
	v_mfma_f32_16x16x32_bf16 v[44:47], v[146:149], v[198:201], v[44:47]
	v_mfma_f32_16x16x32_bf16 v[44:47], v[150:153], v[202:205], v[44:47]
	v_mfma_f32_16x16x32_bf16 v[36:39], v[154:157], v[198:201], v[36:39]
	v_mfma_f32_16x16x32_bf16 v[36:39], v[158:161], v[202:205], v[36:39]
	v_mfma_f32_16x16x32_bf16 v[28:31], v[146:149], v[206:209], v[28:31]
	v_mfma_f32_16x16x32_bf16 v[28:31], v[150:153], v[210:213], v[28:31]
	v_mfma_f32_16x16x32_bf16 v[20:23], v[154:157], v[206:209], v[20:23]
	v_mfma_f32_16x16x32_bf16 v[20:23], v[158:161], v[210:213], v[20:23]
	v_mfma_f32_16x16x32_bf16 v[12:15], v[146:149], v[214:217], v[12:15]
	v_mfma_f32_16x16x32_bf16 v[12:15], v[150:153], v[218:221], v[12:15]
	v_mfma_f32_16x16x32_bf16 v[4:7], v[154:157], v[214:217], v[4:7]
	v_mfma_f32_16x16x32_bf16 v[4:7], v[158:161], v[218:221], v[4:7]
	v_mfma_f32_16x16x32_bf16 v[56:59], v[162:165], v[190:193], v[56:59]
	v_mfma_f32_16x16x32_bf16 v[56:59], v[178:181], v[194:197], v[56:59]
	v_mfma_f32_16x16x32_bf16 v[48:51], v[182:185], v[190:193], v[48:51]
	v_mfma_f32_16x16x32_bf16 v[48:51], v[186:189], v[194:197], v[48:51]
	v_mfma_f32_16x16x32_bf16 v[40:43], v[162:165], v[198:201], v[40:43]
	v_mfma_f32_16x16x32_bf16 v[40:43], v[178:181], v[202:205], v[40:43]
	v_mfma_f32_16x16x32_bf16 v[32:35], v[182:185], v[198:201], v[32:35]
	v_mfma_f32_16x16x32_bf16 v[32:35], v[186:189], v[202:205], v[32:35]
	v_mfma_f32_16x16x32_bf16 v[24:27], v[162:165], v[206:209], v[24:27]
	v_mfma_f32_16x16x32_bf16 v[24:27], v[178:181], v[210:213], v[24:27]
	v_mfma_f32_16x16x32_bf16 v[16:19], v[182:185], v[206:209], v[16:19]
	v_mfma_f32_16x16x32_bf16 v[16:19], v[186:189], v[210:213], v[16:19]
	v_mfma_f32_16x16x32_bf16 v[8:11], v[162:165], v[214:217], v[8:11]
	v_mfma_f32_16x16x32_bf16 v[8:11], v[178:181], v[218:221], v[8:11]
	s_waitcnt vmcnt(8)
	s_setprio 3
	s_barrier
	v_mfma_f32_16x16x32_bf16 v[0:3], v[182:185], v[214:217], v[0:3]
	v_mfma_f32_16x16x32_bf16 v[0:3], v[186:189], v[218:221], v[0:3]
	s_setprio 0
.Lkazj_4_1:
	s_add_i32 s67, 0, 0x18000
	s_add_i32 s73, 0, 0x1c000
	v_add_u32_e32 v158, s67, v171
	v_add_u32_e32 v186, s73, v171
	ds_read_b128 v[146:149], v158
	ds_read_b128 v[150:153], v158 offset:1024
	ds_read_b128 v[154:157], v158 offset:2048
	ds_read_b128 v[158:161], v158 offset:3072
	ds_read_b128 v[162:165], v186
	ds_read_b128 v[178:181], v186 offset:1024
	ds_read_b128 v[182:185], v186 offset:2048
	ds_read_b128 v[186:189], v186 offset:3072
	s_add_u32 s68, s82, 0x40000
	s_addc_u32 s69, s83, 0
	s_mov_b32 m0, s19
	v_lshl_add_u64 v[228:229], s[68:69], 0, v[134:135]
	ds_read_b128 v[190:193], v176 offset:32768
	ds_read_b128 v[194:197], v176 offset:33792
	ds_read_b128 v[198:201], v176 offset:34816
	ds_read_b128 v[202:205], v176 offset:35840
	ds_read_b128 v[206:209], v176 offset:36864
	ds_read_b128 v[210:213], v176 offset:37888
	ds_read_b128 v[214:217], v176 offset:38912
	ds_read_b128 v[218:221], v176 offset:39936
	global_load_lds_dwordx4 v[228:229], off
	s_mov_b32 m0, s20
	v_lshl_add_u64 v[228:229], s[68:69], 0, v[130:131]
	global_load_lds_dwordx4 v[228:229], off
	s_waitcnt lgkmcnt(0)
	s_barrier
	s_setprio 1
	v_mfma_f32_16x16x32_bf16 v[124:127], v[146:149], v[190:193], v[124:127]
	v_mfma_f32_16x16x32_bf16 v[124:127], v[150:153], v[194:197], v[124:127]
	v_mfma_f32_16x16x32_bf16 v[116:119], v[154:157], v[190:193], v[116:119]
	v_mfma_f32_16x16x32_bf16 v[116:119], v[158:161], v[194:197], v[116:119]
	v_mfma_f32_16x16x32_bf16 v[108:111], v[146:149], v[198:201], v[108:111]
	v_mfma_f32_16x16x32_bf16 v[108:111], v[150:153], v[202:205], v[108:111]
	v_mfma_f32_16x16x32_bf16 v[100:103], v[154:157], v[198:201], v[100:103]
	v_mfma_f32_16x16x32_bf16 v[100:103], v[158:161], v[202:205], v[100:103]
	v_mfma_f32_16x16x32_bf16 v[92:95], v[146:149], v[206:209], v[92:95]
	v_mfma_f32_16x16x32_bf16 v[92:95], v[150:153], v[210:213], v[92:95]
	v_mfma_f32_16x16x32_bf16 v[84:87], v[154:157], v[206:209], v[84:87]
	v_mfma_f32_16x16x32_bf16 v[84:87], v[158:161], v[210:213], v[84:87]
	v_mfma_f32_16x16x32_bf16 v[76:79], v[146:149], v[214:217], v[76:79]
	v_mfma_f32_16x16x32_bf16 v[76:79], v[150:153], v[218:221], v[76:79]
	v_mfma_f32_16x16x32_bf16 v[68:71], v[154:157], v[214:217], v[68:71]
	v_mfma_f32_16x16x32_bf16 v[68:71], v[158:161], v[218:221], v[68:71]
	v_mfma_f32_16x16x32_bf16 v[120:123], v[162:165], v[190:193], v[120:123]
	v_mfma_f32_16x16x32_bf16 v[120:123], v[178:181], v[194:197], v[120:123]
	v_mfma_f32_16x16x32_bf16 v[112:115], v[182:185], v[190:193], v[112:115]
	v_mfma_f32_16x16x32_bf16 v[112:115], v[186:189], v[194:197], v[112:115]
	v_mfma_f32_16x16x32_bf16 v[104:107], v[162:165], v[198:201], v[104:107]
	v_mfma_f32_16x16x32_bf16 v[104:107], v[178:181], v[202:205], v[104:107]
	v_mfma_f32_16x16x32_bf16 v[96:99], v[182:185], v[198:201], v[96:99]
	v_mfma_f32_16x16x32_bf16 v[96:99], v[186:189], v[202:205], v[96:99]
	v_mfma_f32_16x16x32_bf16 v[88:91], v[162:165], v[206:209], v[88:91]
	v_mfma_f32_16x16x32_bf16 v[88:91], v[178:181], v[210:213], v[88:91]
	v_mfma_f32_16x16x32_bf16 v[80:83], v[182:185], v[206:209], v[80:83]
	v_mfma_f32_16x16x32_bf16 v[80:83], v[186:189], v[210:213], v[80:83]
	v_mfma_f32_16x16x32_bf16 v[72:75], v[162:165], v[214:217], v[72:75]
	v_mfma_f32_16x16x32_bf16 v[72:75], v[178:181], v[218:221], v[72:75]
	s_waitcnt vmcnt(8)
	s_setprio 3
	s_barrier
	v_mfma_f32_16x16x32_bf16 v[64:67], v[182:185], v[214:217], v[64:67]
	v_mfma_f32_16x16x32_bf16 v[64:67], v[186:189], v[218:221], v[64:67]
	s_setprio 0
	s_add_i32 s67, s67, s16
	v_lshl_add_u64 v[166:167], v[166:167], 0, s[10:11]
	s_mov_b32 m0, s67
	ds_read_b128 v[190:193], v176 offset:49152
	ds_read_b128 v[194:197], v176 offset:50176
	ds_read_b128 v[198:201], v176 offset:51200
	ds_read_b128 v[202:205], v176 offset:52224
	ds_read_b128 v[206:209], v176 offset:53248
	ds_read_b128 v[210:213], v176 offset:54272
	ds_read_b128 v[214:217], v176 offset:55296
	ds_read_b128 v[218:221], v176 offset:56320
	global_load_lds_dwordx4 v[166:167], off
	s_add_i32 m0, s67, 0x2000
	s_add_u32 s68, s80, 0x40080
	v_lshl_add_u64 v[166:167], v[222:223], 0, s[10:11]
	s_addc_u32 s69, s81, 0
	s_add_i32 s67, s73, s16
	global_load_lds_dwordx4 v[166:167], off
	s_mov_b32 m0, s67
	v_lshl_add_u64 v[166:167], s[68:69], 0, v[132:133]
	global_load_lds_dwordx4 v[166:167], off
	s_add_i32 m0, s67, 0x2000
	v_lshl_add_u64 v[166:167], s[68:69], 0, v[128:129]
	global_load_lds_dwordx4 v[166:167], off
	s_mov_b32 m0, s23
	v_lshl_add_u64 v[166:167], v[224:225], 0, s[10:11]
	global_load_lds_dwordx4 v[166:167], off
	s_mov_b32 m0, s24
	v_lshl_add_u64 v[166:167], v[226:227], 0, s[10:11]
	global_load_lds_dwordx4 v[166:167], off
	s_waitcnt lgkmcnt(0)
	s_barrier
	s_setprio 1
	v_mfma_f32_16x16x32_bf16 v[60:63], v[146:149], v[190:193], v[60:63]
	v_mfma_f32_16x16x32_bf16 v[60:63], v[150:153], v[194:197], v[60:63]
	v_mfma_f32_16x16x32_bf16 v[52:55], v[154:157], v[190:193], v[52:55]
	v_mfma_f32_16x16x32_bf16 v[52:55], v[158:161], v[194:197], v[52:55]
	v_mfma_f32_16x16x32_bf16 v[44:47], v[146:149], v[198:201], v[44:47]
	v_mfma_f32_16x16x32_bf16 v[44:47], v[150:153], v[202:205], v[44:47]
	v_mfma_f32_16x16x32_bf16 v[36:39], v[154:157], v[198:201], v[36:39]
	v_mfma_f32_16x16x32_bf16 v[36:39], v[158:161], v[202:205], v[36:39]
	v_mfma_f32_16x16x32_bf16 v[28:31], v[146:149], v[206:209], v[28:31]
	v_mfma_f32_16x16x32_bf16 v[28:31], v[150:153], v[210:213], v[28:31]
	v_mfma_f32_16x16x32_bf16 v[20:23], v[154:157], v[206:209], v[20:23]
	v_mfma_f32_16x16x32_bf16 v[20:23], v[158:161], v[210:213], v[20:23]
	v_mfma_f32_16x16x32_bf16 v[12:15], v[146:149], v[214:217], v[12:15]
	v_mfma_f32_16x16x32_bf16 v[12:15], v[150:153], v[218:221], v[12:15]
	v_mfma_f32_16x16x32_bf16 v[4:7], v[154:157], v[214:217], v[4:7]
	v_mfma_f32_16x16x32_bf16 v[4:7], v[158:161], v[218:221], v[4:7]
	v_mfma_f32_16x16x32_bf16 v[56:59], v[162:165], v[190:193], v[56:59]
	v_mfma_f32_16x16x32_bf16 v[56:59], v[178:181], v[194:197], v[56:59]
	v_mfma_f32_16x16x32_bf16 v[48:51], v[182:185], v[190:193], v[48:51]
	v_mfma_f32_16x16x32_bf16 v[48:51], v[186:189], v[194:197], v[48:51]
	v_mfma_f32_16x16x32_bf16 v[40:43], v[162:165], v[198:201], v[40:43]
	v_mfma_f32_16x16x32_bf16 v[40:43], v[178:181], v[202:205], v[40:43]
	v_mfma_f32_16x16x32_bf16 v[32:35], v[182:185], v[198:201], v[32:35]
	v_mfma_f32_16x16x32_bf16 v[32:35], v[186:189], v[202:205], v[32:35]
	v_mfma_f32_16x16x32_bf16 v[24:27], v[162:165], v[206:209], v[24:27]
	v_mfma_f32_16x16x32_bf16 v[24:27], v[178:181], v[210:213], v[24:27]
	v_mfma_f32_16x16x32_bf16 v[16:19], v[182:185], v[206:209], v[16:19]
	v_mfma_f32_16x16x32_bf16 v[16:19], v[186:189], v[210:213], v[16:19]
	v_mfma_f32_16x16x32_bf16 v[8:11], v[162:165], v[214:217], v[8:11]
	v_mfma_f32_16x16x32_bf16 v[8:11], v[178:181], v[218:221], v[8:11]
	s_waitcnt vmcnt(8)
	s_setprio 3
	s_barrier
	v_mfma_f32_16x16x32_bf16 v[0:3], v[182:185], v[214:217], v[0:3]
	v_mfma_f32_16x16x32_bf16 v[0:3], v[186:189], v[218:221], v[0:3]
	s_setprio 0
	s_add_i32 s66, s66, 2
	s_add_u32 s78, s78, 0x100
	s_addc_u32 s79, s79, 0
	s_add_u32 s58, s58, 0x100
	s_addc_u32 s59, s59, 0
	s_cmp_gt_u32 s66, 13
	s_cbranch_scc0 .Lka4_head
	s_branch .Lzskip_4
.Lkazv_4_0:
	v_mfma_f32_16x16x32_bf16 v[124:127], v[146:149], v[190:193], 0
	v_mfma_f32_16x16x32_bf16 v[124:127], v[150:153], v[194:197], v[124:127]
	v_mfma_f32_16x16x32_bf16 v[116:119], v[154:157], v[190:193], 0
	v_mfma_f32_16x16x32_bf16 v[116:119], v[158:161], v[194:197], v[116:119]
	v_mfma_f32_16x16x32_bf16 v[108:111], v[146:149], v[198:201], 0
	v_mfma_f32_16x16x32_bf16 v[108:111], v[150:153], v[202:205], v[108:111]
	v_mfma_f32_16x16x32_bf16 v[100:103], v[154:157], v[198:201], 0
	v_mfma_f32_16x16x32_bf16 v[100:103], v[158:161], v[202:205], v[100:103]
	v_mfma_f32_16x16x32_bf16 v[92:95], v[146:149], v[206:209], 0
	v_mfma_f32_16x16x32_bf16 v[92:95], v[150:153], v[210:213], v[92:95]
	v_mfma_f32_16x16x32_bf16 v[84:87], v[154:157], v[206:209], 0
	v_mfma_f32_16x16x32_bf16 v[84:87], v[158:161], v[210:213], v[84:87]
	v_mfma_f32_16x16x32_bf16 v[76:79], v[146:149], v[214:217], 0
	v_mfma_f32_16x16x32_bf16 v[76:79], v[150:153], v[218:221], v[76:79]
	v_mfma_f32_16x16x32_bf16 v[68:71], v[154:157], v[214:217], 0
	v_mfma_f32_16x16x32_bf16 v[68:71], v[158:161], v[218:221], v[68:71]
	v_mfma_f32_16x16x32_bf16 v[120:123], v[162:165], v[190:193], 0
	v_mfma_f32_16x16x32_bf16 v[120:123], v[178:181], v[194:197], v[120:123]
	v_mfma_f32_16x16x32_bf16 v[112:115], v[182:185], v[190:193], 0
	v_mfma_f32_16x16x32_bf16 v[112:115], v[186:189], v[194:197], v[112:115]
	v_mfma_f32_16x16x32_bf16 v[104:107], v[162:165], v[198:201], 0
	v_mfma_f32_16x16x32_bf16 v[104:107], v[178:181], v[202:205], v[104:107]
	v_mfma_f32_16x16x32_bf16 v[96:99], v[182:185], v[198:201], 0
	v_mfma_f32_16x16x32_bf16 v[96:99], v[186:189], v[202:205], v[96:99]
	v_mfma_f32_16x16x32_bf16 v[88:91], v[162:165], v[206:209], 0
	v_mfma_f32_16x16x32_bf16 v[88:91], v[178:181], v[210:213], v[88:91]
	v_mfma_f32_16x16x32_bf16 v[80:83], v[182:185], v[206:209], 0
	v_mfma_f32_16x16x32_bf16 v[80:83], v[186:189], v[210:213], v[80:83]
	v_mfma_f32_16x16x32_bf16 v[72:75], v[162:165], v[214:217], 0
	v_mfma_f32_16x16x32_bf16 v[72:75], v[178:181], v[218:221], v[72:75]
	s_waitcnt vmcnt(8)
	s_setprio 3
	s_barrier
	v_mfma_f32_16x16x32_bf16 v[64:67], v[182:185], v[214:217], 0
	v_mfma_f32_16x16x32_bf16 v[64:67], v[186:189], v[218:221], v[64:67]
	s_setprio 0
	s_branch .Lkazj_4_0
.Lkazv_4_1:
	v_mfma_f32_16x16x32_bf16 v[60:63], v[146:149], v[190:193], 0
	v_mfma_f32_16x16x32_bf16 v[60:63], v[150:153], v[194:197], v[60:63]
	v_mfma_f32_16x16x32_bf16 v[52:55], v[154:157], v[190:193], 0
	v_mfma_f32_16x16x32_bf16 v[52:55], v[158:161], v[194:197], v[52:55]
	v_mfma_f32_16x16x32_bf16 v[44:47], v[146:149], v[198:201], 0
	v_mfma_f32_16x16x32_bf16 v[44:47], v[150:153], v[202:205], v[44:47]
	v_mfma_f32_16x16x32_bf16 v[36:39], v[154:157], v[198:201], 0
	v_mfma_f32_16x16x32_bf16 v[36:39], v[158:161], v[202:205], v[36:39]
	v_mfma_f32_16x16x32_bf16 v[28:31], v[146:149], v[206:209], 0
	v_mfma_f32_16x16x32_bf16 v[28:31], v[150:153], v[210:213], v[28:31]
	v_mfma_f32_16x16x32_bf16 v[20:23], v[154:157], v[206:209], 0
	v_mfma_f32_16x16x32_bf16 v[20:23], v[158:161], v[210:213], v[20:23]
	v_mfma_f32_16x16x32_bf16 v[12:15], v[146:149], v[214:217], 0
	v_mfma_f32_16x16x32_bf16 v[12:15], v[150:153], v[218:221], v[12:15]
	v_mfma_f32_16x16x32_bf16 v[4:7], v[154:157], v[214:217], 0
	v_mfma_f32_16x16x32_bf16 v[4:7], v[158:161], v[218:221], v[4:7]
	v_mfma_f32_16x16x32_bf16 v[56:59], v[162:165], v[190:193], 0
	v_mfma_f32_16x16x32_bf16 v[56:59], v[178:181], v[194:197], v[56:59]
	v_mfma_f32_16x16x32_bf16 v[48:51], v[182:185], v[190:193], 0
	v_mfma_f32_16x16x32_bf16 v[48:51], v[186:189], v[194:197], v[48:51]
	v_mfma_f32_16x16x32_bf16 v[40:43], v[162:165], v[198:201], 0
	v_mfma_f32_16x16x32_bf16 v[40:43], v[178:181], v[202:205], v[40:43]
	v_mfma_f32_16x16x32_bf16 v[32:35], v[182:185], v[198:201], 0
	v_mfma_f32_16x16x32_bf16 v[32:35], v[186:189], v[202:205], v[32:35]
	v_mfma_f32_16x16x32_bf16 v[24:27], v[162:165], v[206:209], 0
	v_mfma_f32_16x16x32_bf16 v[24:27], v[178:181], v[210:213], v[24:27]
	v_mfma_f32_16x16x32_bf16 v[16:19], v[182:185], v[206:209], 0
	v_mfma_f32_16x16x32_bf16 v[16:19], v[186:189], v[210:213], v[16:19]
	v_mfma_f32_16x16x32_bf16 v[8:11], v[162:165], v[214:217], 0
	v_mfma_f32_16x16x32_bf16 v[8:11], v[178:181], v[218:221], v[8:11]
	s_waitcnt vmcnt(8)
	s_setprio 3
	s_barrier
	v_mfma_f32_16x16x32_bf16 v[0:3], v[182:185], v[214:217], 0
	v_mfma_f32_16x16x32_bf16 v[0:3], v[186:189], v[218:221], v[0:3]
	s_setprio 0
	s_branch .Lkazj_4_1
	s_branch .Lzskip_4

.LBB0_1298:
	s_add_u32 s76, s76, 0xb0080
	s_addc_u32 s77, s77, 0
	s_add_u32 s55, s78, 0x100
	v_mov_b32_e32 v0, 0
	s_addc_u32 s58, s79, 0
	s_mov_b32 s59, -2
	s_and_b64 s[100:101], exec, s[50:51]
	s_cbranch_scc1 .Lka5_head

.Lka5_head:
	ds_read_b128 v[120:123], v245
	ds_read_b128 v[124:127], v245 offset:1024
	ds_read_b128 v[128:131], v245 offset:2048
	ds_read_b128 v[132:135], v245 offset:3072
	ds_read_b128 v[144:147], v246
	ds_read_b128 v[148:151], v246 offset:1024
	ds_read_b128 v[152:155], v246 offset:2048
	ds_read_b128 v[156:159], v246 offset:3072
	s_add_u32 s66, s76, 0xfff50080
	s_addc_u32 s67, s77, -1
	s_cmp_eq_u32 s59, 40
	s_cselect_b32 s81, s9, s67
	s_cselect_b32 s80, s8, s66
	s_cselect_b32 s79, s53, s58
	s_cselect_b32 s78, s52, s55
	v_lshl_add_u64 v[204:205], s[76:77], 0, v[200:201]
	s_add_i32 m0, s16, 0xc000
	ds_read_b128 v[160:163], v247
	ds_read_b128 v[164:167], v247 offset:1024
	ds_read_b128 v[168:171], v247 offset:2048
	ds_read_b128 v[172:175], v247 offset:3072
	ds_read_b128 v[176:179], v247 offset:4096
	ds_read_b128 v[180:183], v247 offset:5120
	ds_read_b128 v[184:187], v247 offset:6144
	ds_read_b128 v[188:191], v247 offset:7168
	global_load_lds_dwordx4 v[204:205], off
	s_add_i32 m0, s16, 0xe000
	v_lshl_add_u64 v[204:205], s[76:77], 0, v[202:203]
	global_load_lds_dwordx4 v[204:205], off
	s_cmp_eq_u32 s59, -2
	s_waitcnt lgkmcnt(0)
	s_barrier
	s_setprio 1
	s_cbranch_scc1 .Lkazv_5_0
	v_mfma_f32_16x16x32_bf16 v[140:143], v[120:123], v[160:163], v[140:143]
	v_mfma_f32_16x16x32_bf16 v[140:143], v[124:127], v[164:167], v[140:143]
	v_mfma_f32_16x16x32_bf16 v[136:139], v[128:131], v[160:163], v[136:139]
	v_mfma_f32_16x16x32_bf16 v[136:139], v[132:135], v[164:167], v[136:139]
	v_mfma_f32_16x16x32_bf16 v[108:111], v[120:123], v[168:171], v[108:111]
	v_mfma_f32_16x16x32_bf16 v[108:111], v[124:127], v[172:175], v[108:111]
	v_mfma_f32_16x16x32_bf16 v[104:107], v[128:131], v[168:171], v[104:107]
	v_mfma_f32_16x16x32_bf16 v[104:107], v[132:135], v[172:175], v[104:107]
	v_mfma_f32_16x16x32_bf16 v[92:95], v[120:123], v[176:179], v[92:95]
	v_mfma_f32_16x16x32_bf16 v[92:95], v[124:127], v[180:183], v[92:95]
	v_mfma_f32_16x16x32_bf16 v[88:91], v[128:131], v[176:179], v[88:91]
	v_mfma_f32_16x16x32_bf16 v[88:91], v[132:135], v[180:183], v[88:91]
	v_mfma_f32_16x16x32_bf16 v[76:79], v[120:123], v[184:187], v[76:79]
	v_mfma_f32_16x16x32_bf16 v[76:79], v[124:127], v[188:191], v[76:79]
	v_mfma_f32_16x16x32_bf16 v[72:75], v[128:131], v[184:187], v[72:75]
	v_mfma_f32_16x16x32_bf16 v[72:75], v[132:135], v[188:191], v[72:75]
	v_mfma_f32_16x16x32_bf16 v[116:119], v[144:147], v[160:163], v[116:119]
	v_mfma_f32_16x16x32_bf16 v[116:119], v[148:151], v[164:167], v[116:119]
	v_mfma_f32_16x16x32_bf16 v[112:115], v[152:155], v[160:163], v[112:115]
	v_mfma_f32_16x16x32_bf16 v[112:115], v[156:159], v[164:167], v[112:115]
	v_mfma_f32_16x16x32_bf16 v[100:103], v[144:147], v[168:171], v[100:103]
	v_mfma_f32_16x16x32_bf16 v[100:103], v[148:151], v[172:175], v[100:103]
	v_mfma_f32_16x16x32_bf16 v[96:99], v[152:155], v[168:171], v[96:99]
	v_mfma_f32_16x16x32_bf16 v[96:99], v[156:159], v[172:175], v[96:99]
	v_mfma_f32_16x16x32_bf16 v[84:87], v[144:147], v[176:179], v[84:87]
	v_mfma_f32_16x16x32_bf16 v[84:87], v[148:151], v[180:183], v[84:87]
	v_mfma_f32_16x16x32_bf16 v[80:83], v[152:155], v[176:179], v[80:83]
	v_mfma_f32_16x16x32_bf16 v[80:83], v[156:159], v[180:183], v[80:83]
	v_mfma_f32_16x16x32_bf16 v[68:71], v[144:147], v[184:187], v[68:71]
	v_mfma_f32_16x16x32_bf16 v[68:71], v[148:151], v[188:191], v[68:71]
	s_waitcnt vmcnt(8)
	s_setprio 3
	s_barrier
	v_mfma_f32_16x16x32_bf16 v[64:67], v[152:155], v[184:187], v[64:67]
	v_mfma_f32_16x16x32_bf16 v[64:67], v[156:159], v[188:191], v[64:67]
	s_setprio 0
.Lkazj_5_0:
	s_add_i32 s66, s26, s15
	v_lshl_add_u64 v[204:205], s[78:79], 0, v[194:195]
	s_mov_b32 m0, s66
	ds_read_b128 v[160:163], v247 offset:16384
	ds_read_b128 v[164:167], v247 offset:17408
	ds_read_b128 v[168:171], v247 offset:18432
	ds_read_b128 v[172:175], v247 offset:19456
	ds_read_b128 v[176:179], v247 offset:20480
	ds_read_b128 v[180:183], v247 offset:21504
	ds_read_b128 v[184:187], v247 offset:22528
	ds_read_b128 v[188:191], v247 offset:23552
	global_load_lds_dwordx4 v[204:205], off
	s_add_i32 m0, s66, 0x2000
	s_add_u32 s66, s78, 0xb0000
	v_lshl_add_u64 v[206:207], s[78:79], 0, v[198:199]
	s_addc_u32 s67, s79, 0
	s_add_i32 s68, s27, s15
	global_load_lds_dwordx4 v[206:207], off
	v_lshl_add_u64 v[208:209], s[66:67], 0, v[194:195]
	s_mov_b32 m0, s68
	global_load_lds_dwordx4 v[208:209], off
	s_add_i32 m0, s68, 0x2000
	v_lshl_add_u64 v[208:209], s[66:67], 0, v[198:199]
	global_load_lds_dwordx4 v[208:209], off
	s_mov_b32 m0, s16
	v_lshl_add_u64 v[208:209], s[80:81], 0, v[192:193]
	global_load_lds_dwordx4 v[208:209], off
	s_mov_b32 m0, s17
	v_lshl_add_u64 v[210:211], s[80:81], 0, v[196:197]
	global_load_lds_dwordx4 v[210:211], off
	s_cmp_eq_u32 s59, -2
	s_waitcnt lgkmcnt(0)
	s_barrier
	s_setprio 1
	s_cbranch_scc1 .Lkazv_5_1
	v_mfma_f32_16x16x32_bf16 v[60:63], v[120:123], v[160:163], v[60:63]
	v_mfma_f32_16x16x32_bf16 v[60:63], v[124:127], v[164:167], v[60:63]
	v_mfma_f32_16x16x32_bf16 v[56:59], v[128:131], v[160:163], v[56:59]
	v_mfma_f32_16x16x32_bf16 v[56:59], v[132:135], v[164:167], v[56:59]
	v_mfma_f32_16x16x32_bf16 v[44:47], v[120:123], v[168:171], v[44:47]
	v_mfma_f32_16x16x32_bf16 v[44:47], v[124:127], v[172:175], v[44:47]
	v_mfma_f32_16x16x32_bf16 v[40:43], v[128:131], v[168:171], v[40:43]
	v_mfma_f32_16x16x32_bf16 v[40:43], v[132:135], v[172:175], v[40:43]
	v_mfma_f32_16x16x32_bf16 v[28:31], v[120:123], v[176:179], v[28:31]
	v_mfma_f32_16x16x32_bf16 v[28:31], v[124:127], v[180:183], v[28:31]
	v_mfma_f32_16x16x32_bf16 v[24:27], v[128:131], v[176:179], v[24:27]
	v_mfma_f32_16x16x32_bf16 v[24:27], v[132:135], v[180:183], v[24:27]
	v_mfma_f32_16x16x32_bf16 v[12:15], v[120:123], v[184:187], v[12:15]
	v_mfma_f32_16x16x32_bf16 v[12:15], v[124:127], v[188:191], v[12:15]
	v_mfma_f32_16x16x32_bf16 v[8:11], v[128:131], v[184:187], v[8:11]
	v_mfma_f32_16x16x32_bf16 v[8:11], v[132:135], v[188:191], v[8:11]
	v_mfma_f32_16x16x32_bf16 v[52:55], v[144:147], v[160:163], v[52:55]
	v_mfma_f32_16x16x32_bf16 v[52:55], v[148:151], v[164:167], v[52:55]
	v_mfma_f32_16x16x32_bf16 v[48:51], v[152:155], v[160:163], v[48:51]
	v_mfma_f32_16x16x32_bf16 v[48:51], v[156:159], v[164:167], v[48:51]
	v_mfma_f32_16x16x32_bf16 v[36:39], v[144:147], v[168:171], v[36:39]
	v_mfma_f32_16x16x32_bf16 v[36:39], v[148:151], v[172:175], v[36:39]
	v_mfma_f32_16x16x32_bf16 v[32:35], v[152:155], v[168:171], v[32:35]
	v_mfma_f32_16x16x32_bf16 v[32:35], v[156:159], v[172:175], v[32:35]
	v_mfma_f32_16x16x32_bf16 v[20:23], v[144:147], v[176:179], v[20:23]
	v_mfma_f32_16x16x32_bf16 v[20:23], v[148:151], v[180:183], v[20:23]
	v_mfma_f32_16x16x32_bf16 v[16:19], v[152:155], v[176:179], v[16:19]
	v_mfma_f32_16x16x32_bf16 v[16:19], v[156:159], v[180:183], v[16:19]
	v_mfma_f32_16x16x32_bf16 v[4:7], v[144:147], v[184:187], v[4:7]
	v_mfma_f32_16x16x32_bf16 v[4:7], v[148:151], v[188:191], v[4:7]
	s_waitcnt vmcnt(8)
	s_setprio 3
	s_barrier
	v_mfma_f32_16x16x32_bf16 v[0:3], v[152:155], v[184:187], v[0:3]
	v_mfma_f32_16x16x32_bf16 v[0:3], v[156:159], v[188:191], v[0:3]
	s_setprio 0
.Lkazj_5_1:
	s_add_i32 s68, 0, 0x18000
	s_add_i32 s69, 0, 0x1c000
	v_add_u32_e32 v132, s68, v243
	v_add_u32_e32 v156, s69, v243
	ds_read_b128 v[120:123], v132
	ds_read_b128 v[124:127], v132 offset:1024
	ds_read_b128 v[128:131], v132 offset:2048
	ds_read_b128 v[132:135], v132 offset:3072
	ds_read_b128 v[144:147], v156
	ds_read_b128 v[148:151], v156 offset:1024
	ds_read_b128 v[152:155], v156 offset:2048
	ds_read_b128 v[156:159], v156 offset:3072
	s_add_u32 s66, s80, 0xb0000
	s_addc_u32 s67, s81, 0
	s_mov_b32 m0, s18
	v_lshl_add_u64 v[212:213], s[66:67], 0, v[192:193]
	ds_read_b128 v[160:163], v247 offset:32768
	ds_read_b128 v[164:167], v247 offset:33792
	ds_read_b128 v[168:171], v247 offset:34816
	ds_read_b128 v[172:175], v247 offset:35840
	ds_read_b128 v[176:179], v247 offset:36864
	ds_read_b128 v[180:183], v247 offset:37888
	ds_read_b128 v[184:187], v247 offset:38912
	ds_read_b128 v[188:191], v247 offset:39936
	global_load_lds_dwordx4 v[212:213], off
	s_mov_b32 m0, s19
	v_lshl_add_u64 v[212:213], s[66:67], 0, v[196:197]
	global_load_lds_dwordx4 v[212:213], off
	s_waitcnt lgkmcnt(0)
	s_barrier
	s_setprio 1
	v_mfma_f32_16x16x32_bf16 v[140:143], v[120:123], v[160:163], v[140:143]
	v_mfma_f32_16x16x32_bf16 v[140:143], v[124:127], v[164:167], v[140:143]
	v_mfma_f32_16x16x32_bf16 v[136:139], v[128:131], v[160:163], v[136:139]
	v_mfma_f32_16x16x32_bf16 v[136:139], v[132:135], v[164:167], v[136:139]
	v_mfma_f32_16x16x32_bf16 v[108:111], v[120:123], v[168:171], v[108:111]
	v_mfma_f32_16x16x32_bf16 v[108:111], v[124:127], v[172:175], v[108:111]
	v_mfma_f32_16x16x32_bf16 v[104:107], v[128:131], v[168:171], v[104:107]
	v_mfma_f32_16x16x32_bf16 v[104:107], v[132:135], v[172:175], v[104:107]
	v_mfma_f32_16x16x32_bf16 v[92:95], v[120:123], v[176:179], v[92:95]
	v_mfma_f32_16x16x32_bf16 v[92:95], v[124:127], v[180:183], v[92:95]
	v_mfma_f32_16x16x32_bf16 v[88:91], v[128:131], v[176:179], v[88:91]
	v_mfma_f32_16x16x32_bf16 v[88:91], v[132:135], v[180:183], v[88:91]
	v_mfma_f32_16x16x32_bf16 v[76:79], v[120:123], v[184:187], v[76:79]
	v_mfma_f32_16x16x32_bf16 v[76:79], v[124:127], v[188:191], v[76:79]
	v_mfma_f32_16x16x32_bf16 v[72:75], v[128:131], v[184:187], v[72:75]
	v_mfma_f32_16x16x32_bf16 v[72:75], v[132:135], v[188:191], v[72:75]
	v_mfma_f32_16x16x32_bf16 v[116:119], v[144:147], v[160:163], v[116:119]
	v_mfma_f32_16x16x32_bf16 v[116:119], v[148:151], v[164:167], v[116:119]
	v_mfma_f32_16x16x32_bf16 v[112:115], v[152:155], v[160:163], v[112:115]
	v_mfma_f32_16x16x32_bf16 v[112:115], v[156:159], v[164:167], v[112:115]
	v_mfma_f32_16x16x32_bf16 v[100:103], v[144:147], v[168:171], v[100:103]
	v_mfma_f32_16x16x32_bf16 v[100:103], v[148:151], v[172:175], v[100:103]
	v_mfma_f32_16x16x32_bf16 v[96:99], v[152:155], v[168:171], v[96:99]
	v_mfma_f32_16x16x32_bf16 v[96:99], v[156:159], v[172:175], v[96:99]
	v_mfma_f32_16x16x32_bf16 v[84:87], v[144:147], v[176:179], v[84:87]
	v_mfma_f32_16x16x32_bf16 v[84:87], v[148:151], v[180:183], v[84:87]
	v_mfma_f32_16x16x32_bf16 v[80:83], v[152:155], v[176:179], v[80:83]
	v_mfma_f32_16x16x32_bf16 v[80:83], v[156:159], v[180:183], v[80:83]
	v_mfma_f32_16x16x32_bf16 v[68:71], v[144:147], v[184:187], v[68:71]
	v_mfma_f32_16x16x32_bf16 v[68:71], v[148:151], v[188:191], v[68:71]
	s_waitcnt vmcnt(8)
	s_setprio 3
	s_barrier
	v_mfma_f32_16x16x32_bf16 v[64:67], v[152:155], v[184:187], v[64:67]
	v_mfma_f32_16x16x32_bf16 v[64:67], v[156:159], v[188:191], v[64:67]
	s_setprio 0
	s_add_i32 s66, s68, s15
	v_lshl_add_u64 v[204:205], v[204:205], 0, s[48:49]
	s_mov_b32 m0, s66
	ds_read_b128 v[160:163], v247 offset:49152
	ds_read_b128 v[164:167], v247 offset:50176
	ds_read_b128 v[168:171], v247 offset:51200
	ds_read_b128 v[172:175], v247 offset:52224
	ds_read_b128 v[176:179], v247 offset:53248
	ds_read_b128 v[180:183], v247 offset:54272
	ds_read_b128 v[184:187], v247 offset:55296
	ds_read_b128 v[188:191], v247 offset:56320
	global_load_lds_dwordx4 v[204:205], off
	s_add_i32 m0, s66, 0x2000
	s_add_u32 s66, s78, 0xb0080
	v_lshl_add_u64 v[204:205], v[206:207], 0, s[48:49]
	s_addc_u32 s67, s79, 0
	s_add_i32 s68, s69, s15
	global_load_lds_dwordx4 v[204:205], off
	s_mov_b32 m0, s68
	v_lshl_add_u64 v[204:205], s[66:67], 0, v[194:195]
	global_load_lds_dwordx4 v[204:205], off
	s_add_i32 m0, s68, 0x2000
	v_lshl_add_u64 v[204:205], s[66:67], 0, v[198:199]
	global_load_lds_dwordx4 v[204:205], off
	s_mov_b32 m0, s21
	v_lshl_add_u64 v[204:205], v[208:209], 0, s[48:49]
	global_load_lds_dwordx4 v[204:205], off
	s_mov_b32 m0, s22
	v_lshl_add_u64 v[204:205], v[210:211], 0, s[48:49]
	global_load_lds_dwordx4 v[204:205], off
	s_waitcnt lgkmcnt(0)
	s_barrier
	s_setprio 1
	v_mfma_f32_16x16x32_bf16 v[60:63], v[120:123], v[160:163], v[60:63]
	v_mfma_f32_16x16x32_bf16 v[60:63], v[124:127], v[164:167], v[60:63]
	v_mfma_f32_16x16x32_bf16 v[56:59], v[128:131], v[160:163], v[56:59]
	v_mfma_f32_16x16x32_bf16 v[56:59], v[132:135], v[164:167], v[56:59]
	v_mfma_f32_16x16x32_bf16 v[44:47], v[120:123], v[168:171], v[44:47]
	v_mfma_f32_16x16x32_bf16 v[44:47], v[124:127], v[172:175], v[44:47]
	v_mfma_f32_16x16x32_bf16 v[40:43], v[128:131], v[168:171], v[40:43]
	v_mfma_f32_16x16x32_bf16 v[40:43], v[132:135], v[172:175], v[40:43]
	v_mfma_f32_16x16x32_bf16 v[28:31], v[120:123], v[176:179], v[28:31]
	v_mfma_f32_16x16x32_bf16 v[28:31], v[124:127], v[180:183], v[28:31]
	v_mfma_f32_16x16x32_bf16 v[24:27], v[128:131], v[176:179], v[24:27]
	v_mfma_f32_16x16x32_bf16 v[24:27], v[132:135], v[180:183], v[24:27]
	v_mfma_f32_16x16x32_bf16 v[12:15], v[120:123], v[184:187], v[12:15]
	v_mfma_f32_16x16x32_bf16 v[12:15], v[124:127], v[188:191], v[12:15]
	v_mfma_f32_16x16x32_bf16 v[8:11], v[128:131], v[184:187], v[8:11]
	v_mfma_f32_16x16x32_bf16 v[8:11], v[132:135], v[188:191], v[8:11]
	v_mfma_f32_16x16x32_bf16 v[52:55], v[144:147], v[160:163], v[52:55]
	v_mfma_f32_16x16x32_bf16 v[52:55], v[148:151], v[164:167], v[52:55]
	v_mfma_f32_16x16x32_bf16 v[48:51], v[152:155], v[160:163], v[48:51]
	v_mfma_f32_16x16x32_bf16 v[48:51], v[156:159], v[164:167], v[48:51]
	v_mfma_f32_16x16x32_bf16 v[36:39], v[144:147], v[168:171], v[36:39]
	v_mfma_f32_16x16x32_bf16 v[36:39], v[148:151], v[172:175], v[36:39]
	v_mfma_f32_16x16x32_bf16 v[32:35], v[152:155], v[168:171], v[32:35]
	v_mfma_f32_16x16x32_bf16 v[32:35], v[156:159], v[172:175], v[32:35]
	v_mfma_f32_16x16x32_bf16 v[20:23], v[144:147], v[176:179], v[20:23]
	v_mfma_f32_16x16x32_bf16 v[20:23], v[148:151], v[180:183], v[20:23]
	v_mfma_f32_16x16x32_bf16 v[16:19], v[152:155], v[176:179], v[16:19]
	v_mfma_f32_16x16x32_bf16 v[16:19], v[156:159], v[180:183], v[16:19]
	v_mfma_f32_16x16x32_bf16 v[4:7], v[144:147], v[184:187], v[4:7]
	v_mfma_f32_16x16x32_bf16 v[4:7], v[148:151], v[188:191], v[4:7]
	s_waitcnt vmcnt(8)
	s_setprio 3
	s_barrier
	v_mfma_f32_16x16x32_bf16 v[0:3], v[152:155], v[184:187], v[0:3]
	v_mfma_f32_16x16x32_bf16 v[0:3], v[156:159], v[188:191], v[0:3]
	s_setprio 0
	s_add_i32 s59, s59, 2
	s_add_u32 s76, s76, 0x100
	s_addc_u32 s77, s77, 0
	s_add_u32 s55, s55, 0x100
	s_addc_u32 s58, s58, 0
	s_cmp_gt_u32 s59, 41
	s_cbranch_scc0 .Lka5_head
	s_branch .Lzskip_5

.LBB0_1759:
	s_ashr_i32 s49, s48, 31
	s_lshl_b64 s[50:51], s[48:49], 19
	s_add_u32 s50, s12, s50
	s_addc_u32 s51, s13, s51
	s_and_b64 s[52:53], s[4:5], exec
	s_cselect_b32 s49, s51, s79
	s_cselect_b32 s54, s50, s78
	s_ashr_i32 s47, s46, 31
	s_lshl_b64 s[52:53], s[46:47], 19
	s_add_u32 s52, s14, s52
	s_addc_u32 s53, s15, s53
	s_and_b64 s[66:67], s[4:5], exec
	s_cselect_b32 s47, s53, s81
	s_cselect_b32 s55, s52, s80
	s_add_u32 s78, s78, 0x40080
	s_addc_u32 s79, s79, 0
	s_add_u32 s66, s80, 0x100
	v_mov_b32_e32 v0, 0
	s_addc_u32 s67, s81, 0
	s_mov_b32 s68, -2
	s_waitcnt lgkmcnt(0)
	s_and_b64 s[100:101], exec, s[44:45]
	s_cbranch_scc1 .Lka8_head

.Lka8_head:
	ds_read_b128 v[128:131], v181
	ds_read_b128 v[132:135], v181 offset:1024
	ds_read_b128 v[136:139], v181 offset:2048
	ds_read_b128 v[160:163], v181 offset:3072
	ds_read_b128 v[164:167], v182
	ds_read_b128 v[168:171], v182 offset:1024
	ds_read_b128 v[186:189], v182 offset:2048
	ds_read_b128 v[190:193], v182 offset:3072
	s_add_u32 s69, s78, 0xfffc0080
	s_addc_u32 s73, s79, -1
	s_cmp_eq_u32 s68, 12
	s_cselect_b32 s83, s49, s73
	s_cselect_b32 s82, s54, s69
	s_cselect_b32 s81, s47, s67
	s_cselect_b32 s80, s55, s66
	v_lshl_add_u64 v[172:173], s[78:79], 0, v[152:153]
	s_add_i32 m0, s18, 0xc000
	ds_read_b128 v[194:197], v183
	ds_read_b128 v[198:201], v183 offset:1024
	ds_read_b128 v[202:205], v183 offset:2048
	ds_read_b128 v[206:209], v183 offset:3072
	ds_read_b128 v[210:213], v183 offset:4096
	ds_read_b128 v[214:217], v183 offset:5120
	ds_read_b128 v[218:221], v183 offset:6144
	ds_read_b128 v[222:225], v183 offset:7168
	global_load_lds_dwordx4 v[172:173], off
	s_add_i32 m0, s18, 0xe000
	v_lshl_add_u64 v[172:173], s[78:79], 0, v[154:155]
	global_load_lds_dwordx4 v[172:173], off
	s_cmp_eq_u32 s68, -2
	s_waitcnt lgkmcnt(0)
	s_barrier
	s_setprio 1
	s_cbranch_scc1 .Lkazv_8_0
	v_mfma_f32_16x16x32_bf16 v[124:127], v[128:131], v[194:197], v[124:127]
	v_mfma_f32_16x16x32_bf16 v[124:127], v[132:135], v[198:201], v[124:127]
	v_mfma_f32_16x16x32_bf16 v[120:123], v[136:139], v[194:197], v[120:123]
	v_mfma_f32_16x16x32_bf16 v[120:123], v[160:163], v[198:201], v[120:123]
	v_mfma_f32_16x16x32_bf16 v[108:111], v[128:131], v[202:205], v[108:111]
	v_mfma_f32_16x16x32_bf16 v[108:111], v[132:135], v[206:209], v[108:111]
	v_mfma_f32_16x16x32_bf16 v[104:107], v[136:139], v[202:205], v[104:107]
	v_mfma_f32_16x16x32_bf16 v[104:107], v[160:163], v[206:209], v[104:107]
	v_mfma_f32_16x16x32_bf16 v[92:95], v[128:131], v[210:213], v[92:95]
	v_mfma_f32_16x16x32_bf16 v[92:95], v[132:135], v[214:217], v[92:95]
	v_mfma_f32_16x16x32_bf16 v[88:91], v[136:139], v[210:213], v[88:91]
	v_mfma_f32_16x16x32_bf16 v[88:91], v[160:163], v[214:217], v[88:91]
	v_mfma_f32_16x16x32_bf16 v[76:79], v[128:131], v[218:221], v[76:79]
	v_mfma_f32_16x16x32_bf16 v[76:79], v[132:135], v[222:225], v[76:79]
	v_mfma_f32_16x16x32_bf16 v[72:75], v[136:139], v[218:221], v[72:75]
	v_mfma_f32_16x16x32_bf16 v[72:75], v[160:163], v[222:225], v[72:75]
	v_mfma_f32_16x16x32_bf16 v[116:119], v[164:167], v[194:197], v[116:119]
	v_mfma_f32_16x16x32_bf16 v[116:119], v[168:171], v[198:201], v[116:119]
	v_mfma_f32_16x16x32_bf16 v[112:115], v[186:189], v[194:197], v[112:115]
	v_mfma_f32_16x16x32_bf16 v[112:115], v[190:193], v[198:201], v[112:115]
	v_mfma_f32_16x16x32_bf16 v[100:103], v[164:167], v[202:205], v[100:103]
	v_mfma_f32_16x16x32_bf16 v[100:103], v[168:171], v[206:209], v[100:103]
	v_mfma_f32_16x16x32_bf16 v[96:99], v[186:189], v[202:205], v[96:99]
	v_mfma_f32_16x16x32_bf16 v[96:99], v[190:193], v[206:209], v[96:99]
	v_mfma_f32_16x16x32_bf16 v[84:87], v[164:167], v[210:213], v[84:87]
	v_mfma_f32_16x16x32_bf16 v[84:87], v[168:171], v[214:217], v[84:87]
	v_mfma_f32_16x16x32_bf16 v[80:83], v[186:189], v[210:213], v[80:83]
	v_mfma_f32_16x16x32_bf16 v[80:83], v[190:193], v[214:217], v[80:83]
	v_mfma_f32_16x16x32_bf16 v[68:71], v[164:167], v[218:221], v[68:71]
	v_mfma_f32_16x16x32_bf16 v[68:71], v[168:171], v[222:225], v[68:71]
	s_waitcnt vmcnt(8)
	s_setprio 3
	s_barrier
	v_mfma_f32_16x16x32_bf16 v[64:67], v[186:189], v[218:221], v[64:67]
	v_mfma_f32_16x16x32_bf16 v[64:67], v[190:193], v[222:225], v[64:67]
	s_setprio 0
.Lkazj_8_0:
	s_add_i32 s69, s25, s17
	v_lshl_add_u64 v[172:173], s[80:81], 0, v[142:143]
	s_mov_b32 m0, s69
	ds_read_b128 v[194:197], v183 offset:16384
	ds_read_b128 v[198:201], v183 offset:17408
	ds_read_b128 v[202:205], v183 offset:18432
	ds_read_b128 v[206:209], v183 offset:19456
	ds_read_b128 v[210:213], v183 offset:20480
	ds_read_b128 v[214:217], v183 offset:21504
	ds_read_b128 v[218:221], v183 offset:22528
	ds_read_b128 v[222:225], v183 offset:23552
	global_load_lds_dwordx4 v[172:173], off
	s_add_i32 m0, s69, 0x2000
	s_add_u32 s84, s80, 0x40000
	v_lshl_add_u64 v[226:227], s[80:81], 0, v[146:147]
	s_addc_u32 s85, s81, 0
	s_add_i32 s69, s26, s17
	global_load_lds_dwordx4 v[226:227], off
	v_lshl_add_u64 v[228:229], s[84:85], 0, v[142:143]
	s_mov_b32 m0, s69
	global_load_lds_dwordx4 v[228:229], off
	s_add_i32 m0, s69, 0x2000
	v_lshl_add_u64 v[228:229], s[84:85], 0, v[146:147]
	global_load_lds_dwordx4 v[228:229], off
	s_mov_b32 m0, s18
	v_lshl_add_u64 v[228:229], s[82:83], 0, v[140:141]
	global_load_lds_dwordx4 v[228:229], off
	s_mov_b32 m0, s19
	v_lshl_add_u64 v[230:231], s[82:83], 0, v[144:145]
	global_load_lds_dwordx4 v[230:231], off
	s_cmp_eq_u32 s68, -2
	s_waitcnt lgkmcnt(0)
	s_barrier
	s_setprio 1
	s_cbranch_scc1 .Lkazv_8_1
	v_mfma_f32_16x16x32_bf16 v[60:63], v[128:131], v[194:197], v[60:63]
	v_mfma_f32_16x16x32_bf16 v[60:63], v[132:135], v[198:201], v[60:63]
	v_mfma_f32_16x16x32_bf16 v[56:59], v[136:139], v[194:197], v[56:59]
	v_mfma_f32_16x16x32_bf16 v[56:59], v[160:163], v[198:201], v[56:59]
	v_mfma_f32_16x16x32_bf16 v[44:47], v[128:131], v[202:205], v[44:47]
	v_mfma_f32_16x16x32_bf16 v[44:47], v[132:135], v[206:209], v[44:47]
	v_mfma_f32_16x16x32_bf16 v[40:43], v[136:139], v[202:205], v[40:43]
	v_mfma_f32_16x16x32_bf16 v[40:43], v[160:163], v[206:209], v[40:43]
	v_mfma_f32_16x16x32_bf16 v[28:31], v[128:131], v[210:213], v[28:31]
	v_mfma_f32_16x16x32_bf16 v[28:31], v[132:135], v[214:217], v[28:31]
	v_mfma_f32_16x16x32_bf16 v[24:27], v[136:139], v[210:213], v[24:27]
	v_mfma_f32_16x16x32_bf16 v[24:27], v[160:163], v[214:217], v[24:27]
	v_mfma_f32_16x16x32_bf16 v[12:15], v[128:131], v[218:221], v[12:15]
	v_mfma_f32_16x16x32_bf16 v[12:15], v[132:135], v[222:225], v[12:15]
	v_mfma_f32_16x16x32_bf16 v[8:11], v[136:139], v[218:221], v[8:11]
	v_mfma_f32_16x16x32_bf16 v[8:11], v[160:163], v[222:225], v[8:11]
	v_mfma_f32_16x16x32_bf16 v[52:55], v[164:167], v[194:197], v[52:55]
	v_mfma_f32_16x16x32_bf16 v[52:55], v[168:171], v[198:201], v[52:55]
	v_mfma_f32_16x16x32_bf16 v[48:51], v[186:189], v[194:197], v[48:51]
	v_mfma_f32_16x16x32_bf16 v[48:51], v[190:193], v[198:201], v[48:51]
	v_mfma_f32_16x16x32_bf16 v[36:39], v[164:167], v[202:205], v[36:39]
	v_mfma_f32_16x16x32_bf16 v[36:39], v[168:171], v[206:209], v[36:39]
	v_mfma_f32_16x16x32_bf16 v[32:35], v[186:189], v[202:205], v[32:35]
	v_mfma_f32_16x16x32_bf16 v[32:35], v[190:193], v[206:209], v[32:35]
	v_mfma_f32_16x16x32_bf16 v[20:23], v[164:167], v[210:213], v[20:23]
	v_mfma_f32_16x16x32_bf16 v[20:23], v[168:171], v[214:217], v[20:23]
	v_mfma_f32_16x16x32_bf16 v[16:19], v[186:189], v[210:213], v[16:19]
	v_mfma_f32_16x16x32_bf16 v[16:19], v[190:193], v[214:217], v[16:19]
	v_mfma_f32_16x16x32_bf16 v[4:7], v[164:167], v[218:221], v[4:7]
	v_mfma_f32_16x16x32_bf16 v[4:7], v[168:171], v[222:225], v[4:7]
	s_waitcnt vmcnt(8)
	s_setprio 3
	s_barrier
	v_mfma_f32_16x16x32_bf16 v[0:3], v[186:189], v[218:221], v[0:3]
	v_mfma_f32_16x16x32_bf16 v[0:3], v[190:193], v[222:225], v[0:3]
	s_setprio 0
.Lkazj_8_1:
	s_add_i32 s69, 0, 0x18000
	v_add_u32_e32 v148, s69, v177
	s_add_i32 s73, 0, 0x1c000
	ds_read_b128 v[128:131], v148
	ds_read_b128 v[132:135], v148 offset:1024
	ds_read_b128 v[136:139], v148 offset:2048
	ds_read_b128 v[160:163], v148 offset:3072
	v_add_u32_e32 v148, s73, v177
	ds_read_b128 v[164:167], v148
	ds_read_b128 v[168:171], v148 offset:1024
	ds_read_b128 v[186:189], v148 offset:2048
	ds_read_b128 v[190:193], v148 offset:3072
	s_add_u32 s82, s82, 0x40000
	s_addc_u32 s83, s83, 0
	s_mov_b32 m0, s20
	v_lshl_add_u64 v[232:233], s[82:83], 0, v[140:141]
	ds_read_b128 v[194:197], v183 offset:32768
	ds_read_b128 v[198:201], v183 offset:33792
	ds_read_b128 v[202:205], v183 offset:34816
	ds_read_b128 v[206:209], v183 offset:35840
	ds_read_b128 v[210:213], v183 offset:36864
	ds_read_b128 v[214:217], v183 offset:37888
	ds_read_b128 v[218:221], v183 offset:38912
	ds_read_b128 v[222:225], v183 offset:39936
	global_load_lds_dwordx4 v[232:233], off
	s_mov_b32 m0, s21
	v_lshl_add_u64 v[232:233], s[82:83], 0, v[144:145]
	global_load_lds_dwordx4 v[232:233], off
	s_waitcnt lgkmcnt(0)
	s_barrier
	s_setprio 1
	v_mfma_f32_16x16x32_bf16 v[124:127], v[128:131], v[194:197], v[124:127]
	v_mfma_f32_16x16x32_bf16 v[124:127], v[132:135], v[198:201], v[124:127]
	v_mfma_f32_16x16x32_bf16 v[120:123], v[136:139], v[194:197], v[120:123]
	v_mfma_f32_16x16x32_bf16 v[120:123], v[160:163], v[198:201], v[120:123]
	v_mfma_f32_16x16x32_bf16 v[108:111], v[128:131], v[202:205], v[108:111]
	v_mfma_f32_16x16x32_bf16 v[108:111], v[132:135], v[206:209], v[108:111]
	v_mfma_f32_16x16x32_bf16 v[104:107], v[136:139], v[202:205], v[104:107]
	v_mfma_f32_16x16x32_bf16 v[104:107], v[160:163], v[206:209], v[104:107]
	v_mfma_f32_16x16x32_bf16 v[92:95], v[128:131], v[210:213], v[92:95]
	v_mfma_f32_16x16x32_bf16 v[92:95], v[132:135], v[214:217], v[92:95]
	v_mfma_f32_16x16x32_bf16 v[88:91], v[136:139], v[210:213], v[88:91]
	v_mfma_f32_16x16x32_bf16 v[88:91], v[160:163], v[214:217], v[88:91]
	v_mfma_f32_16x16x32_bf16 v[76:79], v[128:131], v[218:221], v[76:79]
	v_mfma_f32_16x16x32_bf16 v[76:79], v[132:135], v[222:225], v[76:79]
	v_mfma_f32_16x16x32_bf16 v[72:75], v[136:139], v[218:221], v[72:75]
	v_mfma_f32_16x16x32_bf16 v[72:75], v[160:163], v[222:225], v[72:75]
	v_mfma_f32_16x16x32_bf16 v[116:119], v[164:167], v[194:197], v[116:119]
	v_mfma_f32_16x16x32_bf16 v[116:119], v[168:171], v[198:201], v[116:119]
	v_mfma_f32_16x16x32_bf16 v[112:115], v[186:189], v[194:197], v[112:115]
	v_mfma_f32_16x16x32_bf16 v[112:115], v[190:193], v[198:201], v[112:115]
	v_mfma_f32_16x16x32_bf16 v[100:103], v[164:167], v[202:205], v[100:103]
	v_mfma_f32_16x16x32_bf16 v[100:103], v[168:171], v[206:209], v[100:103]
	v_mfma_f32_16x16x32_bf16 v[96:99], v[186:189], v[202:205], v[96:99]
	v_mfma_f32_16x16x32_bf16 v[96:99], v[190:193], v[206:209], v[96:99]
	v_mfma_f32_16x16x32_bf16 v[84:87], v[164:167], v[210:213], v[84:87]
	v_mfma_f32_16x16x32_bf16 v[84:87], v[168:171], v[214:217], v[84:87]
	v_mfma_f32_16x16x32_bf16 v[80:83], v[186:189], v[210:213], v[80:83]
	v_mfma_f32_16x16x32_bf16 v[80:83], v[190:193], v[214:217], v[80:83]
	v_mfma_f32_16x16x32_bf16 v[68:71], v[164:167], v[218:221], v[68:71]
	v_mfma_f32_16x16x32_bf16 v[68:71], v[168:171], v[222:225], v[68:71]
	s_waitcnt vmcnt(8)
	s_setprio 3
	s_barrier
	v_mfma_f32_16x16x32_bf16 v[64:67], v[186:189], v[218:221], v[64:67]
	v_mfma_f32_16x16x32_bf16 v[64:67], v[190:193], v[222:225], v[64:67]
	s_setprio 0
	s_add_i32 s69, s69, s17
	v_lshl_add_u64 v[172:173], v[172:173], 0, s[10:11]
	s_mov_b32 m0, s69
	ds_read_b128 v[194:197], v183 offset:49152
	ds_read_b128 v[198:201], v183 offset:50176
	ds_read_b128 v[202:205], v183 offset:51200
	ds_read_b128 v[206:209], v183 offset:52224
	ds_read_b128 v[210:213], v183 offset:53248
	ds_read_b128 v[214:217], v183 offset:54272
	ds_read_b128 v[218:221], v183 offset:55296
	ds_read_b128 v[222:225], v183 offset:56320
	global_load_lds_dwordx4 v[172:173], off
	s_add_i32 m0, s69, 0x2000
	s_add_u32 s80, s80, 0x40080
	v_lshl_add_u64 v[172:173], v[226:227], 0, s[10:11]
	s_addc_u32 s81, s81, 0
	s_add_i32 s69, s73, s17
	global_load_lds_dwordx4 v[172:173], off
	s_mov_b32 m0, s69
	v_lshl_add_u64 v[172:173], s[80:81], 0, v[142:143]
	global_load_lds_dwordx4 v[172:173], off
	s_add_i32 m0, s69, 0x2000
	v_lshl_add_u64 v[172:173], s[80:81], 0, v[146:147]
	global_load_lds_dwordx4 v[172:173], off
	s_mov_b32 m0, s23
	v_lshl_add_u64 v[172:173], v[228:229], 0, s[10:11]
	global_load_lds_dwordx4 v[172:173], off
	s_mov_b32 m0, s24
	v_lshl_add_u64 v[172:173], v[230:231], 0, s[10:11]
	global_load_lds_dwordx4 v[172:173], off
	s_waitcnt lgkmcnt(0)
	s_barrier
	s_setprio 1
	v_mfma_f32_16x16x32_bf16 v[60:63], v[128:131], v[194:197], v[60:63]
	v_mfma_f32_16x16x32_bf16 v[60:63], v[132:135], v[198:201], v[60:63]
	v_mfma_f32_16x16x32_bf16 v[56:59], v[136:139], v[194:197], v[56:59]
	v_mfma_f32_16x16x32_bf16 v[56:59], v[160:163], v[198:201], v[56:59]
	v_mfma_f32_16x16x32_bf16 v[44:47], v[128:131], v[202:205], v[44:47]
	v_mfma_f32_16x16x32_bf16 v[44:47], v[132:135], v[206:209], v[44:47]
	v_mfma_f32_16x16x32_bf16 v[40:43], v[136:139], v[202:205], v[40:43]
	v_mfma_f32_16x16x32_bf16 v[40:43], v[160:163], v[206:209], v[40:43]
	v_mfma_f32_16x16x32_bf16 v[28:31], v[128:131], v[210:213], v[28:31]
	v_mfma_f32_16x16x32_bf16 v[28:31], v[132:135], v[214:217], v[28:31]
	v_mfma_f32_16x16x32_bf16 v[24:27], v[136:139], v[210:213], v[24:27]
	v_mfma_f32_16x16x32_bf16 v[24:27], v[160:163], v[214:217], v[24:27]
	v_mfma_f32_16x16x32_bf16 v[12:15], v[128:131], v[218:221], v[12:15]
	v_mfma_f32_16x16x32_bf16 v[12:15], v[132:135], v[222:225], v[12:15]
	v_mfma_f32_16x16x32_bf16 v[8:11], v[136:139], v[218:221], v[8:11]
	v_mfma_f32_16x16x32_bf16 v[8:11], v[160:163], v[222:225], v[8:11]
	v_mfma_f32_16x16x32_bf16 v[52:55], v[164:167], v[194:197], v[52:55]
	v_mfma_f32_16x16x32_bf16 v[52:55], v[168:171], v[198:201], v[52:55]
	v_mfma_f32_16x16x32_bf16 v[48:51], v[186:189], v[194:197], v[48:51]
	v_mfma_f32_16x16x32_bf16 v[48:51], v[190:193], v[198:201], v[48:51]
	v_mfma_f32_16x16x32_bf16 v[36:39], v[164:167], v[202:205], v[36:39]
	v_mfma_f32_16x16x32_bf16 v[36:39], v[168:171], v[206:209], v[36:39]
	v_mfma_f32_16x16x32_bf16 v[32:35], v[186:189], v[202:205], v[32:35]
	v_mfma_f32_16x16x32_bf16 v[32:35], v[190:193], v[206:209], v[32:35]
	v_mfma_f32_16x16x32_bf16 v[20:23], v[164:167], v[210:213], v[20:23]
	v_mfma_f32_16x16x32_bf16 v[20:23], v[168:171], v[214:217], v[20:23]
	v_mfma_f32_16x16x32_bf16 v[16:19], v[186:189], v[210:213], v[16:19]
	v_mfma_f32_16x16x32_bf16 v[16:19], v[190:193], v[214:217], v[16:19]
	v_mfma_f32_16x16x32_bf16 v[4:7], v[164:167], v[218:221], v[4:7]
	v_mfma_f32_16x16x32_bf16 v[4:7], v[168:171], v[222:225], v[4:7]
	s_waitcnt vmcnt(8)
	s_setprio 3
	s_barrier
	v_mfma_f32_16x16x32_bf16 v[0:3], v[186:189], v[218:221], v[0:3]
	v_mfma_f32_16x16x32_bf16 v[0:3], v[190:193], v[222:225], v[0:3]
	s_setprio 0
	s_add_i32 s68, s68, 2
	s_add_u32 s78, s78, 0x100
	s_addc_u32 s79, s79, 0
	s_add_u32 s66, s66, 0x100
	s_addc_u32 s67, s67, 0
	s_cmp_gt_u32 s68, 13
	s_cbranch_scc0 .Lka8_head
	s_branch .Lzskip_8
.Lkazv_8_0:
	v_mfma_f32_16x16x32_bf16 v[124:127], v[128:131], v[194:197], 0
	v_mfma_f32_16x16x32_bf16 v[124:127], v[132:135], v[198:201], v[124:127]
	v_mfma_f32_16x16x32_bf16 v[120:123], v[136:139], v[194:197], 0
	v_mfma_f32_16x16x32_bf16 v[120:123], v[160:163], v[198:201], v[120:123]
	v_mfma_f32_16x16x32_bf16 v[108:111], v[128:131], v[202:205], 0
	v_mfma_f32_16x16x32_bf16 v[108:111], v[132:135], v[206:209], v[108:111]
	v_mfma_f32_16x16x32_bf16 v[104:107], v[136:139], v[202:205], 0
	v_mfma_f32_16x16x32_bf16 v[104:107], v[160:163], v[206:209], v[104:107]
	v_mfma_f32_16x16x32_bf16 v[92:95], v[128:131], v[210:213], 0
	v_mfma_f32_16x16x32_bf16 v[92:95], v[132:135], v[214:217], v[92:95]
	v_mfma_f32_16x16x32_bf16 v[88:91], v[136:139], v[210:213], 0
	v_mfma_f32_16x16x32_bf16 v[88:91], v[160:163], v[214:217], v[88:91]
	v_mfma_f32_16x16x32_bf16 v[76:79], v[128:131], v[218:221], 0
	v_mfma_f32_16x16x32_bf16 v[76:79], v[132:135], v[222:225], v[76:79]
	v_mfma_f32_16x16x32_bf16 v[72:75], v[136:139], v[218:221], 0
	v_mfma_f32_16x16x32_bf16 v[72:75], v[160:163], v[222:225], v[72:75]
	v_mfma_f32_16x16x32_bf16 v[116:119], v[164:167], v[194:197], 0
	v_mfma_f32_16x16x32_bf16 v[116:119], v[168:171], v[198:201], v[116:119]
	v_mfma_f32_16x16x32_bf16 v[112:115], v[186:189], v[194:197], 0
	v_mfma_f32_16x16x32_bf16 v[112:115], v[190:193], v[198:201], v[112:115]
	v_mfma_f32_16x16x32_bf16 v[100:103], v[164:167], v[202:205], 0
	v_mfma_f32_16x16x32_bf16 v[100:103], v[168:171], v[206:209], v[100:103]
	v_mfma_f32_16x16x32_bf16 v[96:99], v[186:189], v[202:205], 0
	v_mfma_f32_16x16x32_bf16 v[96:99], v[190:193], v[206:209], v[96:99]
	v_mfma_f32_16x16x32_bf16 v[84:87], v[164:167], v[210:213], 0
	v_mfma_f32_16x16x32_bf16 v[84:87], v[168:171], v[214:217], v[84:87]
	v_mfma_f32_16x16x32_bf16 v[80:83], v[186:189], v[210:213], 0
	v_mfma_f32_16x16x32_bf16 v[80:83], v[190:193], v[214:217], v[80:83]
	v_mfma_f32_16x16x32_bf16 v[68:71], v[164:167], v[218:221], 0
	v_mfma_f32_16x16x32_bf16 v[68:71], v[168:171], v[222:225], v[68:71]
	s_waitcnt vmcnt(8)
	s_setprio 3
	s_barrier
	v_mfma_f32_16x16x32_bf16 v[64:67], v[186:189], v[218:221], 0
	v_mfma_f32_16x16x32_bf16 v[64:67], v[190:193], v[222:225], v[64:67]
	s_setprio 0
	s_branch .Lkazj_8_0
.Lkazv_8_1:
	v_mfma_f32_16x16x32_bf16 v[60:63], v[128:131], v[194:197], 0
	v_mfma_f32_16x16x32_bf16 v[60:63], v[132:135], v[198:201], v[60:63]
	v_mfma_f32_16x16x32_bf16 v[56:59], v[136:139], v[194:197], 0
	v_mfma_f32_16x16x32_bf16 v[56:59], v[160:163], v[198:201], v[56:59]
	v_mfma_f32_16x16x32_bf16 v[44:47], v[128:131], v[202:205], 0
	v_mfma_f32_16x16x32_bf16 v[44:47], v[132:135], v[206:209], v[44:47]
	v_mfma_f32_16x16x32_bf16 v[40:43], v[136:139], v[202:205], 0
	v_mfma_f32_16x16x32_bf16 v[40:43], v[160:163], v[206:209], v[40:43]
	v_mfma_f32_16x16x32_bf16 v[28:31], v[128:131], v[210:213], 0
	v_mfma_f32_16x16x32_bf16 v[28:31], v[132:135], v[214:217], v[28:31]
	v_mfma_f32_16x16x32_bf16 v[24:27], v[136:139], v[210:213], 0
	v_mfma_f32_16x16x32_bf16 v[24:27], v[160:163], v[214:217], v[24:27]
	v_mfma_f32_16x16x32_bf16 v[12:15], v[128:131], v[218:221], 0
	v_mfma_f32_16x16x32_bf16 v[12:15], v[132:135], v[222:225], v[12:15]
	v_mfma_f32_16x16x32_bf16 v[8:11], v[136:139], v[218:221], 0
	v_mfma_f32_16x16x32_bf16 v[8:11], v[160:163], v[222:225], v[8:11]
	v_mfma_f32_16x16x32_bf16 v[52:55], v[164:167], v[194:197], 0
	v_mfma_f32_16x16x32_bf16 v[52:55], v[168:171], v[198:201], v[52:55]
	v_mfma_f32_16x16x32_bf16 v[48:51], v[186:189], v[194:197], 0
	v_mfma_f32_16x16x32_bf16 v[48:51], v[190:193], v[198:201], v[48:51]
	v_mfma_f32_16x16x32_bf16 v[36:39], v[164:167], v[202:205], 0
	v_mfma_f32_16x16x32_bf16 v[36:39], v[168:171], v[206:209], v[36:39]
	v_mfma_f32_16x16x32_bf16 v[32:35], v[186:189], v[202:205], 0
	v_mfma_f32_16x16x32_bf16 v[32:35], v[190:193], v[206:209], v[32:35]
	v_mfma_f32_16x16x32_bf16 v[20:23], v[164:167], v[210:213], 0
	v_mfma_f32_16x16x32_bf16 v[20:23], v[168:171], v[214:217], v[20:23]
	v_mfma_f32_16x16x32_bf16 v[16:19], v[186:189], v[210:213], 0
	v_mfma_f32_16x16x32_bf16 v[16:19], v[190:193], v[214:217], v[16:19]
	v_mfma_f32_16x16x32_bf16 v[4:7], v[164:167], v[218:221], 0
	v_mfma_f32_16x16x32_bf16 v[4:7], v[168:171], v[222:225], v[4:7]
	s_waitcnt vmcnt(8)
	s_setprio 3
	s_barrier
	v_mfma_f32_16x16x32_bf16 v[0:3], v[186:189], v[218:221], 0
	v_mfma_f32_16x16x32_bf16 v[0:3], v[190:193], v[222:225], v[0:3]
	s_setprio 0
	s_branch .Lkazj_8_1
	s_branch .Lzskip_8

.LBB0_2036:
	s_ashr_i32 s53, s52, 31
	s_lshl_b64 s[54:55], s[52:53], 19
	s_add_u32 s58, s42, s54
	s_addc_u32 s59, s43, s55
	s_and_b64 s[54:55], s[6:7], exec
	s_cselect_b32 s53, s59, s77
	s_cselect_b32 s54, s58, s76
	s_ashr_i32 s51, s50, 31
	s_lshl_b64 s[56:57], s[50:51], 19
	s_add_u32 s72, s3, s56
	s_addc_u32 s73, s14, s57
	s_and_b64 s[56:57], s[6:7], exec
	s_cselect_b32 s51, s73, s79
	s_cselect_b32 s55, s72, s78
	s_add_u32 s76, s76, 0x40080
	s_addc_u32 s77, s77, 0
	s_add_u32 s56, s78, 0x100
	v_mov_b32_e32 v0, 0
	s_addc_u32 s57, s79, 0
	s_mov_b32 s66, -2
	s_and_b64 s[100:101], exec, s[48:49]
	s_cbranch_scc1 .Lka9_head

.Lka9_head:
	ds_read_b128 v[120:123], v245
	ds_read_b128 v[124:127], v245 offset:1024
	ds_read_b128 v[128:131], v245 offset:2048
	ds_read_b128 v[132:135], v245 offset:3072
	ds_read_b128 v[144:147], v246
	ds_read_b128 v[148:151], v246 offset:1024
	ds_read_b128 v[152:155], v246 offset:2048
	ds_read_b128 v[156:159], v246 offset:3072
	s_add_u32 s67, s76, 0xfffc0080
	s_addc_u32 s68, s77, -1
	s_cmp_eq_u32 s66, 12
	s_cselect_b32 s81, s53, s68
	s_cselect_b32 s80, s54, s67
	s_cselect_b32 s79, s51, s57
	s_cselect_b32 s78, s55, s56
	v_lshl_add_u64 v[204:205], s[76:77], 0, v[200:201]
	s_add_i32 m0, s16, 0xc000
	ds_read_b128 v[160:163], v247
	ds_read_b128 v[164:167], v247 offset:1024
	ds_read_b128 v[168:171], v247 offset:2048
	ds_read_b128 v[172:175], v247 offset:3072
	ds_read_b128 v[176:179], v247 offset:4096
	ds_read_b128 v[180:183], v247 offset:5120
	ds_read_b128 v[184:187], v247 offset:6144
	ds_read_b128 v[188:191], v247 offset:7168
	global_load_lds_dwordx4 v[204:205], off
	s_add_i32 m0, s16, 0xe000
	v_lshl_add_u64 v[204:205], s[76:77], 0, v[202:203]
	global_load_lds_dwordx4 v[204:205], off
	s_cmp_eq_u32 s66, -2
	s_waitcnt lgkmcnt(0)
	s_barrier
	s_setprio 1
	s_cbranch_scc1 .Lkazv_9_0
	v_mfma_f32_16x16x32_bf16 v[140:143], v[120:123], v[160:163], v[140:143]
	v_mfma_f32_16x16x32_bf16 v[140:143], v[124:127], v[164:167], v[140:143]
	v_mfma_f32_16x16x32_bf16 v[136:139], v[128:131], v[160:163], v[136:139]
	v_mfma_f32_16x16x32_bf16 v[136:139], v[132:135], v[164:167], v[136:139]
	v_mfma_f32_16x16x32_bf16 v[108:111], v[120:123], v[168:171], v[108:111]
	v_mfma_f32_16x16x32_bf16 v[108:111], v[124:127], v[172:175], v[108:111]
	v_mfma_f32_16x16x32_bf16 v[104:107], v[128:131], v[168:171], v[104:107]
	v_mfma_f32_16x16x32_bf16 v[104:107], v[132:135], v[172:175], v[104:107]
	v_mfma_f32_16x16x32_bf16 v[92:95], v[120:123], v[176:179], v[92:95]
	v_mfma_f32_16x16x32_bf16 v[92:95], v[124:127], v[180:183], v[92:95]
	v_mfma_f32_16x16x32_bf16 v[88:91], v[128:131], v[176:179], v[88:91]
	v_mfma_f32_16x16x32_bf16 v[88:91], v[132:135], v[180:183], v[88:91]
	v_mfma_f32_16x16x32_bf16 v[76:79], v[120:123], v[184:187], v[76:79]
	v_mfma_f32_16x16x32_bf16 v[76:79], v[124:127], v[188:191], v[76:79]
	v_mfma_f32_16x16x32_bf16 v[72:75], v[128:131], v[184:187], v[72:75]
	v_mfma_f32_16x16x32_bf16 v[72:75], v[132:135], v[188:191], v[72:75]
	v_mfma_f32_16x16x32_bf16 v[116:119], v[144:147], v[160:163], v[116:119]
	v_mfma_f32_16x16x32_bf16 v[116:119], v[148:151], v[164:167], v[116:119]
	v_mfma_f32_16x16x32_bf16 v[112:115], v[152:155], v[160:163], v[112:115]
	v_mfma_f32_16x16x32_bf16 v[112:115], v[156:159], v[164:167], v[112:115]
	v_mfma_f32_16x16x32_bf16 v[100:103], v[144:147], v[168:171], v[100:103]
	v_mfma_f32_16x16x32_bf16 v[100:103], v[148:151], v[172:175], v[100:103]
	v_mfma_f32_16x16x32_bf16 v[96:99], v[152:155], v[168:171], v[96:99]
	v_mfma_f32_16x16x32_bf16 v[96:99], v[156:159], v[172:175], v[96:99]
	v_mfma_f32_16x16x32_bf16 v[84:87], v[144:147], v[176:179], v[84:87]
	v_mfma_f32_16x16x32_bf16 v[84:87], v[148:151], v[180:183], v[84:87]
	v_mfma_f32_16x16x32_bf16 v[80:83], v[152:155], v[176:179], v[80:83]
	v_mfma_f32_16x16x32_bf16 v[80:83], v[156:159], v[180:183], v[80:83]
	v_mfma_f32_16x16x32_bf16 v[68:71], v[144:147], v[184:187], v[68:71]
	v_mfma_f32_16x16x32_bf16 v[68:71], v[148:151], v[188:191], v[68:71]
	s_waitcnt vmcnt(8)
	s_setprio 3
	s_barrier
	v_mfma_f32_16x16x32_bf16 v[64:67], v[152:155], v[184:187], v[64:67]
	v_mfma_f32_16x16x32_bf16 v[64:67], v[156:159], v[188:191], v[64:67]
	s_setprio 0
.Lkazj_9_0:
	s_add_i32 s67, s26, s15
	v_lshl_add_u64 v[204:205], s[78:79], 0, v[194:195]
	s_mov_b32 m0, s67
	ds_read_b128 v[160:163], v247 offset:16384
	ds_read_b128 v[164:167], v247 offset:17408
	ds_read_b128 v[168:171], v247 offset:18432
	ds_read_b128 v[172:175], v247 offset:19456
	ds_read_b128 v[176:179], v247 offset:20480
	ds_read_b128 v[180:183], v247 offset:21504
	ds_read_b128 v[184:187], v247 offset:22528
	ds_read_b128 v[188:191], v247 offset:23552
	global_load_lds_dwordx4 v[204:205], off
	s_add_i32 m0, s67, 0x2000
	s_add_u32 s68, s78, 0x40000
	v_lshl_add_u64 v[206:207], s[78:79], 0, v[198:199]
	s_addc_u32 s69, s79, 0
	s_add_i32 s67, s27, s15
	global_load_lds_dwordx4 v[206:207], off
	v_lshl_add_u64 v[208:209], s[68:69], 0, v[194:195]
	s_mov_b32 m0, s67
	global_load_lds_dwordx4 v[208:209], off
	s_add_i32 m0, s67, 0x2000
	v_lshl_add_u64 v[208:209], s[68:69], 0, v[198:199]
	global_load_lds_dwordx4 v[208:209], off
	s_mov_b32 m0, s16
	v_lshl_add_u64 v[208:209], s[80:81], 0, v[192:193]
	global_load_lds_dwordx4 v[208:209], off
	s_mov_b32 m0, s17
	v_lshl_add_u64 v[210:211], s[80:81], 0, v[196:197]
	global_load_lds_dwordx4 v[210:211], off
	s_cmp_eq_u32 s66, -2
	s_waitcnt lgkmcnt(0)
	s_barrier
	s_setprio 1
	s_cbranch_scc1 .Lkazv_9_1
	v_mfma_f32_16x16x32_bf16 v[60:63], v[120:123], v[160:163], v[60:63]
	v_mfma_f32_16x16x32_bf16 v[60:63], v[124:127], v[164:167], v[60:63]
	v_mfma_f32_16x16x32_bf16 v[56:59], v[128:131], v[160:163], v[56:59]
	v_mfma_f32_16x16x32_bf16 v[56:59], v[132:135], v[164:167], v[56:59]
	v_mfma_f32_16x16x32_bf16 v[44:47], v[120:123], v[168:171], v[44:47]
	v_mfma_f32_16x16x32_bf16 v[44:47], v[124:127], v[172:175], v[44:47]
	v_mfma_f32_16x16x32_bf16 v[40:43], v[128:131], v[168:171], v[40:43]
	v_mfma_f32_16x16x32_bf16 v[40:43], v[132:135], v[172:175], v[40:43]
	v_mfma_f32_16x16x32_bf16 v[28:31], v[120:123], v[176:179], v[28:31]
	v_mfma_f32_16x16x32_bf16 v[28:31], v[124:127], v[180:183], v[28:31]
	v_mfma_f32_16x16x32_bf16 v[24:27], v[128:131], v[176:179], v[24:27]
	v_mfma_f32_16x16x32_bf16 v[24:27], v[132:135], v[180:183], v[24:27]
	v_mfma_f32_16x16x32_bf16 v[12:15], v[120:123], v[184:187], v[12:15]
	v_mfma_f32_16x16x32_bf16 v[12:15], v[124:127], v[188:191], v[12:15]
	v_mfma_f32_16x16x32_bf16 v[8:11], v[128:131], v[184:187], v[8:11]
	v_mfma_f32_16x16x32_bf16 v[8:11], v[132:135], v[188:191], v[8:11]
	v_mfma_f32_16x16x32_bf16 v[52:55], v[144:147], v[160:163], v[52:55]
	v_mfma_f32_16x16x32_bf16 v[52:55], v[148:151], v[164:167], v[52:55]
	v_mfma_f32_16x16x32_bf16 v[48:51], v[152:155], v[160:163], v[48:51]
	v_mfma_f32_16x16x32_bf16 v[48:51], v[156:159], v[164:167], v[48:51]
	v_mfma_f32_16x16x32_bf16 v[36:39], v[144:147], v[168:171], v[36:39]
	v_mfma_f32_16x16x32_bf16 v[36:39], v[148:151], v[172:175], v[36:39]
	v_mfma_f32_16x16x32_bf16 v[32:35], v[152:155], v[168:171], v[32:35]
	v_mfma_f32_16x16x32_bf16 v[32:35], v[156:159], v[172:175], v[32:35]
	v_mfma_f32_16x16x32_bf16 v[20:23], v[144:147], v[176:179], v[20:23]
	v_mfma_f32_16x16x32_bf16 v[20:23], v[148:151], v[180:183], v[20:23]
	v_mfma_f32_16x16x32_bf16 v[16:19], v[152:155], v[176:179], v[16:19]
	v_mfma_f32_16x16x32_bf16 v[16:19], v[156:159], v[180:183], v[16:19]
	v_mfma_f32_16x16x32_bf16 v[4:7], v[144:147], v[184:187], v[4:7]
	v_mfma_f32_16x16x32_bf16 v[4:7], v[148:151], v[188:191], v[4:7]
	s_waitcnt vmcnt(8)
	s_setprio 3
	s_barrier
	v_mfma_f32_16x16x32_bf16 v[0:3], v[152:155], v[184:187], v[0:3]
	v_mfma_f32_16x16x32_bf16 v[0:3], v[156:159], v[188:191], v[0:3]
	s_setprio 0
.Lkazj_9_1:
	s_add_i32 s67, 0, 0x18000
	s_add_i32 s75, 0, 0x1c000
	v_add_u32_e32 v132, s67, v243
	v_add_u32_e32 v156, s75, v243
	ds_read_b128 v[120:123], v132
	ds_read_b128 v[124:127], v132 offset:1024
	ds_read_b128 v[128:131], v132 offset:2048
	ds_read_b128 v[132:135], v132 offset:3072
	ds_read_b128 v[144:147], v156
	ds_read_b128 v[148:151], v156 offset:1024
	ds_read_b128 v[152:155], v156 offset:2048
	ds_read_b128 v[156:159], v156 offset:3072
	s_add_u32 s68, s80, 0x40000
	s_addc_u32 s69, s81, 0
	s_mov_b32 m0, s18
	v_lshl_add_u64 v[212:213], s[68:69], 0, v[192:193]
	ds_read_b128 v[160:163], v247 offset:32768
	ds_read_b128 v[164:167], v247 offset:33792
	ds_read_b128 v[168:171], v247 offset:34816
	ds_read_b128 v[172:175], v247 offset:35840
	ds_read_b128 v[176:179], v247 offset:36864
	ds_read_b128 v[180:183], v247 offset:37888
	ds_read_b128 v[184:187], v247 offset:38912
	ds_read_b128 v[188:191], v247 offset:39936
	global_load_lds_dwordx4 v[212:213], off
	s_mov_b32 m0, s19
	v_lshl_add_u64 v[212:213], s[68:69], 0, v[196:197]
	global_load_lds_dwordx4 v[212:213], off
	s_waitcnt lgkmcnt(0)
	s_barrier
	s_setprio 1
	v_mfma_f32_16x16x32_bf16 v[140:143], v[120:123], v[160:163], v[140:143]
	v_mfma_f32_16x16x32_bf16 v[140:143], v[124:127], v[164:167], v[140:143]
	v_mfma_f32_16x16x32_bf16 v[136:139], v[128:131], v[160:163], v[136:139]
	v_mfma_f32_16x16x32_bf16 v[136:139], v[132:135], v[164:167], v[136:139]
	v_mfma_f32_16x16x32_bf16 v[108:111], v[120:123], v[168:171], v[108:111]
	v_mfma_f32_16x16x32_bf16 v[108:111], v[124:127], v[172:175], v[108:111]
	v_mfma_f32_16x16x32_bf16 v[104:107], v[128:131], v[168:171], v[104:107]
	v_mfma_f32_16x16x32_bf16 v[104:107], v[132:135], v[172:175], v[104:107]
	v_mfma_f32_16x16x32_bf16 v[92:95], v[120:123], v[176:179], v[92:95]
	v_mfma_f32_16x16x32_bf16 v[92:95], v[124:127], v[180:183], v[92:95]
	v_mfma_f32_16x16x32_bf16 v[88:91], v[128:131], v[176:179], v[88:91]
	v_mfma_f32_16x16x32_bf16 v[88:91], v[132:135], v[180:183], v[88:91]
	v_mfma_f32_16x16x32_bf16 v[76:79], v[120:123], v[184:187], v[76:79]
	v_mfma_f32_16x16x32_bf16 v[76:79], v[124:127], v[188:191], v[76:79]
	v_mfma_f32_16x16x32_bf16 v[72:75], v[128:131], v[184:187], v[72:75]
	v_mfma_f32_16x16x32_bf16 v[72:75], v[132:135], v[188:191], v[72:75]
	v_mfma_f32_16x16x32_bf16 v[116:119], v[144:147], v[160:163], v[116:119]
	v_mfma_f32_16x16x32_bf16 v[116:119], v[148:151], v[164:167], v[116:119]
	v_mfma_f32_16x16x32_bf16 v[112:115], v[152:155], v[160:163], v[112:115]
	v_mfma_f32_16x16x32_bf16 v[112:115], v[156:159], v[164:167], v[112:115]
	v_mfma_f32_16x16x32_bf16 v[100:103], v[144:147], v[168:171], v[100:103]
	v_mfma_f32_16x16x32_bf16 v[100:103], v[148:151], v[172:175], v[100:103]
	v_mfma_f32_16x16x32_bf16 v[96:99], v[152:155], v[168:171], v[96:99]
	v_mfma_f32_16x16x32_bf16 v[96:99], v[156:159], v[172:175], v[96:99]
	v_mfma_f32_16x16x32_bf16 v[84:87], v[144:147], v[176:179], v[84:87]
	v_mfma_f32_16x16x32_bf16 v[84:87], v[148:151], v[180:183], v[84:87]
	v_mfma_f32_16x16x32_bf16 v[80:83], v[152:155], v[176:179], v[80:83]
	v_mfma_f32_16x16x32_bf16 v[80:83], v[156:159], v[180:183], v[80:83]
	v_mfma_f32_16x16x32_bf16 v[68:71], v[144:147], v[184:187], v[68:71]
	v_mfma_f32_16x16x32_bf16 v[68:71], v[148:151], v[188:191], v[68:71]
	s_waitcnt vmcnt(8)
	s_setprio 3
	s_barrier
	v_mfma_f32_16x16x32_bf16 v[64:67], v[152:155], v[184:187], v[64:67]
	v_mfma_f32_16x16x32_bf16 v[64:67], v[156:159], v[188:191], v[64:67]
	s_setprio 0
	s_add_i32 s67, s67, s15
	v_lshl_add_u64 v[204:205], v[204:205], 0, s[46:47]
	s_mov_b32 m0, s67
	ds_read_b128 v[160:163], v247 offset:49152
	ds_read_b128 v[164:167], v247 offset:50176
	ds_read_b128 v[168:171], v247 offset:51200
	ds_read_b128 v[172:175], v247 offset:52224
	ds_read_b128 v[176:179], v247 offset:53248
	ds_read_b128 v[180:183], v247 offset:54272
	ds_read_b128 v[184:187], v247 offset:55296
	ds_read_b128 v[188:191], v247 offset:56320
	global_load_lds_dwordx4 v[204:205], off
	s_add_i32 m0, s67, 0x2000
	s_add_u32 s68, s78, 0x40080
	v_lshl_add_u64 v[204:205], v[206:207], 0, s[46:47]
	s_addc_u32 s69, s79, 0
	s_add_i32 s67, s75, s15
	global_load_lds_dwordx4 v[204:205], off
	s_mov_b32 m0, s67
	v_lshl_add_u64 v[204:205], s[68:69], 0, v[194:195]
	global_load_lds_dwordx4 v[204:205], off
	s_add_i32 m0, s67, 0x2000
	v_lshl_add_u64 v[204:205], s[68:69], 0, v[198:199]
	global_load_lds_dwordx4 v[204:205], off
	s_mov_b32 m0, s21
	v_lshl_add_u64 v[204:205], v[208:209], 0, s[46:47]
	global_load_lds_dwordx4 v[204:205], off
	s_mov_b32 m0, s22
	v_lshl_add_u64 v[204:205], v[210:211], 0, s[46:47]
	global_load_lds_dwordx4 v[204:205], off
	s_waitcnt lgkmcnt(0)
	s_barrier
	s_setprio 1
	v_mfma_f32_16x16x32_bf16 v[60:63], v[120:123], v[160:163], v[60:63]
	v_mfma_f32_16x16x32_bf16 v[60:63], v[124:127], v[164:167], v[60:63]
	v_mfma_f32_16x16x32_bf16 v[56:59], v[128:131], v[160:163], v[56:59]
	v_mfma_f32_16x16x32_bf16 v[56:59], v[132:135], v[164:167], v[56:59]
	v_mfma_f32_16x16x32_bf16 v[44:47], v[120:123], v[168:171], v[44:47]
	v_mfma_f32_16x16x32_bf16 v[44:47], v[124:127], v[172:175], v[44:47]
	v_mfma_f32_16x16x32_bf16 v[40:43], v[128:131], v[168:171], v[40:43]
	v_mfma_f32_16x16x32_bf16 v[40:43], v[132:135], v[172:175], v[40:43]
	v_mfma_f32_16x16x32_bf16 v[28:31], v[120:123], v[176:179], v[28:31]
	v_mfma_f32_16x16x32_bf16 v[28:31], v[124:127], v[180:183], v[28:31]
	v_mfma_f32_16x16x32_bf16 v[24:27], v[128:131], v[176:179], v[24:27]
	v_mfma_f32_16x16x32_bf16 v[24:27], v[132:135], v[180:183], v[24:27]
	v_mfma_f32_16x16x32_bf16 v[12:15], v[120:123], v[184:187], v[12:15]
	v_mfma_f32_16x16x32_bf16 v[12:15], v[124:127], v[188:191], v[12:15]
	v_mfma_f32_16x16x32_bf16 v[8:11], v[128:131], v[184:187], v[8:11]
	v_mfma_f32_16x16x32_bf16 v[8:11], v[132:135], v[188:191], v[8:11]
	v_mfma_f32_16x16x32_bf16 v[52:55], v[144:147], v[160:163], v[52:55]
	v_mfma_f32_16x16x32_bf16 v[52:55], v[148:151], v[164:167], v[52:55]
	v_mfma_f32_16x16x32_bf16 v[48:51], v[152:155], v[160:163], v[48:51]
	v_mfma_f32_16x16x32_bf16 v[48:51], v[156:159], v[164:167], v[48:51]
	v_mfma_f32_16x16x32_bf16 v[36:39], v[144:147], v[168:171], v[36:39]
	v_mfma_f32_16x16x32_bf16 v[36:39], v[148:151], v[172:175], v[36:39]
	v_mfma_f32_16x16x32_bf16 v[32:35], v[152:155], v[168:171], v[32:35]
	v_mfma_f32_16x16x32_bf16 v[32:35], v[156:159], v[172:175], v[32:35]
	v_mfma_f32_16x16x32_bf16 v[20:23], v[144:147], v[176:179], v[20:23]
	v_mfma_f32_16x16x32_bf16 v[20:23], v[148:151], v[180:183], v[20:23]
	v_mfma_f32_16x16x32_bf16 v[16:19], v[152:155], v[176:179], v[16:19]
	v_mfma_f32_16x16x32_bf16 v[16:19], v[156:159], v[180:183], v[16:19]
	v_mfma_f32_16x16x32_bf16 v[4:7], v[144:147], v[184:187], v[4:7]
	v_mfma_f32_16x16x32_bf16 v[4:7], v[148:151], v[188:191], v[4:7]
	s_waitcnt vmcnt(8)
	s_setprio 3
	s_barrier
	v_mfma_f32_16x16x32_bf16 v[0:3], v[152:155], v[184:187], v[0:3]
	v_mfma_f32_16x16x32_bf16 v[0:3], v[156:159], v[188:191], v[0:3]
	s_setprio 0
	s_add_i32 s66, s66, 2
	s_add_u32 s76, s76, 0x100
	s_addc_u32 s77, s77, 0
	s_add_u32 s56, s56, 0x100
	s_addc_u32 s57, s57, 0
	s_cmp_gt_u32 s66, 13
	s_cbranch_scc0 .Lka9_head
	s_branch .Lzskip_9

.LBB0_2191:
	s_ashr_i32 s47, s46, 31
	s_lshl_b64 s[48:49], s[46:47], 19
	s_add_u32 s48, s12, s48
	s_addc_u32 s49, s13, s49
	s_and_b64 s[50:51], s[4:5], exec
	s_cselect_b32 s47, s49, s59
	s_cselect_b32 s53, s48, s58
	s_ashr_i32 s45, s44, 31
	s_lshl_b64 s[50:51], s[44:45], 19
	s_add_u32 s50, s14, s50
	s_addc_u32 s51, s15, s51
	s_and_b64 s[66:67], s[4:5], exec
	s_cselect_b32 s45, s51, s73
	s_cselect_b32 s66, s50, s72
	s_add_u32 s58, s58, 0x40080
	s_addc_u32 s59, s59, 0
	s_add_u32 s67, s72, 0x100
	v_mov_b32_e32 v0, 0
	s_addc_u32 s68, s73, 0
	s_mov_b32 s69, -2
	s_waitcnt lgkmcnt(0)
	s_and_b64 s[100:101], exec, s[42:43]
	s_cbranch_scc1 .Lka10_head

.Lka10_head:
	ds_read_b128 v[146:149], v174
	ds_read_b128 v[150:153], v174 offset:1024
	ds_read_b128 v[154:157], v174 offset:2048
	ds_read_b128 v[158:161], v174 offset:3072
	ds_read_b128 v[162:165], v175
	ds_read_b128 v[178:181], v175 offset:1024
	ds_read_b128 v[182:185], v175 offset:2048
	ds_read_b128 v[186:189], v175 offset:3072
	s_add_u32 s70, s58, 0xfffc0080
	s_addc_u32 s71, s59, -1
	s_cmp_eq_u32 s69, 12
	s_cselect_b32 s73, s47, s71
	s_cselect_b32 s72, s53, s70
	s_cselect_b32 s71, s45, s68
	s_cselect_b32 s70, s66, s67
	v_lshl_add_u64 v[166:167], s[58:59], 0, v[136:137]
	s_add_i32 m0, s17, 0xc000
	ds_read_b128 v[190:193], v176
	ds_read_b128 v[194:197], v176 offset:1024
	ds_read_b128 v[198:201], v176 offset:2048
	ds_read_b128 v[202:205], v176 offset:3072
	ds_read_b128 v[206:209], v176 offset:4096
	ds_read_b128 v[210:213], v176 offset:5120
	ds_read_b128 v[214:217], v176 offset:6144
	ds_read_b128 v[218:221], v176 offset:7168
	global_load_lds_dwordx4 v[166:167], off
	s_add_i32 m0, s17, 0xe000
	v_lshl_add_u64 v[166:167], s[58:59], 0, v[140:141]
	global_load_lds_dwordx4 v[166:167], off
	s_cmp_eq_u32 s69, -2
	s_waitcnt lgkmcnt(0)
	s_barrier
	s_setprio 1
	s_cbranch_scc1 .Lkazv_10_0
	v_mfma_f32_16x16x32_bf16 v[124:127], v[146:149], v[190:193], v[124:127]
	v_mfma_f32_16x16x32_bf16 v[124:127], v[150:153], v[194:197], v[124:127]
	v_mfma_f32_16x16x32_bf16 v[116:119], v[154:157], v[190:193], v[116:119]
	v_mfma_f32_16x16x32_bf16 v[116:119], v[158:161], v[194:197], v[116:119]
	v_mfma_f32_16x16x32_bf16 v[108:111], v[146:149], v[198:201], v[108:111]
	v_mfma_f32_16x16x32_bf16 v[108:111], v[150:153], v[202:205], v[108:111]
	v_mfma_f32_16x16x32_bf16 v[100:103], v[154:157], v[198:201], v[100:103]
	v_mfma_f32_16x16x32_bf16 v[100:103], v[158:161], v[202:205], v[100:103]
	v_mfma_f32_16x16x32_bf16 v[92:95], v[146:149], v[206:209], v[92:95]
	v_mfma_f32_16x16x32_bf16 v[92:95], v[150:153], v[210:213], v[92:95]
	v_mfma_f32_16x16x32_bf16 v[84:87], v[154:157], v[206:209], v[84:87]
	v_mfma_f32_16x16x32_bf16 v[84:87], v[158:161], v[210:213], v[84:87]
	v_mfma_f32_16x16x32_bf16 v[76:79], v[146:149], v[214:217], v[76:79]
	v_mfma_f32_16x16x32_bf16 v[76:79], v[150:153], v[218:221], v[76:79]
	v_mfma_f32_16x16x32_bf16 v[68:71], v[154:157], v[214:217], v[68:71]
	v_mfma_f32_16x16x32_bf16 v[68:71], v[158:161], v[218:221], v[68:71]
	v_mfma_f32_16x16x32_bf16 v[120:123], v[162:165], v[190:193], v[120:123]
	v_mfma_f32_16x16x32_bf16 v[120:123], v[178:181], v[194:197], v[120:123]
	v_mfma_f32_16x16x32_bf16 v[112:115], v[182:185], v[190:193], v[112:115]
	v_mfma_f32_16x16x32_bf16 v[112:115], v[186:189], v[194:197], v[112:115]
	v_mfma_f32_16x16x32_bf16 v[104:107], v[162:165], v[198:201], v[104:107]
	v_mfma_f32_16x16x32_bf16 v[104:107], v[178:181], v[202:205], v[104:107]
	v_mfma_f32_16x16x32_bf16 v[96:99], v[182:185], v[198:201], v[96:99]
	v_mfma_f32_16x16x32_bf16 v[96:99], v[186:189], v[202:205], v[96:99]
	v_mfma_f32_16x16x32_bf16 v[88:91], v[162:165], v[206:209], v[88:91]
	v_mfma_f32_16x16x32_bf16 v[88:91], v[178:181], v[210:213], v[88:91]
	v_mfma_f32_16x16x32_bf16 v[80:83], v[182:185], v[206:209], v[80:83]
	v_mfma_f32_16x16x32_bf16 v[80:83], v[186:189], v[210:213], v[80:83]
	v_mfma_f32_16x16x32_bf16 v[72:75], v[162:165], v[214:217], v[72:75]
	v_mfma_f32_16x16x32_bf16 v[72:75], v[178:181], v[218:221], v[72:75]
	s_waitcnt vmcnt(8)
	s_setprio 3
	s_barrier
	v_mfma_f32_16x16x32_bf16 v[64:67], v[182:185], v[214:217], v[64:67]
	v_mfma_f32_16x16x32_bf16 v[64:67], v[186:189], v[218:221], v[64:67]
	s_setprio 0
.Lkazj_10_0:
	s_add_i32 s74, s26, s16
	v_lshl_add_u64 v[166:167], s[70:71], 0, v[132:133]
	s_mov_b32 m0, s74
	ds_read_b128 v[190:193], v176 offset:16384
	ds_read_b128 v[194:197], v176 offset:17408
	ds_read_b128 v[198:201], v176 offset:18432
	ds_read_b128 v[202:205], v176 offset:19456
	ds_read_b128 v[206:209], v176 offset:20480
	ds_read_b128 v[210:213], v176 offset:21504
	ds_read_b128 v[214:217], v176 offset:22528
	ds_read_b128 v[218:221], v176 offset:23552
	global_load_lds_dwordx4 v[166:167], off
	s_add_i32 m0, s74, 0x2000
	s_add_u32 s74, s70, 0x40000
	v_lshl_add_u64 v[222:223], s[70:71], 0, v[128:129]
	s_addc_u32 s75, s71, 0
	s_add_i32 s76, s27, s16
	global_load_lds_dwordx4 v[222:223], off
	v_lshl_add_u64 v[224:225], s[74:75], 0, v[132:133]
	s_mov_b32 m0, s76
	global_load_lds_dwordx4 v[224:225], off
	s_add_i32 m0, s76, 0x2000
	v_lshl_add_u64 v[224:225], s[74:75], 0, v[128:129]
	global_load_lds_dwordx4 v[224:225], off
	s_mov_b32 m0, s17
	v_lshl_add_u64 v[224:225], s[72:73], 0, v[134:135]
	global_load_lds_dwordx4 v[224:225], off
	s_mov_b32 m0, s18
	v_lshl_add_u64 v[226:227], s[72:73], 0, v[130:131]
	global_load_lds_dwordx4 v[226:227], off
	s_cmp_eq_u32 s69, -2
	s_waitcnt lgkmcnt(0)
	s_barrier
	s_setprio 1
	s_cbranch_scc1 .Lkazv_10_1
	v_mfma_f32_16x16x32_bf16 v[60:63], v[146:149], v[190:193], v[60:63]
	v_mfma_f32_16x16x32_bf16 v[60:63], v[150:153], v[194:197], v[60:63]
	v_mfma_f32_16x16x32_bf16 v[52:55], v[154:157], v[190:193], v[52:55]
	v_mfma_f32_16x16x32_bf16 v[52:55], v[158:161], v[194:197], v[52:55]
	v_mfma_f32_16x16x32_bf16 v[44:47], v[146:149], v[198:201], v[44:47]
	v_mfma_f32_16x16x32_bf16 v[44:47], v[150:153], v[202:205], v[44:47]
	v_mfma_f32_16x16x32_bf16 v[36:39], v[154:157], v[198:201], v[36:39]
	v_mfma_f32_16x16x32_bf16 v[36:39], v[158:161], v[202:205], v[36:39]
	v_mfma_f32_16x16x32_bf16 v[28:31], v[146:149], v[206:209], v[28:31]
	v_mfma_f32_16x16x32_bf16 v[28:31], v[150:153], v[210:213], v[28:31]
	v_mfma_f32_16x16x32_bf16 v[20:23], v[154:157], v[206:209], v[20:23]
	v_mfma_f32_16x16x32_bf16 v[20:23], v[158:161], v[210:213], v[20:23]
	v_mfma_f32_16x16x32_bf16 v[12:15], v[146:149], v[214:217], v[12:15]
	v_mfma_f32_16x16x32_bf16 v[12:15], v[150:153], v[218:221], v[12:15]
	v_mfma_f32_16x16x32_bf16 v[4:7], v[154:157], v[214:217], v[4:7]
	v_mfma_f32_16x16x32_bf16 v[4:7], v[158:161], v[218:221], v[4:7]
	v_mfma_f32_16x16x32_bf16 v[56:59], v[162:165], v[190:193], v[56:59]
	v_mfma_f32_16x16x32_bf16 v[56:59], v[178:181], v[194:197], v[56:59]
	v_mfma_f32_16x16x32_bf16 v[48:51], v[182:185], v[190:193], v[48:51]
	v_mfma_f32_16x16x32_bf16 v[48:51], v[186:189], v[194:197], v[48:51]
	v_mfma_f32_16x16x32_bf16 v[40:43], v[162:165], v[198:201], v[40:43]
	v_mfma_f32_16x16x32_bf16 v[40:43], v[178:181], v[202:205], v[40:43]
	v_mfma_f32_16x16x32_bf16 v[32:35], v[182:185], v[198:201], v[32:35]
	v_mfma_f32_16x16x32_bf16 v[32:35], v[186:189], v[202:205], v[32:35]
	v_mfma_f32_16x16x32_bf16 v[24:27], v[162:165], v[206:209], v[24:27]
	v_mfma_f32_16x16x32_bf16 v[24:27], v[178:181], v[210:213], v[24:27]
	v_mfma_f32_16x16x32_bf16 v[16:19], v[182:185], v[206:209], v[16:19]
	v_mfma_f32_16x16x32_bf16 v[16:19], v[186:189], v[210:213], v[16:19]
	v_mfma_f32_16x16x32_bf16 v[8:11], v[162:165], v[214:217], v[8:11]
	v_mfma_f32_16x16x32_bf16 v[8:11], v[178:181], v[218:221], v[8:11]
	s_waitcnt vmcnt(8)
	s_setprio 3
	s_barrier
	v_mfma_f32_16x16x32_bf16 v[0:3], v[182:185], v[214:217], v[0:3]
	v_mfma_f32_16x16x32_bf16 v[0:3], v[186:189], v[218:221], v[0:3]
	s_setprio 0
.Lkazj_10_1:
	s_add_i32 s74, 0, 0x18000
	s_add_i32 s75, 0, 0x1c000
	v_add_u32_e32 v158, s74, v171
	v_add_u32_e32 v186, s75, v171
	ds_read_b128 v[146:149], v158
	ds_read_b128 v[150:153], v158 offset:1024
	ds_read_b128 v[154:157], v158 offset:2048
	ds_read_b128 v[158:161], v158 offset:3072
	ds_read_b128 v[162:165], v186
	ds_read_b128 v[178:181], v186 offset:1024
	ds_read_b128 v[182:185], v186 offset:2048
	ds_read_b128 v[186:189], v186 offset:3072
	s_add_u32 s72, s72, 0x40000
	s_addc_u32 s73, s73, 0
	s_mov_b32 m0, s19
	v_lshl_add_u64 v[228:229], s[72:73], 0, v[134:135]
	ds_read_b128 v[190:193], v176 offset:32768
	ds_read_b128 v[194:197], v176 offset:33792
	ds_read_b128 v[198:201], v176 offset:34816
	ds_read_b128 v[202:205], v176 offset:35840
	ds_read_b128 v[206:209], v176 offset:36864
	ds_read_b128 v[210:213], v176 offset:37888
	ds_read_b128 v[214:217], v176 offset:38912
	ds_read_b128 v[218:221], v176 offset:39936
	global_load_lds_dwordx4 v[228:229], off
	s_mov_b32 m0, s20
	v_lshl_add_u64 v[228:229], s[72:73], 0, v[130:131]
	global_load_lds_dwordx4 v[228:229], off
	s_waitcnt lgkmcnt(0)
	s_barrier
	s_setprio 1
	v_mfma_f32_16x16x32_bf16 v[124:127], v[146:149], v[190:193], v[124:127]
	v_mfma_f32_16x16x32_bf16 v[124:127], v[150:153], v[194:197], v[124:127]
	v_mfma_f32_16x16x32_bf16 v[116:119], v[154:157], v[190:193], v[116:119]
	v_mfma_f32_16x16x32_bf16 v[116:119], v[158:161], v[194:197], v[116:119]
	v_mfma_f32_16x16x32_bf16 v[108:111], v[146:149], v[198:201], v[108:111]
	v_mfma_f32_16x16x32_bf16 v[108:111], v[150:153], v[202:205], v[108:111]
	v_mfma_f32_16x16x32_bf16 v[100:103], v[154:157], v[198:201], v[100:103]
	v_mfma_f32_16x16x32_bf16 v[100:103], v[158:161], v[202:205], v[100:103]
	v_mfma_f32_16x16x32_bf16 v[92:95], v[146:149], v[206:209], v[92:95]
	v_mfma_f32_16x16x32_bf16 v[92:95], v[150:153], v[210:213], v[92:95]
	v_mfma_f32_16x16x32_bf16 v[84:87], v[154:157], v[206:209], v[84:87]
	v_mfma_f32_16x16x32_bf16 v[84:87], v[158:161], v[210:213], v[84:87]
	v_mfma_f32_16x16x32_bf16 v[76:79], v[146:149], v[214:217], v[76:79]
	v_mfma_f32_16x16x32_bf16 v[76:79], v[150:153], v[218:221], v[76:79]
	v_mfma_f32_16x16x32_bf16 v[68:71], v[154:157], v[214:217], v[68:71]
	v_mfma_f32_16x16x32_bf16 v[68:71], v[158:161], v[218:221], v[68:71]
	v_mfma_f32_16x16x32_bf16 v[120:123], v[162:165], v[190:193], v[120:123]
	v_mfma_f32_16x16x32_bf16 v[120:123], v[178:181], v[194:197], v[120:123]
	v_mfma_f32_16x16x32_bf16 v[112:115], v[182:185], v[190:193], v[112:115]
	v_mfma_f32_16x16x32_bf16 v[112:115], v[186:189], v[194:197], v[112:115]
	v_mfma_f32_16x16x32_bf16 v[104:107], v[162:165], v[198:201], v[104:107]
	v_mfma_f32_16x16x32_bf16 v[104:107], v[178:181], v[202:205], v[104:107]
	v_mfma_f32_16x16x32_bf16 v[96:99], v[182:185], v[198:201], v[96:99]
	v_mfma_f32_16x16x32_bf16 v[96:99], v[186:189], v[202:205], v[96:99]
	v_mfma_f32_16x16x32_bf16 v[88:91], v[162:165], v[206:209], v[88:91]
	v_mfma_f32_16x16x32_bf16 v[88:91], v[178:181], v[210:213], v[88:91]
	v_mfma_f32_16x16x32_bf16 v[80:83], v[182:185], v[206:209], v[80:83]
	v_mfma_f32_16x16x32_bf16 v[80:83], v[186:189], v[210:213], v[80:83]
	v_mfma_f32_16x16x32_bf16 v[72:75], v[162:165], v[214:217], v[72:75]
	v_mfma_f32_16x16x32_bf16 v[72:75], v[178:181], v[218:221], v[72:75]
	s_waitcnt vmcnt(8)
	s_setprio 3
	s_barrier
	v_mfma_f32_16x16x32_bf16 v[64:67], v[182:185], v[214:217], v[64:67]
	v_mfma_f32_16x16x32_bf16 v[64:67], v[186:189], v[218:221], v[64:67]
	s_setprio 0
	s_add_i32 s72, s74, s16
	v_lshl_add_u64 v[166:167], v[166:167], 0, s[10:11]
	s_mov_b32 m0, s72
	ds_read_b128 v[190:193], v176 offset:49152
	ds_read_b128 v[194:197], v176 offset:50176
	ds_read_b128 v[198:201], v176 offset:51200
	ds_read_b128 v[202:205], v176 offset:52224
	ds_read_b128 v[206:209], v176 offset:53248
	ds_read_b128 v[210:213], v176 offset:54272
	ds_read_b128 v[214:217], v176 offset:55296
	ds_read_b128 v[218:221], v176 offset:56320
	global_load_lds_dwordx4 v[166:167], off
	s_add_i32 m0, s72, 0x2000
	s_add_u32 s70, s70, 0x40080
	v_lshl_add_u64 v[166:167], v[222:223], 0, s[10:11]
	s_addc_u32 s71, s71, 0
	s_add_i32 s72, s75, s16
	global_load_lds_dwordx4 v[166:167], off
	s_mov_b32 m0, s72
	v_lshl_add_u64 v[166:167], s[70:71], 0, v[132:133]
	global_load_lds_dwordx4 v[166:167], off
	s_add_i32 m0, s72, 0x2000
	v_lshl_add_u64 v[166:167], s[70:71], 0, v[128:129]
	global_load_lds_dwordx4 v[166:167], off
	s_mov_b32 m0, s23
	v_lshl_add_u64 v[166:167], v[224:225], 0, s[10:11]
	global_load_lds_dwordx4 v[166:167], off
	s_mov_b32 m0, s24
	v_lshl_add_u64 v[166:167], v[226:227], 0, s[10:11]
	global_load_lds_dwordx4 v[166:167], off
	s_waitcnt lgkmcnt(0)
	s_barrier
	s_setprio 1
	v_mfma_f32_16x16x32_bf16 v[60:63], v[146:149], v[190:193], v[60:63]
	v_mfma_f32_16x16x32_bf16 v[60:63], v[150:153], v[194:197], v[60:63]
	v_mfma_f32_16x16x32_bf16 v[52:55], v[154:157], v[190:193], v[52:55]
	v_mfma_f32_16x16x32_bf16 v[52:55], v[158:161], v[194:197], v[52:55]
	v_mfma_f32_16x16x32_bf16 v[44:47], v[146:149], v[198:201], v[44:47]
	v_mfma_f32_16x16x32_bf16 v[44:47], v[150:153], v[202:205], v[44:47]
	v_mfma_f32_16x16x32_bf16 v[36:39], v[154:157], v[198:201], v[36:39]
	v_mfma_f32_16x16x32_bf16 v[36:39], v[158:161], v[202:205], v[36:39]
	v_mfma_f32_16x16x32_bf16 v[28:31], v[146:149], v[206:209], v[28:31]
	v_mfma_f32_16x16x32_bf16 v[28:31], v[150:153], v[210:213], v[28:31]
	v_mfma_f32_16x16x32_bf16 v[20:23], v[154:157], v[206:209], v[20:23]
	v_mfma_f32_16x16x32_bf16 v[20:23], v[158:161], v[210:213], v[20:23]
	v_mfma_f32_16x16x32_bf16 v[12:15], v[146:149], v[214:217], v[12:15]
	v_mfma_f32_16x16x32_bf16 v[12:15], v[150:153], v[218:221], v[12:15]
	v_mfma_f32_16x16x32_bf16 v[4:7], v[154:157], v[214:217], v[4:7]
	v_mfma_f32_16x16x32_bf16 v[4:7], v[158:161], v[218:221], v[4:7]
	v_mfma_f32_16x16x32_bf16 v[56:59], v[162:165], v[190:193], v[56:59]
	v_mfma_f32_16x16x32_bf16 v[56:59], v[178:181], v[194:197], v[56:59]
	v_mfma_f32_16x16x32_bf16 v[48:51], v[182:185], v[190:193], v[48:51]
	v_mfma_f32_16x16x32_bf16 v[48:51], v[186:189], v[194:197], v[48:51]
	v_mfma_f32_16x16x32_bf16 v[40:43], v[162:165], v[198:201], v[40:43]
	v_mfma_f32_16x16x32_bf16 v[40:43], v[178:181], v[202:205], v[40:43]
	v_mfma_f32_16x16x32_bf16 v[32:35], v[182:185], v[198:201], v[32:35]
	v_mfma_f32_16x16x32_bf16 v[32:35], v[186:189], v[202:205], v[32:35]
	v_mfma_f32_16x16x32_bf16 v[24:27], v[162:165], v[206:209], v[24:27]
	v_mfma_f32_16x16x32_bf16 v[24:27], v[178:181], v[210:213], v[24:27]
	v_mfma_f32_16x16x32_bf16 v[16:19], v[182:185], v[206:209], v[16:19]
	v_mfma_f32_16x16x32_bf16 v[16:19], v[186:189], v[210:213], v[16:19]
	v_mfma_f32_16x16x32_bf16 v[8:11], v[162:165], v[214:217], v[8:11]
	v_mfma_f32_16x16x32_bf16 v[8:11], v[178:181], v[218:221], v[8:11]
	s_waitcnt vmcnt(8)
	s_setprio 3
	s_barrier
	v_mfma_f32_16x16x32_bf16 v[0:3], v[182:185], v[214:217], v[0:3]
	v_mfma_f32_16x16x32_bf16 v[0:3], v[186:189], v[218:221], v[0:3]
	s_setprio 0
	s_add_i32 s69, s69, 2
	s_add_u32 s58, s58, 0x100
	s_addc_u32 s59, s59, 0
	s_add_u32 s67, s67, 0x100
	s_addc_u32 s68, s68, 0
	s_cmp_gt_u32 s69, 13
	s_cbranch_scc0 .Lka10_head
	s_branch .Lzskip_10

.LBB0_2340:
	s_add_u32 s16, s16, 0xb0080
	s_addc_u32 s17, s17, 0
	s_add_u32 s43, s18, 0x100
	v_mov_b32_e32 v0, 0
	s_addc_u32 s44, s19, 0
	s_mov_b32 s45, -2
	s_and_b64 s[100:101], exec, s[10:11]
	s_cbranch_scc1 .Lka11_head

.Lka11_head:
	ds_read_b128 v[128:131], v197
	ds_read_b128 v[132:135], v197 offset:1024
	ds_read_b128 v[136:139], v197 offset:2048
	ds_read_b128 v[140:143], v197 offset:3072
	ds_read_b128 v[144:147], v198
	ds_read_b128 v[148:151], v198 offset:1024
	ds_read_b128 v[152:155], v198 offset:2048
	ds_read_b128 v[156:159], v198 offset:3072
	s_add_u32 s18, s16, 0xfff50080
	s_addc_u32 s19, s17, -1
	s_cmp_eq_u32 s45, 40
	s_cselect_b32 s21, s5, s19
	s_cselect_b32 s20, s4, s18
	s_cselect_b32 s19, s15, s44
	s_cselect_b32 s18, s14, s43
	v_lshl_add_u64 v[192:193], s[16:17], 0, v[172:173]
	s_add_i32 m0, s25, 0xc000
	ds_read_b128 v[160:163], v199
	ds_read_b128 v[180:183], v199 offset:1024
	ds_read_b128 v[184:187], v199 offset:2048
	ds_read_b128 v[188:191], v199 offset:3072
	ds_read_b128 v[200:203], v199 offset:4096
	ds_read_b128 v[204:207], v199 offset:5120
	ds_read_b128 v[208:211], v199 offset:6144
	ds_read_b128 v[212:215], v199 offset:7168
	global_load_lds_dwordx4 v[192:193], off
	s_add_i32 m0, s25, 0xe000
	v_lshl_add_u64 v[192:193], s[16:17], 0, v[174:175]
	global_load_lds_dwordx4 v[192:193], off
	s_cmp_eq_u32 s45, -2
	s_waitcnt lgkmcnt(0)
	s_barrier
	s_setprio 1
	s_cbranch_scc1 .Lkazv_11_0
	v_mfma_f32_16x16x32_bf16 v[124:127], v[128:131], v[160:163], v[124:127]
	v_mfma_f32_16x16x32_bf16 v[124:127], v[132:135], v[180:183], v[124:127]
	v_mfma_f32_16x16x32_bf16 v[120:123], v[136:139], v[160:163], v[120:123]
	v_mfma_f32_16x16x32_bf16 v[120:123], v[140:143], v[180:183], v[120:123]
	v_mfma_f32_16x16x32_bf16 v[108:111], v[128:131], v[184:187], v[108:111]
	v_mfma_f32_16x16x32_bf16 v[108:111], v[132:135], v[188:191], v[108:111]
	v_mfma_f32_16x16x32_bf16 v[104:107], v[136:139], v[184:187], v[104:107]
	v_mfma_f32_16x16x32_bf16 v[104:107], v[140:143], v[188:191], v[104:107]
	v_mfma_f32_16x16x32_bf16 v[96:99], v[128:131], v[200:203], v[96:99]
	v_mfma_f32_16x16x32_bf16 v[96:99], v[132:135], v[204:207], v[96:99]
	v_mfma_f32_16x16x32_bf16 v[88:91], v[136:139], v[200:203], v[88:91]
	v_mfma_f32_16x16x32_bf16 v[88:91], v[140:143], v[204:207], v[88:91]
	v_mfma_f32_16x16x32_bf16 v[80:83], v[128:131], v[208:211], v[80:83]
	v_mfma_f32_16x16x32_bf16 v[80:83], v[132:135], v[212:215], v[80:83]
	v_mfma_f32_16x16x32_bf16 v[72:75], v[136:139], v[208:211], v[72:75]
	v_mfma_f32_16x16x32_bf16 v[72:75], v[140:143], v[212:215], v[72:75]
	v_mfma_f32_16x16x32_bf16 v[116:119], v[144:147], v[160:163], v[116:119]
	v_mfma_f32_16x16x32_bf16 v[116:119], v[148:151], v[180:183], v[116:119]
	v_mfma_f32_16x16x32_bf16 v[112:115], v[152:155], v[160:163], v[112:115]
	v_mfma_f32_16x16x32_bf16 v[112:115], v[156:159], v[180:183], v[112:115]
	v_mfma_f32_16x16x32_bf16 v[100:103], v[144:147], v[184:187], v[100:103]
	v_mfma_f32_16x16x32_bf16 v[100:103], v[148:151], v[188:191], v[100:103]
	v_mfma_f32_16x16x32_bf16 v[92:95], v[152:155], v[184:187], v[92:95]
	v_mfma_f32_16x16x32_bf16 v[92:95], v[156:159], v[188:191], v[92:95]
	v_mfma_f32_16x16x32_bf16 v[84:87], v[144:147], v[200:203], v[84:87]
	v_mfma_f32_16x16x32_bf16 v[84:87], v[148:151], v[204:207], v[84:87]
	v_mfma_f32_16x16x32_bf16 v[76:79], v[152:155], v[200:203], v[76:79]
	v_mfma_f32_16x16x32_bf16 v[76:79], v[156:159], v[204:207], v[76:79]
	v_mfma_f32_16x16x32_bf16 v[68:71], v[144:147], v[208:211], v[68:71]
	v_mfma_f32_16x16x32_bf16 v[68:71], v[148:151], v[212:215], v[68:71]
	s_waitcnt vmcnt(8)
	s_setprio 3
	s_barrier
	v_mfma_f32_16x16x32_bf16 v[64:67], v[152:155], v[208:211], v[64:67]
	v_mfma_f32_16x16x32_bf16 v[64:67], v[156:159], v[212:215], v[64:67]
	s_setprio 0
.Lkazj_11_0:
	s_add_i32 s46, s37, s24
	v_lshl_add_u64 v[192:193], s[18:19], 0, v[166:167]
	s_mov_b32 m0, s46
	ds_read_b128 v[160:163], v199 offset:16384
	ds_read_b128 v[180:183], v199 offset:17408
	ds_read_b128 v[184:187], v199 offset:18432
	ds_read_b128 v[188:191], v199 offset:19456
	ds_read_b128 v[200:203], v199 offset:20480
	ds_read_b128 v[204:207], v199 offset:21504
	ds_read_b128 v[208:211], v199 offset:22528
	ds_read_b128 v[212:215], v199 offset:23552
	global_load_lds_dwordx4 v[192:193], off
	s_add_i32 m0, s46, 0x2000
	s_add_u32 s46, s18, 0xb0000
	v_lshl_add_u64 v[216:217], s[18:19], 0, v[170:171]
	s_addc_u32 s47, s19, 0
	s_add_i32 s48, s38, s24
	global_load_lds_dwordx4 v[216:217], off
	v_lshl_add_u64 v[218:219], s[46:47], 0, v[166:167]
	s_mov_b32 m0, s48
	global_load_lds_dwordx4 v[218:219], off
	s_add_i32 m0, s48, 0x2000
	v_lshl_add_u64 v[218:219], s[46:47], 0, v[170:171]
	global_load_lds_dwordx4 v[218:219], off
	s_mov_b32 m0, s25
	v_lshl_add_u64 v[218:219], s[20:21], 0, v[164:165]
	global_load_lds_dwordx4 v[218:219], off
	s_mov_b32 m0, s26
	v_lshl_add_u64 v[220:221], s[20:21], 0, v[168:169]
	global_load_lds_dwordx4 v[220:221], off
	s_cmp_eq_u32 s45, -2
	s_waitcnt lgkmcnt(0)
	s_barrier
	s_setprio 1
	s_cbranch_scc1 .Lkazv_11_1
	v_mfma_f32_16x16x32_bf16 v[60:63], v[128:131], v[160:163], v[60:63]
	v_mfma_f32_16x16x32_bf16 v[60:63], v[132:135], v[180:183], v[60:63]
	v_mfma_f32_16x16x32_bf16 v[56:59], v[136:139], v[160:163], v[56:59]
	v_mfma_f32_16x16x32_bf16 v[56:59], v[140:143], v[180:183], v[56:59]
	v_mfma_f32_16x16x32_bf16 v[48:51], v[128:131], v[184:187], v[48:51]
	v_mfma_f32_16x16x32_bf16 v[48:51], v[132:135], v[188:191], v[48:51]
	v_mfma_f32_16x16x32_bf16 v[40:43], v[136:139], v[184:187], v[40:43]
	v_mfma_f32_16x16x32_bf16 v[40:43], v[140:143], v[188:191], v[40:43]
	v_mfma_f32_16x16x32_bf16 v[32:35], v[128:131], v[200:203], v[32:35]
	v_mfma_f32_16x16x32_bf16 v[32:35], v[132:135], v[204:207], v[32:35]
	v_mfma_f32_16x16x32_bf16 v[24:27], v[136:139], v[200:203], v[24:27]
	v_mfma_f32_16x16x32_bf16 v[24:27], v[140:143], v[204:207], v[24:27]
	v_mfma_f32_16x16x32_bf16 v[16:19], v[128:131], v[208:211], v[16:19]
	v_mfma_f32_16x16x32_bf16 v[16:19], v[132:135], v[212:215], v[16:19]
	v_mfma_f32_16x16x32_bf16 v[8:11], v[136:139], v[208:211], v[8:11]
	v_mfma_f32_16x16x32_bf16 v[8:11], v[140:143], v[212:215], v[8:11]
	v_mfma_f32_16x16x32_bf16 v[52:55], v[144:147], v[160:163], v[52:55]
	v_mfma_f32_16x16x32_bf16 v[52:55], v[148:151], v[180:183], v[52:55]
	v_mfma_f32_16x16x32_bf16 v[44:47], v[152:155], v[160:163], v[44:47]
	v_mfma_f32_16x16x32_bf16 v[44:47], v[156:159], v[180:183], v[44:47]
	v_mfma_f32_16x16x32_bf16 v[36:39], v[144:147], v[184:187], v[36:39]
	v_mfma_f32_16x16x32_bf16 v[36:39], v[148:151], v[188:191], v[36:39]
	v_mfma_f32_16x16x32_bf16 v[28:31], v[152:155], v[184:187], v[28:31]
	v_mfma_f32_16x16x32_bf16 v[28:31], v[156:159], v[188:191], v[28:31]
	v_mfma_f32_16x16x32_bf16 v[20:23], v[144:147], v[200:203], v[20:23]
	v_mfma_f32_16x16x32_bf16 v[20:23], v[148:151], v[204:207], v[20:23]
	v_mfma_f32_16x16x32_bf16 v[12:15], v[152:155], v[200:203], v[12:15]
	v_mfma_f32_16x16x32_bf16 v[12:15], v[156:159], v[204:207], v[12:15]
	v_mfma_f32_16x16x32_bf16 v[4:7], v[144:147], v[208:211], v[4:7]
	v_mfma_f32_16x16x32_bf16 v[4:7], v[148:151], v[212:215], v[4:7]
	s_waitcnt vmcnt(8)
	s_setprio 3
	s_barrier
	v_mfma_f32_16x16x32_bf16 v[0:3], v[152:155], v[208:211], v[0:3]
	v_mfma_f32_16x16x32_bf16 v[0:3], v[156:159], v[212:215], v[0:3]
	s_setprio 0
.Lkazj_11_1:
	s_add_i32 s46, 0, 0x18000
	s_add_i32 s47, 0, 0x1c000
	v_add_u32_e32 v140, s46, v195
	v_add_u32_e32 v156, s47, v195
	ds_read_b128 v[128:131], v140
	ds_read_b128 v[132:135], v140 offset:1024
	ds_read_b128 v[136:139], v140 offset:2048
	ds_read_b128 v[140:143], v140 offset:3072
	ds_read_b128 v[144:147], v156
	ds_read_b128 v[148:151], v156 offset:1024
	ds_read_b128 v[152:155], v156 offset:2048
	ds_read_b128 v[156:159], v156 offset:3072
	s_add_u32 s20, s20, 0xb0000
	s_addc_u32 s21, s21, 0
	s_mov_b32 m0, s27
	v_lshl_add_u64 v[222:223], s[20:21], 0, v[164:165]
	ds_read_b128 v[160:163], v199 offset:32768
	ds_read_b128 v[180:183], v199 offset:33792
	ds_read_b128 v[184:187], v199 offset:34816
	ds_read_b128 v[188:191], v199 offset:35840
	ds_read_b128 v[200:203], v199 offset:36864
	ds_read_b128 v[204:207], v199 offset:37888
	ds_read_b128 v[208:211], v199 offset:38912
	ds_read_b128 v[212:215], v199 offset:39936
	global_load_lds_dwordx4 v[222:223], off
	s_mov_b32 m0, s28
	v_lshl_add_u64 v[222:223], s[20:21], 0, v[168:169]
	global_load_lds_dwordx4 v[222:223], off
	s_waitcnt lgkmcnt(0)
	s_barrier
	s_setprio 1
	v_mfma_f32_16x16x32_bf16 v[124:127], v[128:131], v[160:163], v[124:127]
	v_mfma_f32_16x16x32_bf16 v[124:127], v[132:135], v[180:183], v[124:127]
	v_mfma_f32_16x16x32_bf16 v[120:123], v[136:139], v[160:163], v[120:123]
	v_mfma_f32_16x16x32_bf16 v[120:123], v[140:143], v[180:183], v[120:123]
	v_mfma_f32_16x16x32_bf16 v[108:111], v[128:131], v[184:187], v[108:111]
	v_mfma_f32_16x16x32_bf16 v[108:111], v[132:135], v[188:191], v[108:111]
	v_mfma_f32_16x16x32_bf16 v[104:107], v[136:139], v[184:187], v[104:107]
	v_mfma_f32_16x16x32_bf16 v[104:107], v[140:143], v[188:191], v[104:107]
	v_mfma_f32_16x16x32_bf16 v[96:99], v[128:131], v[200:203], v[96:99]
	v_mfma_f32_16x16x32_bf16 v[96:99], v[132:135], v[204:207], v[96:99]
	v_mfma_f32_16x16x32_bf16 v[88:91], v[136:139], v[200:203], v[88:91]
	v_mfma_f32_16x16x32_bf16 v[88:91], v[140:143], v[204:207], v[88:91]
	v_mfma_f32_16x16x32_bf16 v[80:83], v[128:131], v[208:211], v[80:83]
	v_mfma_f32_16x16x32_bf16 v[80:83], v[132:135], v[212:215], v[80:83]
	v_mfma_f32_16x16x32_bf16 v[72:75], v[136:139], v[208:211], v[72:75]
	v_mfma_f32_16x16x32_bf16 v[72:75], v[140:143], v[212:215], v[72:75]
	v_mfma_f32_16x16x32_bf16 v[116:119], v[144:147], v[160:163], v[116:119]
	v_mfma_f32_16x16x32_bf16 v[116:119], v[148:151], v[180:183], v[116:119]
	v_mfma_f32_16x16x32_bf16 v[112:115], v[152:155], v[160:163], v[112:115]
	v_mfma_f32_16x16x32_bf16 v[112:115], v[156:159], v[180:183], v[112:115]
	v_mfma_f32_16x16x32_bf16 v[100:103], v[144:147], v[184:187], v[100:103]
	v_mfma_f32_16x16x32_bf16 v[100:103], v[148:151], v[188:191], v[100:103]
	v_mfma_f32_16x16x32_bf16 v[92:95], v[152:155], v[184:187], v[92:95]
	v_mfma_f32_16x16x32_bf16 v[92:95], v[156:159], v[188:191], v[92:95]
	v_mfma_f32_16x16x32_bf16 v[84:87], v[144:147], v[200:203], v[84:87]
	v_mfma_f32_16x16x32_bf16 v[84:87], v[148:151], v[204:207], v[84:87]
	v_mfma_f32_16x16x32_bf16 v[76:79], v[152:155], v[200:203], v[76:79]
	v_mfma_f32_16x16x32_bf16 v[76:79], v[156:159], v[204:207], v[76:79]
	v_mfma_f32_16x16x32_bf16 v[68:71], v[144:147], v[208:211], v[68:71]
	v_mfma_f32_16x16x32_bf16 v[68:71], v[148:151], v[212:215], v[68:71]
	s_waitcnt vmcnt(8)
	s_setprio 3
	s_barrier
	v_mfma_f32_16x16x32_bf16 v[64:67], v[152:155], v[208:211], v[64:67]
	v_mfma_f32_16x16x32_bf16 v[64:67], v[156:159], v[212:215], v[64:67]
	s_setprio 0
	s_add_i32 s20, s46, s24
	v_lshl_add_u64 v[192:193], v[192:193], 0, s[8:9]
	s_mov_b32 m0, s20
	ds_read_b128 v[160:163], v199 offset:49152
	ds_read_b128 v[180:183], v199 offset:50176
	ds_read_b128 v[184:187], v199 offset:51200
	ds_read_b128 v[188:191], v199 offset:52224
	ds_read_b128 v[200:203], v199 offset:53248
	ds_read_b128 v[204:207], v199 offset:54272
	ds_read_b128 v[208:211], v199 offset:55296
	ds_read_b128 v[212:215], v199 offset:56320
	global_load_lds_dwordx4 v[192:193], off
	s_add_i32 m0, s20, 0x2000
	s_add_u32 s18, s18, 0xb0080
	v_lshl_add_u64 v[192:193], v[216:217], 0, s[8:9]
	s_addc_u32 s19, s19, 0
	s_add_i32 s20, s47, s24
	global_load_lds_dwordx4 v[192:193], off
	s_mov_b32 m0, s20
	v_lshl_add_u64 v[192:193], s[18:19], 0, v[166:167]
	global_load_lds_dwordx4 v[192:193], off
	s_add_i32 m0, s20, 0x2000
	v_lshl_add_u64 v[192:193], s[18:19], 0, v[170:171]
	global_load_lds_dwordx4 v[192:193], off
	s_mov_b32 m0, s33
	v_lshl_add_u64 v[192:193], v[218:219], 0, s[8:9]
	global_load_lds_dwordx4 v[192:193], off
	s_mov_b32 m0, s35
	v_lshl_add_u64 v[192:193], v[220:221], 0, s[8:9]
	global_load_lds_dwordx4 v[192:193], off
	s_waitcnt lgkmcnt(0)
	s_barrier
	s_setprio 1
	v_mfma_f32_16x16x32_bf16 v[60:63], v[128:131], v[160:163], v[60:63]
	v_mfma_f32_16x16x32_bf16 v[60:63], v[132:135], v[180:183], v[60:63]
	v_mfma_f32_16x16x32_bf16 v[56:59], v[136:139], v[160:163], v[56:59]
	v_mfma_f32_16x16x32_bf16 v[56:59], v[140:143], v[180:183], v[56:59]
	v_mfma_f32_16x16x32_bf16 v[48:51], v[128:131], v[184:187], v[48:51]
	v_mfma_f32_16x16x32_bf16 v[48:51], v[132:135], v[188:191], v[48:51]
	v_mfma_f32_16x16x32_bf16 v[40:43], v[136:139], v[184:187], v[40:43]
	v_mfma_f32_16x16x32_bf16 v[40:43], v[140:143], v[188:191], v[40:43]
	v_mfma_f32_16x16x32_bf16 v[32:35], v[128:131], v[200:203], v[32:35]
	v_mfma_f32_16x16x32_bf16 v[32:35], v[132:135], v[204:207], v[32:35]
	v_mfma_f32_16x16x32_bf16 v[24:27], v[136:139], v[200:203], v[24:27]
	v_mfma_f32_16x16x32_bf16 v[24:27], v[140:143], v[204:207], v[24:27]
	v_mfma_f32_16x16x32_bf16 v[16:19], v[128:131], v[208:211], v[16:19]
	v_mfma_f32_16x16x32_bf16 v[16:19], v[132:135], v[212:215], v[16:19]
	v_mfma_f32_16x16x32_bf16 v[8:11], v[136:139], v[208:211], v[8:11]
	v_mfma_f32_16x16x32_bf16 v[8:11], v[140:143], v[212:215], v[8:11]
	v_mfma_f32_16x16x32_bf16 v[52:55], v[144:147], v[160:163], v[52:55]
	v_mfma_f32_16x16x32_bf16 v[52:55], v[148:151], v[180:183], v[52:55]
	v_mfma_f32_16x16x32_bf16 v[44:47], v[152:155], v[160:163], v[44:47]
	v_mfma_f32_16x16x32_bf16 v[44:47], v[156:159], v[180:183], v[44:47]
	v_mfma_f32_16x16x32_bf16 v[36:39], v[144:147], v[184:187], v[36:39]
	v_mfma_f32_16x16x32_bf16 v[36:39], v[148:151], v[188:191], v[36:39]
	v_mfma_f32_16x16x32_bf16 v[28:31], v[152:155], v[184:187], v[28:31]
	v_mfma_f32_16x16x32_bf16 v[28:31], v[156:159], v[188:191], v[28:31]
	v_mfma_f32_16x16x32_bf16 v[20:23], v[144:147], v[200:203], v[20:23]
	v_mfma_f32_16x16x32_bf16 v[20:23], v[148:151], v[204:207], v[20:23]
	v_mfma_f32_16x16x32_bf16 v[12:15], v[152:155], v[200:203], v[12:15]
	v_mfma_f32_16x16x32_bf16 v[12:15], v[156:159], v[204:207], v[12:15]
	v_mfma_f32_16x16x32_bf16 v[4:7], v[144:147], v[208:211], v[4:7]
	v_mfma_f32_16x16x32_bf16 v[4:7], v[148:151], v[212:215], v[4:7]
	s_waitcnt vmcnt(8)
	s_setprio 3
	s_barrier
	v_mfma_f32_16x16x32_bf16 v[0:3], v[152:155], v[208:211], v[0:3]
	v_mfma_f32_16x16x32_bf16 v[0:3], v[156:159], v[212:215], v[0:3]
	s_setprio 0
	s_add_i32 s45, s45, 2
	s_add_u32 s16, s16, 0x100
	s_addc_u32 s17, s17, 0
	s_add_u32 s43, s43, 0x100
	s_addc_u32 s44, s44, 0
	s_cmp_gt_u32 s45, 41
	s_cbranch_scc0 .Lka11_head
	s_branch .Lzskip_11
.Lkazv_11_0:
	v_mfma_f32_16x16x32_bf16 v[124:127], v[128:131], v[160:163], 0
	v_mfma_f32_16x16x32_bf16 v[124:127], v[132:135], v[180:183], v[124:127]
	v_mfma_f32_16x16x32_bf16 v[120:123], v[136:139], v[160:163], 0
	v_mfma_f32_16x16x32_bf16 v[120:123], v[140:143], v[180:183], v[120:123]
	v_mfma_f32_16x16x32_bf16 v[108:111], v[128:131], v[184:187], 0
	v_mfma_f32_16x16x32_bf16 v[108:111], v[132:135], v[188:191], v[108:111]
	v_mfma_f32_16x16x32_bf16 v[104:107], v[136:139], v[184:187], 0
	v_mfma_f32_16x16x32_bf16 v[104:107], v[140:143], v[188:191], v[104:107]
	v_mfma_f32_16x16x32_bf16 v[96:99], v[128:131], v[200:203], 0
	v_mfma_f32_16x16x32_bf16 v[96:99], v[132:135], v[204:207], v[96:99]
	v_mfma_f32_16x16x32_bf16 v[88:91], v[136:139], v[200:203], 0
	v_mfma_f32_16x16x32_bf16 v[88:91], v[140:143], v[204:207], v[88:91]
	v_mfma_f32_16x16x32_bf16 v[80:83], v[128:131], v[208:211], 0
	v_mfma_f32_16x16x32_bf16 v[80:83], v[132:135], v[212:215], v[80:83]
	v_mfma_f32_16x16x32_bf16 v[72:75], v[136:139], v[208:211], 0
	v_mfma_f32_16x16x32_bf16 v[72:75], v[140:143], v[212:215], v[72:75]
	v_mfma_f32_16x16x32_bf16 v[116:119], v[144:147], v[160:163], 0
	v_mfma_f32_16x16x32_bf16 v[116:119], v[148:151], v[180:183], v[116:119]
	v_mfma_f32_16x16x32_bf16 v[112:115], v[152:155], v[160:163], 0
	v_mfma_f32_16x16x32_bf16 v[112:115], v[156:159], v[180:183], v[112:115]
	v_mfma_f32_16x16x32_bf16 v[100:103], v[144:147], v[184:187], 0
	v_mfma_f32_16x16x32_bf16 v[100:103], v[148:151], v[188:191], v[100:103]
	v_mfma_f32_16x16x32_bf16 v[92:95], v[152:155], v[184:187], 0
	v_mfma_f32_16x16x32_bf16 v[92:95], v[156:159], v[188:191], v[92:95]
	v_mfma_f32_16x16x32_bf16 v[84:87], v[144:147], v[200:203], 0
	v_mfma_f32_16x16x32_bf16 v[84:87], v[148:151], v[204:207], v[84:87]
	v_mfma_f32_16x16x32_bf16 v[76:79], v[152:155], v[200:203], 0
	v_mfma_f32_16x16x32_bf16 v[76:79], v[156:159], v[204:207], v[76:79]
	v_mfma_f32_16x16x32_bf16 v[68:71], v[144:147], v[208:211], 0
	v_mfma_f32_16x16x32_bf16 v[68:71], v[148:151], v[212:215], v[68:71]
	s_waitcnt vmcnt(8)
	s_setprio 3
	s_barrier
	v_mfma_f32_16x16x32_bf16 v[64:67], v[152:155], v[208:211], 0
	v_mfma_f32_16x16x32_bf16 v[64:67], v[156:159], v[212:215], v[64:67]
	s_setprio 0
	s_branch .Lkazj_11_0
.Lkazv_11_1:
	v_mfma_f32_16x16x32_bf16 v[60:63], v[128:131], v[160:163], 0
	v_mfma_f32_16x16x32_bf16 v[60:63], v[132:135], v[180:183], v[60:63]
	v_mfma_f32_16x16x32_bf16 v[56:59], v[136:139], v[160:163], 0
	v_mfma_f32_16x16x32_bf16 v[56:59], v[140:143], v[180:183], v[56:59]
	v_mfma_f32_16x16x32_bf16 v[48:51], v[128:131], v[184:187], 0
	v_mfma_f32_16x16x32_bf16 v[48:51], v[132:135], v[188:191], v[48:51]
	v_mfma_f32_16x16x32_bf16 v[40:43], v[136:139], v[184:187], 0
	v_mfma_f32_16x16x32_bf16 v[40:43], v[140:143], v[188:191], v[40:43]
	v_mfma_f32_16x16x32_bf16 v[32:35], v[128:131], v[200:203], 0
	v_mfma_f32_16x16x32_bf16 v[32:35], v[132:135], v[204:207], v[32:35]
	v_mfma_f32_16x16x32_bf16 v[24:27], v[136:139], v[200:203], 0
	v_mfma_f32_16x16x32_bf16 v[24:27], v[140:143], v[204:207], v[24:27]
	v_mfma_f32_16x16x32_bf16 v[16:19], v[128:131], v[208:211], 0
	v_mfma_f32_16x16x32_bf16 v[16:19], v[132:135], v[212:215], v[16:19]
	v_mfma_f32_16x16x32_bf16 v[8:11], v[136:139], v[208:211], 0
	v_mfma_f32_16x16x32_bf16 v[8:11], v[140:143], v[212:215], v[8:11]
	v_mfma_f32_16x16x32_bf16 v[52:55], v[144:147], v[160:163], 0
	v_mfma_f32_16x16x32_bf16 v[52:55], v[148:151], v[180:183], v[52:55]
	v_mfma_f32_16x16x32_bf16 v[44:47], v[152:155], v[160:163], 0
	v_mfma_f32_16x16x32_bf16 v[44:47], v[156:159], v[180:183], v[44:47]
	v_mfma_f32_16x16x32_bf16 v[36:39], v[144:147], v[184:187], 0
	v_mfma_f32_16x16x32_bf16 v[36:39], v[148:151], v[188:191], v[36:39]
	v_mfma_f32_16x16x32_bf16 v[28:31], v[152:155], v[184:187], 0
	v_mfma_f32_16x16x32_bf16 v[28:31], v[156:159], v[188:191], v[28:31]
	v_mfma_f32_16x16x32_bf16 v[20:23], v[144:147], v[200:203], 0
	v_mfma_f32_16x16x32_bf16 v[20:23], v[148:151], v[204:207], v[20:23]
	v_mfma_f32_16x16x32_bf16 v[12:15], v[152:155], v[200:203], 0
	v_mfma_f32_16x16x32_bf16 v[12:15], v[156:159], v[204:207], v[12:15]
	v_mfma_f32_16x16x32_bf16 v[4:7], v[144:147], v[208:211], 0
	v_mfma_f32_16x16x32_bf16 v[4:7], v[148:151], v[212:215], v[4:7]
	s_waitcnt vmcnt(8)
	s_setprio 3
	s_barrier
	v_mfma_f32_16x16x32_bf16 v[0:3], v[152:155], v[208:211], 0
	v_mfma_f32_16x16x32_bf16 v[0:3], v[156:159], v[212:215], v[0:3]
	s_setprio 0
	s_branch .Lkazj_11_1
	s_branch .Lzskip_11
